# variant: setprio 1/0 only around each 32-MFMA block (mid flips dropped), loader VALU removed
# speedup vs baseline: 1.0049x; 1.0049x over previous
; #define PG8_STAGE(bufoff, gbase, voff) do { _Pragma("unroll") for (int _i = 0; _i < 2; ++_i) \
;         __builtin_amdgcn_global_load_lds((const unsigned*)((const char*)(gbase) + (voff)[_i]), (PG8_LAS unsigned*)(lds + (bufoff) + ldsw + _i * 8192), 16, 0, 0); } while (0)
; #define PG8_LDA(dst, b, h) do { _Pragma("unroll") for (int m = 0; m < 4; ++m) _Pragma("unroll") for (int k = 0; k < 2; ++k) dst[m][k] = *(const PG8_LAS bf16x8*)(lds + PG8_SA(b, h) + aoff + m * 2048 + k * 1024); } while (0)
; #define PG8_LDB(dst, b, h) do { _Pragma("unroll") for (int n = 0; n < 2; ++n) _Pragma("unroll") for (int k = 0; k < 2; ++k) dst[n][k] = *(const PG8_LAS bf16x8*)(lds + PG8_SB(b, h) + boff + n * 2048 + k * 1024); } while (0)
; #define PG8_MMA(ai, bj, At, Bt) do { __builtin_amdgcn_s_setprio(1); _Pragma("unroll") for (int m = 0; m < 4; ++m) _Pragma("unroll") for (int n = 0; n < 2; ++n) _Pragma("unroll") for (int k = 0; k < 2; ++k) \
;         acc[ai][bj][m][n] = __builtin_amdgcn_mfma_f32_16x16x32_bf16(Bt[n][k], At[m][k], acc[ai][bj][m][n], 0, 0, 0); __builtin_amdgcn_s_setprio(0); } while (0)
; #define PG8_WAIT_V(n) asm volatile("s_waitcnt vmcnt(" #n ")" ::: "memory")
; #define PG8_WAIT_L(n) asm volatile("s_waitcnt lgkmcnt(" #n ")" ::: "memory")
; template <class Epi, class Sched, bool ALIGN_EPI = false, bool SP2 = false>
; __device__ __forceinline__ void gemm_phase(PG8_LAS unsigned char* lds, const Gemm g, const Sched& S, const Epi& E) {
;     ...
;             const bool last = (t == nt - 2);
;             const char* a1 = cA + (size_t)(t + 1) * kstep;
;             const char* a2 = last ? nA : cA + (size_t)(t + 2) * kstep; const char* b2 = last ? nB : cB + (size_t)(t + 2) * kstep;
;             const char* a3 = a2 + kstep; const char* b3 = b2 + kstep;
;             if (last && has_next) S.a_ready(nxt);
;             if constexpr (SP2) {
;             PG8_LDB(B0, 0, 0); PG8_LDB(B1, 0, 1); PG8_SCHED; PG8_LDA(At, 0, 0); PG8_STAGE(PG8_SA(1, 1), a1 + hstep, voffA);
;             PG8_WAIT_V(8); PG8_WAIT_L(0); PG8_BAR; PG8_MMA(0, 0, At, B0); PG8_MMA(0, 1, At, B1); PG8_BAR; PG8_SCHED;
;             PG8_LDA(At, 0, 1); PG8_STAGE(PG8_SB(0, 0), b2, voffB); PG8_STAGE(PG8_SB(0, 1), b2 + hstep, voffB); PG8_STAGE(PG8_SA(0, 0), a2, voffA);
;             PG8_WAIT_V(8); PG8_WAIT_L(0); PG8_BAR; PG8_MMA(1, 0, At, B0); PG8_MMA(1, 1, At, B1); PG8_BAR; PG8_SCHED;
.LBB0_673:
	ds_read_b128 v[148:151], v241 offset:0
	ds_read_b128 v[156:159], v241 offset:1024
	ds_read_b128 v[166:169], v241 offset:2048
	ds_read_b128 v[170:173], v241 offset:3072
	ds_read_b128 v[174:177], v241 offset:16384
	ds_read_b128 v[178:181], v241 offset:17408
	ds_read_b128 v[182:185], v241 offset:18432
	ds_read_b128 v[186:189], v241 offset:19456
	s_add_u32 s20, s22, 0xfff00080
	s_addc_u32 s21, s23, -1
	s_cmp_eq_u32 s35, 60
	s_cselect_b32 s25, s11, s21
	s_cselect_b32 s24, s52, s20
	s_cselect_b32 s21, s13, s34
	s_cselect_b32 s20, s53, s62
	s_add_i32 m0, s19, 0xc000
	ds_read_b128 v[190:193], v161
	ds_read_b128 v[194:197], v161 offset:1024
	ds_read_b128 v[198:201], v161 offset:2048
	ds_read_b128 v[202:205], v161 offset:3072
	ds_read_b128 v[206:209], v161 offset:4096
	ds_read_b128 v[210:213], v161 offset:5120
	ds_read_b128 v[214:217], v161 offset:6144
	ds_read_b128 v[218:221], v161 offset:7168
	global_load_lds_dwordx4 v138, s[22:23]
	s_add_i32 m0, s19, 0xe000
	s_nop 0
	global_load_lds_dwordx4 v140, s[22:23]
	s_waitcnt vmcnt(8)
	s_waitcnt lgkmcnt(0)
	s_barrier
	s_setprio 1
	v_mfma_f32_16x16x32_bf16 v[118:121], v[148:151], v[190:193], v[118:121]
	v_mfma_f32_16x16x32_bf16 v[114:117], v[166:169], v[190:193], v[114:117]
	v_mfma_f32_16x16x32_bf16 v[102:105], v[148:151], v[198:201], v[102:105]
	v_mfma_f32_16x16x32_bf16 v[98:101], v[166:169], v[198:201], v[98:101]
	v_mfma_f32_16x16x32_bf16 v[86:89], v[148:151], v[206:209], v[86:89]
	v_mfma_f32_16x16x32_bf16 v[82:85], v[166:169], v[206:209], v[82:85]
	v_mfma_f32_16x16x32_bf16 v[70:73], v[148:151], v[214:217], v[70:73]
	v_mfma_f32_16x16x32_bf16 v[66:69], v[166:169], v[214:217], v[66:69]
	v_mfma_f32_16x16x32_bf16 v[118:121], v[156:159], v[194:197], v[118:121]
	v_mfma_f32_16x16x32_bf16 v[114:117], v[170:173], v[194:197], v[114:117]
	v_mfma_f32_16x16x32_bf16 v[102:105], v[156:159], v[202:205], v[102:105]
	v_mfma_f32_16x16x32_bf16 v[98:101], v[170:173], v[202:205], v[98:101]
	v_mfma_f32_16x16x32_bf16 v[86:89], v[156:159], v[210:213], v[86:89]
	v_mfma_f32_16x16x32_bf16 v[82:85], v[170:173], v[210:213], v[82:85]
	v_mfma_f32_16x16x32_bf16 v[70:73], v[156:159], v[218:221], v[70:73]
	v_mfma_f32_16x16x32_bf16 v[66:69], v[170:173], v[218:221], v[66:69]
	v_mfma_f32_16x16x32_bf16 v[126:129], v[174:177], v[190:193], v[126:129]
	v_mfma_f32_16x16x32_bf16 v[122:125], v[182:185], v[190:193], v[122:125]
	v_mfma_f32_16x16x32_bf16 v[110:113], v[174:177], v[198:201], v[110:113]
	v_mfma_f32_16x16x32_bf16 v[106:109], v[182:185], v[198:201], v[106:109]
	v_mfma_f32_16x16x32_bf16 v[94:97], v[174:177], v[206:209], v[94:97]
	v_mfma_f32_16x16x32_bf16 v[90:93], v[182:185], v[206:209], v[90:93]
	v_mfma_f32_16x16x32_bf16 v[78:81], v[174:177], v[214:217], v[78:81]
	v_mfma_f32_16x16x32_bf16 v[74:77], v[182:185], v[214:217], v[74:77]
	v_mfma_f32_16x16x32_bf16 v[126:129], v[178:181], v[194:197], v[126:129]
	v_mfma_f32_16x16x32_bf16 v[122:125], v[186:189], v[194:197], v[122:125]
	v_mfma_f32_16x16x32_bf16 v[110:113], v[178:181], v[202:205], v[110:113]
	v_mfma_f32_16x16x32_bf16 v[106:109], v[186:189], v[202:205], v[106:109]
	v_mfma_f32_16x16x32_bf16 v[94:97], v[178:181], v[210:213], v[94:97]
	v_mfma_f32_16x16x32_bf16 v[90:93], v[186:189], v[210:213], v[90:93]
	v_mfma_f32_16x16x32_bf16 v[78:81], v[178:181], v[218:221], v[78:81]
	v_mfma_f32_16x16x32_bf16 v[74:77], v[186:189], v[218:221], v[74:77]
	s_setprio 0
	s_barrier
	s_add_i32 s63, s43, s26
	s_mov_b32 m0, s63
	ds_read_b128 v[190:193], v161 offset:16384
	ds_read_b128 v[194:197], v161 offset:17408
	ds_read_b128 v[198:201], v161 offset:18432
	ds_read_b128 v[202:205], v161 offset:19456
	ds_read_b128 v[206:209], v161 offset:20480
	ds_read_b128 v[210:213], v161 offset:21504
	ds_read_b128 v[214:217], v161 offset:22528
	ds_read_b128 v[218:221], v161 offset:23552
	global_load_lds_dwordx4 v132, s[20:21]
	s_add_i32 m0, s63, 0x2000
	s_add_u32 s64, s20, 0x100000
	s_addc_u32 s65, s21, 0
	s_add_i32 s63, s46, s26
	global_load_lds_dwordx4 v136, s[20:21]
	s_mov_b32 m0, s63
	s_add_u32 s100, s24, 0x80
	s_addc_u32 s101, s25, 0
	global_load_lds_dwordx4 v132, s[64:65]
	s_add_i32 m0, s63, 0x2000
	s_nop 0
	global_load_lds_dwordx4 v136, s[64:65]
	s_mov_b32 m0, s19
	s_nop 0
	global_load_lds_dwordx4 v130, s[24:25]
	s_mov_b32 m0, s29
	s_nop 0
	global_load_lds_dwordx4 v134, s[24:25]
	s_waitcnt vmcnt(8)
	s_waitcnt lgkmcnt(0)
	s_barrier
	s_setprio 1
	v_mfma_f32_16x16x32_bf16 v[54:57], v[148:151], v[190:193], v[54:57]
	v_mfma_f32_16x16x32_bf16 v[50:53], v[166:169], v[190:193], v[50:53]
	v_mfma_f32_16x16x32_bf16 v[38:41], v[148:151], v[198:201], v[38:41]
	v_mfma_f32_16x16x32_bf16 v[34:37], v[166:169], v[198:201], v[34:37]
	v_mfma_f32_16x16x32_bf16 v[22:25], v[148:151], v[206:209], v[22:25]
	v_mfma_f32_16x16x32_bf16 v[18:21], v[166:169], v[206:209], v[18:21]
	v_mfma_f32_16x16x32_bf16 v[6:9], v[148:151], v[214:217], v[6:9]
	v_mfma_f32_16x16x32_bf16 v[2:5], v[166:169], v[214:217], v[2:5]
	v_mfma_f32_16x16x32_bf16 v[54:57], v[156:159], v[194:197], v[54:57]
	v_mfma_f32_16x16x32_bf16 v[50:53], v[170:173], v[194:197], v[50:53]
	v_mfma_f32_16x16x32_bf16 v[38:41], v[156:159], v[202:205], v[38:41]
	v_mfma_f32_16x16x32_bf16 v[34:37], v[170:173], v[202:205], v[34:37]
	v_mfma_f32_16x16x32_bf16 v[22:25], v[156:159], v[210:213], v[22:25]
	v_mfma_f32_16x16x32_bf16 v[18:21], v[170:173], v[210:213], v[18:21]
	v_mfma_f32_16x16x32_bf16 v[6:9], v[156:159], v[218:221], v[6:9]
	v_mfma_f32_16x16x32_bf16 v[2:5], v[170:173], v[218:221], v[2:5]
	v_mfma_f32_16x16x32_bf16 v[62:65], v[174:177], v[190:193], v[62:65]
	v_mfma_f32_16x16x32_bf16 v[58:61], v[182:185], v[190:193], v[58:61]
	v_mfma_f32_16x16x32_bf16 v[46:49], v[174:177], v[198:201], v[46:49]
	v_mfma_f32_16x16x32_bf16 v[42:45], v[182:185], v[198:201], v[42:45]
	v_mfma_f32_16x16x32_bf16 v[30:33], v[174:177], v[206:209], v[30:33]
	v_mfma_f32_16x16x32_bf16 v[26:29], v[182:185], v[206:209], v[26:29]
	v_mfma_f32_16x16x32_bf16 v[10:13], v[174:177], v[214:217], v[10:13]
	v_mfma_f32_16x16x32_bf16 v[14:17], v[182:185], v[214:217], v[14:17]
	v_mfma_f32_16x16x32_bf16 v[62:65], v[178:181], v[194:197], v[62:65]
	v_mfma_f32_16x16x32_bf16 v[58:61], v[186:189], v[194:197], v[58:61]
	v_mfma_f32_16x16x32_bf16 v[46:49], v[178:181], v[202:205], v[46:49]
	v_mfma_f32_16x16x32_bf16 v[42:45], v[186:189], v[202:205], v[42:45]
	v_mfma_f32_16x16x32_bf16 v[30:33], v[178:181], v[210:213], v[30:33]
	v_mfma_f32_16x16x32_bf16 v[26:29], v[186:189], v[210:213], v[26:29]
	v_mfma_f32_16x16x32_bf16 v[10:13], v[178:181], v[218:221], v[10:13]
	v_mfma_f32_16x16x32_bf16 v[14:17], v[186:189], v[218:221], v[14:17]
	s_setprio 0
	s_barrier
; #define PG8_STAGE(bufoff, gbase, voff) do { _Pragma("unroll") for (int _i = 0; _i < 2; ++_i) \
;         __builtin_amdgcn_global_load_lds((const unsigned*)((const char*)(gbase) + (voff)[_i]), (PG8_LAS unsigned*)(lds + (bufoff) + ldsw + _i * 8192), 16, 0, 0); } while (0)
; #define PG8_LDA(dst, b, h) do { _Pragma("unroll") for (int m = 0; m < 4; ++m) _Pragma("unroll") for (int k = 0; k < 2; ++k) dst[m][k] = *(const PG8_LAS bf16x8*)(lds + PG8_SA(b, h) + aoff + m * 2048 + k * 1024); } while (0)
; #define PG8_LDB(dst, b, h) do { _Pragma("unroll") for (int n = 0; n < 2; ++n) _Pragma("unroll") for (int k = 0; k < 2; ++k) dst[n][k] = *(const PG8_LAS bf16x8*)(lds + PG8_SB(b, h) + boff + n * 2048 + k * 1024); } while (0)
; #define PG8_MMA(ai, bj, At, Bt) do { __builtin_amdgcn_s_setprio(1); _Pragma("unroll") for (int m = 0; m < 4; ++m) _Pragma("unroll") for (int n = 0; n < 2; ++n) _Pragma("unroll") for (int k = 0; k < 2; ++k) \
;         acc[ai][bj][m][n] = __builtin_amdgcn_mfma_f32_16x16x32_bf16(Bt[n][k], At[m][k], acc[ai][bj][m][n], 0, 0, 0); __builtin_amdgcn_s_setprio(0); } while (0)
; #define PG8_WAIT_V(n) asm volatile("s_waitcnt vmcnt(" #n ")" ::: "memory")
; #define PG8_WAIT_L(n) asm volatile("s_waitcnt lgkmcnt(" #n ")" ::: "memory")
; #define PG8_BAR __builtin_amdgcn_s_barrier()
; #define PG8_SCHED __builtin_amdgcn_sched_barrier(0)
; template <class Epi, class Sched, bool ALIGN_EPI = false, bool SP2 = false>
; __device__ __forceinline__ void gemm_phase(PG8_LAS unsigned char* lds, const Gemm g, const Sched& S, const Epi& E) {
;     ...
;             PG8_LDB(B0, 1, 0); PG8_LDB(B1, 1, 1); PG8_SCHED; PG8_LDA(At, 1, 0); PG8_STAGE(PG8_SA(0, 1), a2 + hstep, voffA);
;             PG8_WAIT_V(8); PG8_WAIT_L(0); PG8_BAR; PG8_MMA(0, 0, At, B0); PG8_MMA(0, 1, At, B1); PG8_BAR; PG8_SCHED;
;             PG8_LDA(At, 1, 1); PG8_STAGE(PG8_SB(1, 0), b3, voffB); PG8_STAGE(PG8_SB(1, 1), b3 + hstep, voffB); PG8_STAGE(PG8_SA(1, 0), a3, voffA);
;             PG8_WAIT_V(8); PG8_WAIT_L(0); PG8_BAR; PG8_MMA(1, 0, At, B0); PG8_MMA(1, 1, At, B1); PG8_BAR; PG8_SCHED;
;     ...
;         }
;         if constexpr (ALIGN_EPI) { if (wr == 0) PG8_BAR; }
	s_add_i32 s63, 0, 0x18000
	s_add_i32 s64, 0, 0x1c000
	ds_read_b128 v[148:151], v241 offset:32768
	ds_read_b128 v[156:159], v241 offset:33792
	ds_read_b128 v[166:169], v241 offset:34816
	ds_read_b128 v[170:173], v241 offset:35840
	ds_read_b128 v[174:177], v241 offset:49152
	ds_read_b128 v[178:181], v241 offset:50176
	ds_read_b128 v[182:185], v241 offset:51200
	ds_read_b128 v[186:189], v241 offset:52224
	s_add_u32 s24, s24, 0x100000
	s_addc_u32 s25, s25, 0
	s_mov_b32 m0, s30
	ds_read_b128 v[190:193], v161 offset:32768
	ds_read_b128 v[194:197], v161 offset:33792
	ds_read_b128 v[198:201], v161 offset:34816
	ds_read_b128 v[202:205], v161 offset:35840
	ds_read_b128 v[206:209], v161 offset:36864
	ds_read_b128 v[210:213], v161 offset:37888
	ds_read_b128 v[214:217], v161 offset:38912
	ds_read_b128 v[218:221], v161 offset:39936
	global_load_lds_dwordx4 v130, s[24:25]
	s_mov_b32 m0, s31
	s_nop 0
	global_load_lds_dwordx4 v134, s[24:25]
	s_waitcnt vmcnt(8)
	s_waitcnt lgkmcnt(0)
	s_barrier
	s_setprio 1
	v_mfma_f32_16x16x32_bf16 v[118:121], v[148:151], v[190:193], v[118:121]
	v_mfma_f32_16x16x32_bf16 v[114:117], v[166:169], v[190:193], v[114:117]
	v_mfma_f32_16x16x32_bf16 v[102:105], v[148:151], v[198:201], v[102:105]
	v_mfma_f32_16x16x32_bf16 v[98:101], v[166:169], v[198:201], v[98:101]
	v_mfma_f32_16x16x32_bf16 v[86:89], v[148:151], v[206:209], v[86:89]
	v_mfma_f32_16x16x32_bf16 v[82:85], v[166:169], v[206:209], v[82:85]
	v_mfma_f32_16x16x32_bf16 v[70:73], v[148:151], v[214:217], v[70:73]
	v_mfma_f32_16x16x32_bf16 v[66:69], v[166:169], v[214:217], v[66:69]
	v_mfma_f32_16x16x32_bf16 v[118:121], v[156:159], v[194:197], v[118:121]
	v_mfma_f32_16x16x32_bf16 v[114:117], v[170:173], v[194:197], v[114:117]
	v_mfma_f32_16x16x32_bf16 v[102:105], v[156:159], v[202:205], v[102:105]
	v_mfma_f32_16x16x32_bf16 v[98:101], v[170:173], v[202:205], v[98:101]
	v_mfma_f32_16x16x32_bf16 v[86:89], v[156:159], v[210:213], v[86:89]
	v_mfma_f32_16x16x32_bf16 v[82:85], v[170:173], v[210:213], v[82:85]
	v_mfma_f32_16x16x32_bf16 v[70:73], v[156:159], v[218:221], v[70:73]
	v_mfma_f32_16x16x32_bf16 v[66:69], v[170:173], v[218:221], v[66:69]
	v_mfma_f32_16x16x32_bf16 v[126:129], v[174:177], v[190:193], v[126:129]
	v_mfma_f32_16x16x32_bf16 v[122:125], v[182:185], v[190:193], v[122:125]
	v_mfma_f32_16x16x32_bf16 v[110:113], v[174:177], v[198:201], v[110:113]
	v_mfma_f32_16x16x32_bf16 v[106:109], v[182:185], v[198:201], v[106:109]
	v_mfma_f32_16x16x32_bf16 v[94:97], v[174:177], v[206:209], v[94:97]
	v_mfma_f32_16x16x32_bf16 v[90:93], v[182:185], v[206:209], v[90:93]
	v_mfma_f32_16x16x32_bf16 v[78:81], v[174:177], v[214:217], v[78:81]
	v_mfma_f32_16x16x32_bf16 v[74:77], v[182:185], v[214:217], v[74:77]
	v_mfma_f32_16x16x32_bf16 v[126:129], v[178:181], v[194:197], v[126:129]
	v_mfma_f32_16x16x32_bf16 v[122:125], v[186:189], v[194:197], v[122:125]
	v_mfma_f32_16x16x32_bf16 v[110:113], v[178:181], v[202:205], v[110:113]
	v_mfma_f32_16x16x32_bf16 v[106:109], v[186:189], v[202:205], v[106:109]
	v_mfma_f32_16x16x32_bf16 v[94:97], v[178:181], v[210:213], v[94:97]
	v_mfma_f32_16x16x32_bf16 v[90:93], v[186:189], v[210:213], v[90:93]
	v_mfma_f32_16x16x32_bf16 v[78:81], v[178:181], v[218:221], v[78:81]
	v_mfma_f32_16x16x32_bf16 v[74:77], v[186:189], v[218:221], v[74:77]
	s_setprio 0
	s_barrier
	s_add_i32 s24, s63, s26
	s_add_i32 m0, s24, 0xffffff80
	ds_read_b128 v[190:193], v161 offset:49152
	ds_read_b128 v[194:197], v161 offset:50176
	ds_read_b128 v[198:201], v161 offset:51200
	ds_read_b128 v[202:205], v161 offset:52224
	ds_read_b128 v[206:209], v161 offset:53248
	ds_read_b128 v[210:213], v161 offset:54272
	ds_read_b128 v[214:217], v161 offset:55296
	ds_read_b128 v[218:221], v161 offset:56320
	global_load_lds_dwordx4 v132, s[20:21] offset:128
	s_add_i32 m0, s24, 0x1f80
	s_add_i32 s24, s64, s26
	global_load_lds_dwordx4 v136, s[20:21] offset:128
	s_add_u32 s20, s20, 0x100080
	s_addc_u32 s21, s21, 0
	s_mov_b32 m0, s24
	s_nop 0
	global_load_lds_dwordx4 v132, s[20:21]
	s_add_i32 m0, s24, 0x2000
	s_nop 0
	global_load_lds_dwordx4 v136, s[20:21]
	s_mov_b32 m0, s40
	s_nop 0
	global_load_lds_dwordx4 v130, s[100:101]
	s_mov_b32 m0, s41
	s_nop 0
	global_load_lds_dwordx4 v134, s[100:101]
	s_waitcnt vmcnt(8)
	s_waitcnt lgkmcnt(0)
	s_barrier
	s_setprio 1
	v_mfma_f32_16x16x32_bf16 v[54:57], v[148:151], v[190:193], v[54:57]
	v_mfma_f32_16x16x32_bf16 v[50:53], v[166:169], v[190:193], v[50:53]
	v_mfma_f32_16x16x32_bf16 v[38:41], v[148:151], v[198:201], v[38:41]
	v_mfma_f32_16x16x32_bf16 v[34:37], v[166:169], v[198:201], v[34:37]
	v_mfma_f32_16x16x32_bf16 v[22:25], v[148:151], v[206:209], v[22:25]
	v_mfma_f32_16x16x32_bf16 v[18:21], v[166:169], v[206:209], v[18:21]
	v_mfma_f32_16x16x32_bf16 v[6:9], v[148:151], v[214:217], v[6:9]
	v_mfma_f32_16x16x32_bf16 v[2:5], v[166:169], v[214:217], v[2:5]
	v_mfma_f32_16x16x32_bf16 v[54:57], v[156:159], v[194:197], v[54:57]
	v_mfma_f32_16x16x32_bf16 v[50:53], v[170:173], v[194:197], v[50:53]
	v_mfma_f32_16x16x32_bf16 v[38:41], v[156:159], v[202:205], v[38:41]
	v_mfma_f32_16x16x32_bf16 v[34:37], v[170:173], v[202:205], v[34:37]
	v_mfma_f32_16x16x32_bf16 v[22:25], v[156:159], v[210:213], v[22:25]
	v_mfma_f32_16x16x32_bf16 v[18:21], v[170:173], v[210:213], v[18:21]
	v_mfma_f32_16x16x32_bf16 v[6:9], v[156:159], v[218:221], v[6:9]
	v_mfma_f32_16x16x32_bf16 v[2:5], v[170:173], v[218:221], v[2:5]
	v_mfma_f32_16x16x32_bf16 v[62:65], v[174:177], v[190:193], v[62:65]
	v_mfma_f32_16x16x32_bf16 v[58:61], v[182:185], v[190:193], v[58:61]
	v_mfma_f32_16x16x32_bf16 v[46:49], v[174:177], v[198:201], v[46:49]
	v_mfma_f32_16x16x32_bf16 v[42:45], v[182:185], v[198:201], v[42:45]
	v_mfma_f32_16x16x32_bf16 v[30:33], v[174:177], v[206:209], v[30:33]
	v_mfma_f32_16x16x32_bf16 v[26:29], v[182:185], v[206:209], v[26:29]
	v_mfma_f32_16x16x32_bf16 v[10:13], v[174:177], v[214:217], v[10:13]
	v_mfma_f32_16x16x32_bf16 v[14:17], v[182:185], v[214:217], v[14:17]
	v_mfma_f32_16x16x32_bf16 v[62:65], v[178:181], v[194:197], v[62:65]
	v_mfma_f32_16x16x32_bf16 v[58:61], v[186:189], v[194:197], v[58:61]
	v_mfma_f32_16x16x32_bf16 v[46:49], v[178:181], v[202:205], v[46:49]
	v_mfma_f32_16x16x32_bf16 v[42:45], v[186:189], v[202:205], v[42:45]
	v_mfma_f32_16x16x32_bf16 v[30:33], v[178:181], v[210:213], v[30:33]
	v_mfma_f32_16x16x32_bf16 v[26:29], v[186:189], v[210:213], v[26:29]
	v_mfma_f32_16x16x32_bf16 v[10:13], v[178:181], v[218:221], v[10:13]
	v_mfma_f32_16x16x32_bf16 v[14:17], v[186:189], v[218:221], v[14:17]
	s_setprio 0
	s_barrier
	s_add_i32 s35, s35, 2
	s_add_u32 s22, s22, 0x100
	s_addc_u32 s23, s23, 0
	s_add_u32 s62, s62, 0x100
	s_addc_u32 s34, s34, 0
	s_cmp_gt_u32 s35, 61
	s_cbranch_scc0 .LBB0_673
	s_and_b64 vcc, exec, s[8:9]
	s_cbranch_vccz .LBB0_676
	s_barrier

; #define PG8_STAGE(bufoff, gbase, voff) do { _Pragma("unroll") for (int _i = 0; _i < 2; ++_i) \
;         __builtin_amdgcn_global_load_lds((const unsigned*)((const char*)(gbase) + (voff)[_i]), (PG8_LAS unsigned*)(lds + (bufoff) + ldsw + _i * 8192), 16, 0, 0); } while (0)
; #define PG8_LDA(dst, b, h) do { _Pragma("unroll") for (int m = 0; m < 4; ++m) _Pragma("unroll") for (int k = 0; k < 2; ++k) dst[m][k] = *(const PG8_LAS bf16x8*)(lds + PG8_SA(b, h) + aoff + m * 2048 + k * 1024); } while (0)
; #define PG8_LDB(dst, b, h) do { _Pragma("unroll") for (int n = 0; n < 2; ++n) _Pragma("unroll") for (int k = 0; k < 2; ++k) dst[n][k] = *(const PG8_LAS bf16x8*)(lds + PG8_SB(b, h) + boff + n * 2048 + k * 1024); } while (0)
; #define PG8_MMA(ai, bj, At, Bt) do { __builtin_amdgcn_s_setprio(1); _Pragma("unroll") for (int m = 0; m < 4; ++m) _Pragma("unroll") for (int n = 0; n < 2; ++n) _Pragma("unroll") for (int k = 0; k < 2; ++k) \
;         acc[ai][bj][m][n] = __builtin_amdgcn_mfma_f32_16x16x32_bf16(Bt[n][k], At[m][k], acc[ai][bj][m][n], 0, 0, 0); __builtin_amdgcn_s_setprio(0); } while (0)
; #define PG8_WAIT_V(n) asm volatile("s_waitcnt vmcnt(" #n ")" ::: "memory")
; #define PG8_BAR __builtin_amdgcn_s_barrier()
; template <class Epi, class Sched, bool ALIGN_EPI = false, bool SP2 = false>
; __device__ __forceinline__ void gemm_phase(PG8_LAS unsigned char* lds, const Gemm g, const Sched& S, const Epi& E) {
;     ...
;         for (int t = 0; t < nt; t += 2) {
;             const bool last = (t == nt - 2);
;             const char* a1 = cA + (size_t)(t + 1) * kstep;
;             const char* a2 = last ? nA : cA + (size_t)(t + 2) * kstep; const char* b2 = last ? nB : cB + (size_t)(t + 2) * kstep;
;             const char* a3 = a2 + kstep; const char* b3 = b2 + kstep;
;             if (last && has_next) S.a_ready(nxt);
;             if constexpr (SP2) {
;             PG8_LDB(B0, 0, 0); PG8_LDB(B1, 0, 1); PG8_SCHED; PG8_LDA(At, 0, 0); PG8_STAGE(PG8_SA(1, 1), a1 + hstep, voffA);
;             PG8_WAIT_V(8); PG8_WAIT_L(0); PG8_BAR; PG8_MMA(0, 0, At, B0); PG8_MMA(0, 1, At, B1); PG8_BAR; PG8_SCHED;
;             PG8_LDA(At, 0, 1); PG8_STAGE(PG8_SB(0, 0), b2, voffB); PG8_STAGE(PG8_SB(0, 1), b2 + hstep, voffB); PG8_STAGE(PG8_SA(0, 0), a2, voffA);
;             PG8_WAIT_V(8); PG8_WAIT_L(0); PG8_BAR; PG8_MMA(1, 0, At, B0); PG8_MMA(1, 1, At, B1); PG8_BAR; PG8_SCHED;
.LBB0_1039:
	ds_read_b128 v[130:133], v241 offset:0
	ds_read_b128 v[134:137], v241 offset:1024
	ds_read_b128 v[138:141], v241 offset:2048
	ds_read_b128 v[142:145], v241 offset:3072
	ds_read_b128 v[146:149], v241 offset:16384
	ds_read_b128 v[150:153], v241 offset:17408
	ds_read_b128 v[172:175], v241 offset:18432
	ds_read_b128 v[176:179], v241 offset:19456
	s_add_u32 s24, s26, 0xfff00080
	s_addc_u32 s25, s27, -1
	s_cmp_eq_u32 s68, 60
	s_cselect_b32 s29, s15, s25
	s_cselect_b32 s28, s21, s24
	s_cselect_b32 s25, s13, s67
	s_cselect_b32 s24, s65, s66
	s_add_i32 m0, s23, 0xc000
	ds_read_b128 v[180:183], v185
	ds_read_b128 v[188:191], v185 offset:1024
	ds_read_b128 v[192:195], v185 offset:2048
	ds_read_b128 v[196:199], v185 offset:3072
	ds_read_b128 v[200:203], v185 offset:4096
	ds_read_b128 v[204:207], v185 offset:5120
	ds_read_b128 v[208:211], v185 offset:6144
	ds_read_b128 v[212:215], v185 offset:7168
	global_load_lds_dwordx4 v162, s[26:27]
	s_add_i32 m0, s23, 0xe000
	s_nop 0
	global_load_lds_dwordx4 v166, s[26:27]
	s_waitcnt vmcnt(8)
	s_waitcnt lgkmcnt(0)
	s_barrier
	s_setprio 1
	v_mfma_f32_16x16x32_bf16 v[114:117], v[130:133], v[180:183], v[114:117]
	v_mfma_f32_16x16x32_bf16 v[118:121], v[138:141], v[180:183], v[118:121]
	v_mfma_f32_16x16x32_bf16 v[106:109], v[130:133], v[192:195], v[106:109]
	v_mfma_f32_16x16x32_bf16 v[98:101], v[138:141], v[192:195], v[98:101]
	v_mfma_f32_16x16x32_bf16 v[90:93], v[130:133], v[200:203], v[90:93]
	v_mfma_f32_16x16x32_bf16 v[82:85], v[138:141], v[200:203], v[82:85]
	v_mfma_f32_16x16x32_bf16 v[74:77], v[130:133], v[208:211], v[74:77]
	v_mfma_f32_16x16x32_bf16 v[66:69], v[138:141], v[208:211], v[66:69]
	v_mfma_f32_16x16x32_bf16 v[114:117], v[134:137], v[188:191], v[114:117]
	v_mfma_f32_16x16x32_bf16 v[118:121], v[142:145], v[188:191], v[118:121]
	v_mfma_f32_16x16x32_bf16 v[106:109], v[134:137], v[196:199], v[106:109]
	v_mfma_f32_16x16x32_bf16 v[98:101], v[142:145], v[196:199], v[98:101]
	v_mfma_f32_16x16x32_bf16 v[90:93], v[134:137], v[204:207], v[90:93]
	v_mfma_f32_16x16x32_bf16 v[82:85], v[142:145], v[204:207], v[82:85]
	v_mfma_f32_16x16x32_bf16 v[74:77], v[134:137], v[212:215], v[74:77]
	v_mfma_f32_16x16x32_bf16 v[66:69], v[142:145], v[212:215], v[66:69]
	v_mfma_f32_16x16x32_bf16 v[122:125], v[146:149], v[180:183], v[122:125]
	v_mfma_f32_16x16x32_bf16 v[126:129], v[172:175], v[180:183], v[126:129]
	v_mfma_f32_16x16x32_bf16 v[110:113], v[146:149], v[192:195], v[110:113]
	v_mfma_f32_16x16x32_bf16 v[102:105], v[172:175], v[192:195], v[102:105]
	v_mfma_f32_16x16x32_bf16 v[94:97], v[146:149], v[200:203], v[94:97]
	v_mfma_f32_16x16x32_bf16 v[86:89], v[172:175], v[200:203], v[86:89]
	v_mfma_f32_16x16x32_bf16 v[78:81], v[146:149], v[208:211], v[78:81]
	v_mfma_f32_16x16x32_bf16 v[70:73], v[172:175], v[208:211], v[70:73]
	v_mfma_f32_16x16x32_bf16 v[122:125], v[150:153], v[188:191], v[122:125]
	v_mfma_f32_16x16x32_bf16 v[126:129], v[176:179], v[188:191], v[126:129]
	v_mfma_f32_16x16x32_bf16 v[110:113], v[150:153], v[196:199], v[110:113]
	v_mfma_f32_16x16x32_bf16 v[102:105], v[176:179], v[196:199], v[102:105]
	v_mfma_f32_16x16x32_bf16 v[94:97], v[150:153], v[204:207], v[94:97]
	v_mfma_f32_16x16x32_bf16 v[86:89], v[176:179], v[204:207], v[86:89]
	v_mfma_f32_16x16x32_bf16 v[78:81], v[150:153], v[212:215], v[78:81]
	v_mfma_f32_16x16x32_bf16 v[70:73], v[176:179], v[212:215], v[70:73]
	s_setprio 0
	s_barrier
	s_add_i32 s33, s62, s36
	s_mov_b32 m0, s33
	ds_read_b128 v[180:183], v185 offset:16384
	ds_read_b128 v[188:191], v185 offset:17408
	ds_read_b128 v[192:195], v185 offset:18432
	ds_read_b128 v[196:199], v185 offset:19456
	ds_read_b128 v[200:203], v185 offset:20480
	ds_read_b128 v[204:207], v185 offset:21504
	ds_read_b128 v[208:211], v185 offset:22528
	ds_read_b128 v[212:215], v185 offset:23552
	global_load_lds_dwordx4 v156, s[24:25]
	s_add_i32 m0, s33, 0x2000
	s_add_u32 s72, s24, 0x100000
	s_addc_u32 s73, s25, 0
	s_add_i32 s33, s63, s36
	global_load_lds_dwordx4 v160, s[24:25]
	s_mov_b32 m0, s33
	s_add_u32 s100, s28, 0x80
	s_addc_u32 s101, s29, 0
	global_load_lds_dwordx4 v156, s[72:73]
	s_add_i32 m0, s33, 0x2000
	s_nop 0
	global_load_lds_dwordx4 v160, s[72:73]
	s_mov_b32 m0, s23
	s_nop 0
	global_load_lds_dwordx4 v154, s[28:29]
	s_mov_b32 m0, s37
	s_nop 0
	global_load_lds_dwordx4 v158, s[28:29]
	s_waitcnt vmcnt(8)
	s_waitcnt lgkmcnt(0)
	s_barrier
	s_setprio 1
	v_mfma_f32_16x16x32_bf16 v[58:61], v[130:133], v[180:183], v[58:61]
	v_mfma_f32_16x16x32_bf16 v[54:57], v[138:141], v[180:183], v[54:57]
	v_mfma_f32_16x16x32_bf16 v[42:45], v[130:133], v[192:195], v[42:45]
	v_mfma_f32_16x16x32_bf16 v[34:37], v[138:141], v[192:195], v[34:37]
	v_mfma_f32_16x16x32_bf16 v[26:29], v[130:133], v[200:203], v[26:29]
	v_mfma_f32_16x16x32_bf16 v[18:21], v[138:141], v[200:203], v[18:21]
	v_mfma_f32_16x16x32_bf16 v[6:9], v[130:133], v[208:211], v[6:9]
	v_mfma_f32_16x16x32_bf16 v[2:5], v[138:141], v[208:211], v[2:5]
	v_mfma_f32_16x16x32_bf16 v[58:61], v[134:137], v[188:191], v[58:61]
	v_mfma_f32_16x16x32_bf16 v[54:57], v[142:145], v[188:191], v[54:57]
	v_mfma_f32_16x16x32_bf16 v[42:45], v[134:137], v[196:199], v[42:45]
	v_mfma_f32_16x16x32_bf16 v[34:37], v[142:145], v[196:199], v[34:37]
	v_mfma_f32_16x16x32_bf16 v[26:29], v[134:137], v[204:207], v[26:29]
	v_mfma_f32_16x16x32_bf16 v[18:21], v[142:145], v[204:207], v[18:21]
	v_mfma_f32_16x16x32_bf16 v[6:9], v[134:137], v[212:215], v[6:9]
	v_mfma_f32_16x16x32_bf16 v[2:5], v[142:145], v[212:215], v[2:5]
	v_mfma_f32_16x16x32_bf16 v[62:65], v[146:149], v[180:183], v[62:65]
	v_mfma_f32_16x16x32_bf16 v[50:53], v[172:175], v[180:183], v[50:53]
	v_mfma_f32_16x16x32_bf16 v[46:49], v[146:149], v[192:195], v[46:49]
	v_mfma_f32_16x16x32_bf16 v[38:41], v[172:175], v[192:195], v[38:41]
	v_mfma_f32_16x16x32_bf16 v[30:33], v[146:149], v[200:203], v[30:33]
	v_mfma_f32_16x16x32_bf16 v[22:25], v[172:175], v[200:203], v[22:25]
	v_mfma_f32_16x16x32_bf16 v[10:13], v[146:149], v[208:211], v[10:13]
	v_mfma_f32_16x16x32_bf16 v[14:17], v[172:175], v[208:211], v[14:17]
	v_mfma_f32_16x16x32_bf16 v[62:65], v[150:153], v[188:191], v[62:65]
	v_mfma_f32_16x16x32_bf16 v[50:53], v[176:179], v[188:191], v[50:53]
	v_mfma_f32_16x16x32_bf16 v[46:49], v[150:153], v[196:199], v[46:49]
	v_mfma_f32_16x16x32_bf16 v[38:41], v[176:179], v[196:199], v[38:41]
	v_mfma_f32_16x16x32_bf16 v[30:33], v[150:153], v[204:207], v[30:33]
	v_mfma_f32_16x16x32_bf16 v[22:25], v[176:179], v[204:207], v[22:25]
	v_mfma_f32_16x16x32_bf16 v[10:13], v[150:153], v[212:215], v[10:13]
	v_mfma_f32_16x16x32_bf16 v[14:17], v[176:179], v[212:215], v[14:17]
	s_setprio 0
	s_barrier
; #define PG8_STAGE(bufoff, gbase, voff) do { _Pragma("unroll") for (int _i = 0; _i < 2; ++_i) \
;         __builtin_amdgcn_global_load_lds((const unsigned*)((const char*)(gbase) + (voff)[_i]), (PG8_LAS unsigned*)(lds + (bufoff) + ldsw + _i * 8192), 16, 0, 0); } while (0)
; #define PG8_LDA(dst, b, h) do { _Pragma("unroll") for (int m = 0; m < 4; ++m) _Pragma("unroll") for (int k = 0; k < 2; ++k) dst[m][k] = *(const PG8_LAS bf16x8*)(lds + PG8_SA(b, h) + aoff + m * 2048 + k * 1024); } while (0)
; #define PG8_LDB(dst, b, h) do { _Pragma("unroll") for (int n = 0; n < 2; ++n) _Pragma("unroll") for (int k = 0; k < 2; ++k) dst[n][k] = *(const PG8_LAS bf16x8*)(lds + PG8_SB(b, h) + boff + n * 2048 + k * 1024); } while (0)
; #define PG8_MMA(ai, bj, At, Bt) do { __builtin_amdgcn_s_setprio(1); _Pragma("unroll") for (int m = 0; m < 4; ++m) _Pragma("unroll") for (int n = 0; n < 2; ++n) _Pragma("unroll") for (int k = 0; k < 2; ++k) \
;         acc[ai][bj][m][n] = __builtin_amdgcn_mfma_f32_16x16x32_bf16(Bt[n][k], At[m][k], acc[ai][bj][m][n], 0, 0, 0); __builtin_amdgcn_s_setprio(0); } while (0)
; #define PG8_WAIT_V(n) asm volatile("s_waitcnt vmcnt(" #n ")" ::: "memory")
; #define PG8_WAIT_L(n) asm volatile("s_waitcnt lgkmcnt(" #n ")" ::: "memory")
; #define PG8_BAR __builtin_amdgcn_s_barrier()
; #define PG8_SCHED __builtin_amdgcn_sched_barrier(0)
; template <class Epi, class Sched, bool ALIGN_EPI = false, bool SP2 = false>
; __device__ __forceinline__ void gemm_phase(PG8_LAS unsigned char* lds, const Gemm g, const Sched& S, const Epi& E) {
;     ...
;             PG8_LDB(B0, 1, 0); PG8_LDB(B1, 1, 1); PG8_SCHED; PG8_LDA(At, 1, 0); PG8_STAGE(PG8_SA(0, 1), a2 + hstep, voffA);
;             PG8_WAIT_V(8); PG8_WAIT_L(0); PG8_BAR; PG8_MMA(0, 0, At, B0); PG8_MMA(0, 1, At, B1); PG8_BAR; PG8_SCHED;
;             PG8_LDA(At, 1, 1); PG8_STAGE(PG8_SB(1, 0), b3, voffB); PG8_STAGE(PG8_SB(1, 1), b3 + hstep, voffB); PG8_STAGE(PG8_SA(1, 0), a3, voffA);
;             PG8_WAIT_V(8); PG8_WAIT_L(0); PG8_BAR; PG8_MMA(1, 0, At, B0); PG8_MMA(1, 1, At, B1); PG8_BAR; PG8_SCHED;
	s_add_i32 s33, 0, 0x18000
	s_add_i32 s42, 0, 0x1c000
	ds_read_b128 v[130:133], v241 offset:32768
	ds_read_b128 v[134:137], v241 offset:33792
	ds_read_b128 v[138:141], v241 offset:34816
	ds_read_b128 v[142:145], v241 offset:35840
	ds_read_b128 v[146:149], v241 offset:49152
	ds_read_b128 v[150:153], v241 offset:50176
	ds_read_b128 v[172:175], v241 offset:51200
	ds_read_b128 v[176:179], v241 offset:52224
	s_add_u32 s28, s28, 0x100000
	s_addc_u32 s29, s29, 0
	s_mov_b32 m0, s40
	ds_read_b128 v[180:183], v185 offset:32768
	ds_read_b128 v[188:191], v185 offset:33792
	ds_read_b128 v[192:195], v185 offset:34816
	ds_read_b128 v[196:199], v185 offset:35840
	ds_read_b128 v[200:203], v185 offset:36864
	ds_read_b128 v[204:207], v185 offset:37888
	ds_read_b128 v[208:211], v185 offset:38912
	ds_read_b128 v[212:215], v185 offset:39936
	global_load_lds_dwordx4 v154, s[28:29]
	s_mov_b32 m0, s41
	s_nop 0
	global_load_lds_dwordx4 v158, s[28:29]
	s_waitcnt vmcnt(8)
	s_waitcnt lgkmcnt(0)
	s_barrier
	s_setprio 1
	v_mfma_f32_16x16x32_bf16 v[114:117], v[130:133], v[180:183], v[114:117]
	v_mfma_f32_16x16x32_bf16 v[118:121], v[138:141], v[180:183], v[118:121]
	v_mfma_f32_16x16x32_bf16 v[106:109], v[130:133], v[192:195], v[106:109]
	v_mfma_f32_16x16x32_bf16 v[98:101], v[138:141], v[192:195], v[98:101]
	v_mfma_f32_16x16x32_bf16 v[90:93], v[130:133], v[200:203], v[90:93]
	v_mfma_f32_16x16x32_bf16 v[82:85], v[138:141], v[200:203], v[82:85]
	v_mfma_f32_16x16x32_bf16 v[74:77], v[130:133], v[208:211], v[74:77]
	v_mfma_f32_16x16x32_bf16 v[66:69], v[138:141], v[208:211], v[66:69]
	v_mfma_f32_16x16x32_bf16 v[114:117], v[134:137], v[188:191], v[114:117]
	v_mfma_f32_16x16x32_bf16 v[118:121], v[142:145], v[188:191], v[118:121]
	v_mfma_f32_16x16x32_bf16 v[106:109], v[134:137], v[196:199], v[106:109]
	v_mfma_f32_16x16x32_bf16 v[98:101], v[142:145], v[196:199], v[98:101]
	v_mfma_f32_16x16x32_bf16 v[90:93], v[134:137], v[204:207], v[90:93]
	v_mfma_f32_16x16x32_bf16 v[82:85], v[142:145], v[204:207], v[82:85]
	v_mfma_f32_16x16x32_bf16 v[74:77], v[134:137], v[212:215], v[74:77]
	v_mfma_f32_16x16x32_bf16 v[66:69], v[142:145], v[212:215], v[66:69]
	v_mfma_f32_16x16x32_bf16 v[122:125], v[146:149], v[180:183], v[122:125]
	v_mfma_f32_16x16x32_bf16 v[126:129], v[172:175], v[180:183], v[126:129]
	v_mfma_f32_16x16x32_bf16 v[110:113], v[146:149], v[192:195], v[110:113]
	v_mfma_f32_16x16x32_bf16 v[102:105], v[172:175], v[192:195], v[102:105]
	v_mfma_f32_16x16x32_bf16 v[94:97], v[146:149], v[200:203], v[94:97]
	v_mfma_f32_16x16x32_bf16 v[86:89], v[172:175], v[200:203], v[86:89]
	v_mfma_f32_16x16x32_bf16 v[78:81], v[146:149], v[208:211], v[78:81]
	v_mfma_f32_16x16x32_bf16 v[70:73], v[172:175], v[208:211], v[70:73]
	v_mfma_f32_16x16x32_bf16 v[122:125], v[150:153], v[188:191], v[122:125]
	v_mfma_f32_16x16x32_bf16 v[126:129], v[176:179], v[188:191], v[126:129]
	v_mfma_f32_16x16x32_bf16 v[110:113], v[150:153], v[196:199], v[110:113]
	v_mfma_f32_16x16x32_bf16 v[102:105], v[176:179], v[196:199], v[102:105]
	v_mfma_f32_16x16x32_bf16 v[94:97], v[150:153], v[204:207], v[94:97]
	v_mfma_f32_16x16x32_bf16 v[86:89], v[176:179], v[204:207], v[86:89]
	v_mfma_f32_16x16x32_bf16 v[78:81], v[150:153], v[212:215], v[78:81]
	v_mfma_f32_16x16x32_bf16 v[70:73], v[176:179], v[212:215], v[70:73]
	s_setprio 0
	s_barrier
	s_add_i32 s28, s33, s36
	s_add_i32 m0, s28, 0xffffff80
	ds_read_b128 v[180:183], v185 offset:49152
	ds_read_b128 v[188:191], v185 offset:50176
	ds_read_b128 v[192:195], v185 offset:51200
	ds_read_b128 v[196:199], v185 offset:52224
	ds_read_b128 v[200:203], v185 offset:53248
	ds_read_b128 v[204:207], v185 offset:54272
	ds_read_b128 v[208:211], v185 offset:55296
	ds_read_b128 v[212:215], v185 offset:56320
	global_load_lds_dwordx4 v156, s[24:25] offset:128
	s_add_i32 m0, s28, 0x1f80
	s_add_i32 s28, s42, s36
	global_load_lds_dwordx4 v160, s[24:25] offset:128
	s_add_u32 s24, s24, 0x100080
	s_addc_u32 s25, s25, 0
	s_mov_b32 m0, s28
	s_nop 0
	global_load_lds_dwordx4 v156, s[24:25]
	s_add_i32 m0, s28, 0x2000
	s_nop 0
	global_load_lds_dwordx4 v160, s[24:25]
	s_mov_b32 m0, s46
	s_nop 0
	global_load_lds_dwordx4 v154, s[100:101]
	s_mov_b32 m0, s47
	s_nop 0
	global_load_lds_dwordx4 v158, s[100:101]
	s_waitcnt vmcnt(8)
	s_waitcnt lgkmcnt(0)
	s_barrier
	s_setprio 1
	v_mfma_f32_16x16x32_bf16 v[58:61], v[130:133], v[180:183], v[58:61]
	v_mfma_f32_16x16x32_bf16 v[54:57], v[138:141], v[180:183], v[54:57]
	v_mfma_f32_16x16x32_bf16 v[42:45], v[130:133], v[192:195], v[42:45]
	v_mfma_f32_16x16x32_bf16 v[34:37], v[138:141], v[192:195], v[34:37]
	v_mfma_f32_16x16x32_bf16 v[26:29], v[130:133], v[200:203], v[26:29]
	v_mfma_f32_16x16x32_bf16 v[18:21], v[138:141], v[200:203], v[18:21]
	v_mfma_f32_16x16x32_bf16 v[6:9], v[130:133], v[208:211], v[6:9]
	v_mfma_f32_16x16x32_bf16 v[2:5], v[138:141], v[208:211], v[2:5]
	v_mfma_f32_16x16x32_bf16 v[58:61], v[134:137], v[188:191], v[58:61]
	v_mfma_f32_16x16x32_bf16 v[54:57], v[142:145], v[188:191], v[54:57]
	v_mfma_f32_16x16x32_bf16 v[42:45], v[134:137], v[196:199], v[42:45]
	v_mfma_f32_16x16x32_bf16 v[34:37], v[142:145], v[196:199], v[34:37]
	v_mfma_f32_16x16x32_bf16 v[26:29], v[134:137], v[204:207], v[26:29]
	v_mfma_f32_16x16x32_bf16 v[18:21], v[142:145], v[204:207], v[18:21]
	v_mfma_f32_16x16x32_bf16 v[6:9], v[134:137], v[212:215], v[6:9]
	v_mfma_f32_16x16x32_bf16 v[2:5], v[142:145], v[212:215], v[2:5]
	v_mfma_f32_16x16x32_bf16 v[62:65], v[146:149], v[180:183], v[62:65]
	v_mfma_f32_16x16x32_bf16 v[50:53], v[172:175], v[180:183], v[50:53]
	v_mfma_f32_16x16x32_bf16 v[46:49], v[146:149], v[192:195], v[46:49]
	v_mfma_f32_16x16x32_bf16 v[38:41], v[172:175], v[192:195], v[38:41]
	v_mfma_f32_16x16x32_bf16 v[30:33], v[146:149], v[200:203], v[30:33]
	v_mfma_f32_16x16x32_bf16 v[22:25], v[172:175], v[200:203], v[22:25]
	v_mfma_f32_16x16x32_bf16 v[10:13], v[146:149], v[208:211], v[10:13]
	v_mfma_f32_16x16x32_bf16 v[14:17], v[172:175], v[208:211], v[14:17]
	v_mfma_f32_16x16x32_bf16 v[62:65], v[150:153], v[188:191], v[62:65]
	v_mfma_f32_16x16x32_bf16 v[50:53], v[176:179], v[188:191], v[50:53]
	v_mfma_f32_16x16x32_bf16 v[46:49], v[150:153], v[196:199], v[46:49]
	v_mfma_f32_16x16x32_bf16 v[38:41], v[176:179], v[196:199], v[38:41]
	v_mfma_f32_16x16x32_bf16 v[30:33], v[150:153], v[204:207], v[30:33]
	v_mfma_f32_16x16x32_bf16 v[22:25], v[176:179], v[204:207], v[22:25]
	v_mfma_f32_16x16x32_bf16 v[10:13], v[150:153], v[212:215], v[10:13]
	v_mfma_f32_16x16x32_bf16 v[14:17], v[176:179], v[212:215], v[14:17]
	s_setprio 0
	s_barrier
	s_add_i32 s68, s68, 2
	s_add_u32 s26, s26, 0x100
	s_addc_u32 s27, s27, 0
	s_add_u32 s66, s66, 0x100
	s_addc_u32 s67, s67, 0
	s_cmp_gt_u32 s68, 61
	s_cbranch_scc0 .LBB0_1039
	s_and_b64 vcc, exec, s[10:11]
	s_cbranch_vccz .LBB0_1042
	s_barrier

; #define PG8_STAGE(bufoff, gbase, voff) do { _Pragma("unroll") for (int _i = 0; _i < 2; ++_i) \
;         __builtin_amdgcn_global_load_lds((const unsigned*)((const char*)(gbase) + (voff)[_i]), (PG8_LAS unsigned*)(lds + (bufoff) + ldsw + _i * 8192), 16, 0, 0); } while (0)
; #define PG8_LDA(dst, b, h) do { _Pragma("unroll") for (int m = 0; m < 4; ++m) _Pragma("unroll") for (int k = 0; k < 2; ++k) dst[m][k] = *(const PG8_LAS bf16x8*)(lds + PG8_SA(b, h) + aoff + m * 2048 + k * 1024); } while (0)
; #define PG8_LDB(dst, b, h) do { _Pragma("unroll") for (int n = 0; n < 2; ++n) _Pragma("unroll") for (int k = 0; k < 2; ++k) dst[n][k] = *(const PG8_LAS bf16x8*)(lds + PG8_SB(b, h) + boff + n * 2048 + k * 1024); } while (0)
; #define PG8_MMA(ai, bj, At, Bt) do { __builtin_amdgcn_s_setprio(1); _Pragma("unroll") for (int m = 0; m < 4; ++m) _Pragma("unroll") for (int n = 0; n < 2; ++n) _Pragma("unroll") for (int k = 0; k < 2; ++k) \
;         acc[ai][bj][m][n] = __builtin_amdgcn_mfma_f32_16x16x32_bf16(Bt[n][k], At[m][k], acc[ai][bj][m][n], 0, 0, 0); __builtin_amdgcn_s_setprio(0); } while (0)
; #define PG8_WAIT_V(n) asm volatile("s_waitcnt vmcnt(" #n ")" ::: "memory")
; #define PG8_BAR __builtin_amdgcn_s_barrier()
; template <class Epi, class Sched, bool ALIGN_EPI = false, bool SP2 = false>
; __device__ __forceinline__ void gemm_phase(PG8_LAS unsigned char* lds, const Gemm g, const Sched& S, const Epi& E) {
;     ...
;         for (int t = 0; t < nt; t += 2) {
;             const bool last = (t == nt - 2);
;             const char* a1 = cA + (size_t)(t + 1) * kstep;
;             const char* a2 = last ? nA : cA + (size_t)(t + 2) * kstep; const char* b2 = last ? nB : cB + (size_t)(t + 2) * kstep;
;             const char* a3 = a2 + kstep; const char* b3 = b2 + kstep;
;             if (last && has_next) S.a_ready(nxt);
;             if constexpr (SP2) {
;             PG8_LDB(B0, 0, 0); PG8_LDB(B1, 0, 1); PG8_SCHED; PG8_LDA(At, 0, 0); PG8_STAGE(PG8_SA(1, 1), a1 + hstep, voffA);
;             PG8_WAIT_V(8); PG8_WAIT_L(0); PG8_BAR; PG8_MMA(0, 0, At, B0); PG8_MMA(0, 1, At, B1); PG8_BAR; PG8_SCHED;
;             PG8_LDA(At, 0, 1); PG8_STAGE(PG8_SB(0, 0), b2, voffB); PG8_STAGE(PG8_SB(0, 1), b2 + hstep, voffB); PG8_STAGE(PG8_SA(0, 0), a2, voffA);
;             PG8_WAIT_V(8); PG8_WAIT_L(0); PG8_BAR; PG8_MMA(1, 0, At, B0); PG8_MMA(1, 1, At, B1); PG8_BAR; PG8_SCHED;
.LBB0_1126:
	ds_read_b128 v[160:163], v241 offset:0
	ds_read_b128 v[166:169], v241 offset:1024
	ds_read_b128 v[170:173], v241 offset:2048
	ds_read_b128 v[174:177], v241 offset:3072
	ds_read_b128 v[178:181], v241 offset:16384
	ds_read_b128 v[182:185], v241 offset:17408
	ds_read_b128 v[186:189], v241 offset:18432
	ds_read_b128 v[190:193], v241 offset:19456
	s_add_u32 s22, s24, 0xfff00080
	s_addc_u32 s23, s25, -1
	s_cmp_eq_u32 s68, 60
	s_cselect_b32 s27, s15, s23
	s_cselect_b32 s26, s64, s22
	s_cselect_b32 s23, s13, s67
	s_cselect_b32 s22, s65, s66
	s_add_i32 m0, s21, 0xc000
	ds_read_b128 v[194:197], v155
	ds_read_b128 v[198:201], v155 offset:1024
	ds_read_b128 v[202:205], v155 offset:2048
	ds_read_b128 v[206:209], v155 offset:3072
	ds_read_b128 v[210:213], v155 offset:4096
	ds_read_b128 v[214:217], v155 offset:5120
	ds_read_b128 v[218:221], v155 offset:6144
	ds_read_b128 v[222:225], v155 offset:7168
	global_load_lds_dwordx4 v138, s[24:25]
	s_add_i32 m0, s21, 0xe000
	s_nop 0
	global_load_lds_dwordx4 v140, s[24:25]
	s_waitcnt vmcnt(8)
	s_waitcnt lgkmcnt(0)
	s_barrier
	s_setprio 1
	v_mfma_f32_16x16x32_bf16 v[122:125], v[160:163], v[194:197], v[122:125]
	v_mfma_f32_16x16x32_bf16 v[114:117], v[170:173], v[194:197], v[114:117]
	v_mfma_f32_16x16x32_bf16 v[106:109], v[160:163], v[202:205], v[106:109]
	v_mfma_f32_16x16x32_bf16 v[98:101], v[170:173], v[202:205], v[98:101]
	v_mfma_f32_16x16x32_bf16 v[90:93], v[160:163], v[210:213], v[90:93]
	v_mfma_f32_16x16x32_bf16 v[82:85], v[170:173], v[210:213], v[82:85]
	v_mfma_f32_16x16x32_bf16 v[74:77], v[160:163], v[218:221], v[74:77]
	v_mfma_f32_16x16x32_bf16 v[62:65], v[170:173], v[218:221], v[62:65]
	v_mfma_f32_16x16x32_bf16 v[122:125], v[166:169], v[198:201], v[122:125]
	v_mfma_f32_16x16x32_bf16 v[114:117], v[174:177], v[198:201], v[114:117]
	v_mfma_f32_16x16x32_bf16 v[106:109], v[166:169], v[206:209], v[106:109]
	v_mfma_f32_16x16x32_bf16 v[98:101], v[174:177], v[206:209], v[98:101]
	v_mfma_f32_16x16x32_bf16 v[90:93], v[166:169], v[214:217], v[90:93]
	v_mfma_f32_16x16x32_bf16 v[82:85], v[174:177], v[214:217], v[82:85]
	v_mfma_f32_16x16x32_bf16 v[74:77], v[166:169], v[222:225], v[74:77]
	v_mfma_f32_16x16x32_bf16 v[62:65], v[174:177], v[222:225], v[62:65]
	v_mfma_f32_16x16x32_bf16 v[126:129], v[178:181], v[194:197], v[126:129]
	v_mfma_f32_16x16x32_bf16 v[118:121], v[186:189], v[194:197], v[118:121]
	v_mfma_f32_16x16x32_bf16 v[110:113], v[178:181], v[202:205], v[110:113]
	v_mfma_f32_16x16x32_bf16 v[102:105], v[186:189], v[202:205], v[102:105]
	v_mfma_f32_16x16x32_bf16 v[94:97], v[178:181], v[210:213], v[94:97]
	v_mfma_f32_16x16x32_bf16 v[86:89], v[186:189], v[210:213], v[86:89]
	v_mfma_f32_16x16x32_bf16 v[78:81], v[178:181], v[218:221], v[78:81]
	v_mfma_f32_16x16x32_bf16 v[70:73], v[186:189], v[218:221], v[70:73]
	v_mfma_f32_16x16x32_bf16 v[126:129], v[182:185], v[198:201], v[126:129]
	v_mfma_f32_16x16x32_bf16 v[118:121], v[190:193], v[198:201], v[118:121]
	v_mfma_f32_16x16x32_bf16 v[110:113], v[182:185], v[206:209], v[110:113]
	v_mfma_f32_16x16x32_bf16 v[102:105], v[190:193], v[206:209], v[102:105]
	v_mfma_f32_16x16x32_bf16 v[94:97], v[182:185], v[214:217], v[94:97]
	v_mfma_f32_16x16x32_bf16 v[86:89], v[190:193], v[214:217], v[86:89]
	v_mfma_f32_16x16x32_bf16 v[78:81], v[182:185], v[222:225], v[78:81]
	v_mfma_f32_16x16x32_bf16 v[70:73], v[190:193], v[222:225], v[70:73]
	s_setprio 0
	s_barrier
	s_add_i32 s33, s52, s29
	s_mov_b32 m0, s33
	ds_read_b128 v[194:197], v155 offset:16384
	ds_read_b128 v[198:201], v155 offset:17408
	ds_read_b128 v[202:205], v155 offset:18432
	ds_read_b128 v[206:209], v155 offset:19456
	ds_read_b128 v[210:213], v155 offset:20480
	ds_read_b128 v[214:217], v155 offset:21504
	ds_read_b128 v[218:221], v155 offset:22528
	ds_read_b128 v[222:225], v155 offset:23552
	global_load_lds_dwordx4 v132, s[22:23]
	s_add_i32 m0, s33, 0x2000
	s_add_u32 s72, s22, 0x100000
	s_addc_u32 s73, s23, 0
	s_add_i32 s33, s53, s29
	global_load_lds_dwordx4 v136, s[22:23]
	s_mov_b32 m0, s33
	s_add_u32 s100, s26, 0x80
	s_addc_u32 s101, s27, 0
	global_load_lds_dwordx4 v132, s[72:73]
	s_add_i32 m0, s33, 0x2000
	s_nop 0
	global_load_lds_dwordx4 v136, s[72:73]
	s_mov_b32 m0, s21
	s_nop 0
	global_load_lds_dwordx4 v130, s[26:27]
	s_mov_b32 m0, s36
	s_nop 0
	global_load_lds_dwordx4 v134, s[26:27]
	s_waitcnt vmcnt(8)
	s_waitcnt lgkmcnt(0)
	s_barrier
	s_setprio 1
	v_mfma_f32_16x16x32_bf16 v[58:61], v[160:163], v[194:197], v[58:61]
	v_mfma_f32_16x16x32_bf16 v[50:53], v[170:173], v[194:197], v[50:53]
	v_mfma_f32_16x16x32_bf16 v[42:45], v[160:163], v[202:205], v[42:45]
	v_mfma_f32_16x16x32_bf16 v[34:37], v[170:173], v[202:205], v[34:37]
	v_mfma_f32_16x16x32_bf16 v[26:29], v[160:163], v[210:213], v[26:29]
	v_mfma_f32_16x16x32_bf16 v[18:21], v[170:173], v[210:213], v[18:21]
	v_mfma_f32_16x16x32_bf16 v[10:13], v[160:163], v[218:221], v[10:13]
	v_mfma_f32_16x16x32_bf16 v[2:5], v[170:173], v[218:221], v[2:5]
	v_mfma_f32_16x16x32_bf16 v[58:61], v[166:169], v[198:201], v[58:61]
	v_mfma_f32_16x16x32_bf16 v[50:53], v[174:177], v[198:201], v[50:53]
	v_mfma_f32_16x16x32_bf16 v[42:45], v[166:169], v[206:209], v[42:45]
	v_mfma_f32_16x16x32_bf16 v[34:37], v[174:177], v[206:209], v[34:37]
	v_mfma_f32_16x16x32_bf16 v[26:29], v[166:169], v[214:217], v[26:29]
	v_mfma_f32_16x16x32_bf16 v[18:21], v[174:177], v[214:217], v[18:21]
	v_mfma_f32_16x16x32_bf16 v[10:13], v[166:169], v[222:225], v[10:13]
	v_mfma_f32_16x16x32_bf16 v[2:5], v[174:177], v[222:225], v[2:5]
	v_mfma_f32_16x16x32_bf16 v[66:69], v[178:181], v[194:197], v[66:69]
	v_mfma_f32_16x16x32_bf16 v[54:57], v[186:189], v[194:197], v[54:57]
	v_mfma_f32_16x16x32_bf16 v[46:49], v[178:181], v[202:205], v[46:49]
	v_mfma_f32_16x16x32_bf16 v[38:41], v[186:189], v[202:205], v[38:41]
	v_mfma_f32_16x16x32_bf16 v[30:33], v[178:181], v[210:213], v[30:33]
	v_mfma_f32_16x16x32_bf16 v[22:25], v[186:189], v[210:213], v[22:25]
	v_mfma_f32_16x16x32_bf16 v[14:17], v[178:181], v[218:221], v[14:17]
	v_mfma_f32_16x16x32_bf16 v[6:9], v[186:189], v[218:221], v[6:9]
	v_mfma_f32_16x16x32_bf16 v[66:69], v[182:185], v[198:201], v[66:69]
	v_mfma_f32_16x16x32_bf16 v[54:57], v[190:193], v[198:201], v[54:57]
	v_mfma_f32_16x16x32_bf16 v[46:49], v[182:185], v[206:209], v[46:49]
	v_mfma_f32_16x16x32_bf16 v[38:41], v[190:193], v[206:209], v[38:41]
	v_mfma_f32_16x16x32_bf16 v[30:33], v[182:185], v[214:217], v[30:33]
	v_mfma_f32_16x16x32_bf16 v[22:25], v[190:193], v[214:217], v[22:25]
	v_mfma_f32_16x16x32_bf16 v[14:17], v[182:185], v[222:225], v[14:17]
	v_mfma_f32_16x16x32_bf16 v[6:9], v[190:193], v[222:225], v[6:9]
	s_setprio 0
	s_barrier
; #define PG8_STAGE(bufoff, gbase, voff) do { _Pragma("unroll") for (int _i = 0; _i < 2; ++_i) \
;         __builtin_amdgcn_global_load_lds((const unsigned*)((const char*)(gbase) + (voff)[_i]), (PG8_LAS unsigned*)(lds + (bufoff) + ldsw + _i * 8192), 16, 0, 0); } while (0)
; #define PG8_LDA(dst, b, h) do { _Pragma("unroll") for (int m = 0; m < 4; ++m) _Pragma("unroll") for (int k = 0; k < 2; ++k) dst[m][k] = *(const PG8_LAS bf16x8*)(lds + PG8_SA(b, h) + aoff + m * 2048 + k * 1024); } while (0)
; #define PG8_LDB(dst, b, h) do { _Pragma("unroll") for (int n = 0; n < 2; ++n) _Pragma("unroll") for (int k = 0; k < 2; ++k) dst[n][k] = *(const PG8_LAS bf16x8*)(lds + PG8_SB(b, h) + boff + n * 2048 + k * 1024); } while (0)
; #define PG8_MMA(ai, bj, At, Bt) do { __builtin_amdgcn_s_setprio(1); _Pragma("unroll") for (int m = 0; m < 4; ++m) _Pragma("unroll") for (int n = 0; n < 2; ++n) _Pragma("unroll") for (int k = 0; k < 2; ++k) \
;         acc[ai][bj][m][n] = __builtin_amdgcn_mfma_f32_16x16x32_bf16(Bt[n][k], At[m][k], acc[ai][bj][m][n], 0, 0, 0); __builtin_amdgcn_s_setprio(0); } while (0)
; #define PG8_WAIT_V(n) asm volatile("s_waitcnt vmcnt(" #n ")" ::: "memory")
; #define PG8_WAIT_L(n) asm volatile("s_waitcnt lgkmcnt(" #n ")" ::: "memory")
; #define PG8_BAR __builtin_amdgcn_s_barrier()
; #define PG8_SCHED __builtin_amdgcn_sched_barrier(0)
; template <class Epi, class Sched, bool ALIGN_EPI = false, bool SP2 = false>
; __device__ __forceinline__ void gemm_phase(PG8_LAS unsigned char* lds, const Gemm g, const Sched& S, const Epi& E) {
;     ...
;             PG8_LDB(B0, 1, 0); PG8_LDB(B1, 1, 1); PG8_SCHED; PG8_LDA(At, 1, 0); PG8_STAGE(PG8_SA(0, 1), a2 + hstep, voffA);
;             PG8_WAIT_V(8); PG8_WAIT_L(0); PG8_BAR; PG8_MMA(0, 0, At, B0); PG8_MMA(0, 1, At, B1); PG8_BAR; PG8_SCHED;
;             PG8_LDA(At, 1, 1); PG8_STAGE(PG8_SB(1, 0), b3, voffB); PG8_STAGE(PG8_SB(1, 1), b3 + hstep, voffB); PG8_STAGE(PG8_SA(1, 0), a3, voffA);
;             PG8_WAIT_V(8); PG8_WAIT_L(0); PG8_BAR; PG8_MMA(1, 0, At, B0); PG8_MMA(1, 1, At, B1); PG8_BAR; PG8_SCHED;
	s_add_i32 s33, 0, 0x18000
	s_add_i32 s42, 0, 0x1c000
	ds_read_b128 v[160:163], v241 offset:32768
	ds_read_b128 v[166:169], v241 offset:33792
	ds_read_b128 v[170:173], v241 offset:34816
	ds_read_b128 v[174:177], v241 offset:35840
	ds_read_b128 v[178:181], v241 offset:49152
	ds_read_b128 v[182:185], v241 offset:50176
	ds_read_b128 v[186:189], v241 offset:51200
	ds_read_b128 v[190:193], v241 offset:52224
	s_add_u32 s26, s26, 0x100000
	s_addc_u32 s27, s27, 0
	s_mov_b32 m0, s37
	ds_read_b128 v[194:197], v155 offset:32768
	ds_read_b128 v[198:201], v155 offset:33792
	ds_read_b128 v[202:205], v155 offset:34816
	ds_read_b128 v[206:209], v155 offset:35840
	ds_read_b128 v[210:213], v155 offset:36864
	ds_read_b128 v[214:217], v155 offset:37888
	ds_read_b128 v[218:221], v155 offset:38912
	ds_read_b128 v[222:225], v155 offset:39936
	global_load_lds_dwordx4 v130, s[26:27]
	s_mov_b32 m0, s40
	s_nop 0
	global_load_lds_dwordx4 v134, s[26:27]
	s_waitcnt vmcnt(8)
	s_waitcnt lgkmcnt(0)
	s_barrier
	s_setprio 1
	v_mfma_f32_16x16x32_bf16 v[122:125], v[160:163], v[194:197], v[122:125]
	v_mfma_f32_16x16x32_bf16 v[114:117], v[170:173], v[194:197], v[114:117]
	v_mfma_f32_16x16x32_bf16 v[106:109], v[160:163], v[202:205], v[106:109]
	v_mfma_f32_16x16x32_bf16 v[98:101], v[170:173], v[202:205], v[98:101]
	v_mfma_f32_16x16x32_bf16 v[90:93], v[160:163], v[210:213], v[90:93]
	v_mfma_f32_16x16x32_bf16 v[82:85], v[170:173], v[210:213], v[82:85]
	v_mfma_f32_16x16x32_bf16 v[74:77], v[160:163], v[218:221], v[74:77]
	v_mfma_f32_16x16x32_bf16 v[62:65], v[170:173], v[218:221], v[62:65]
	v_mfma_f32_16x16x32_bf16 v[122:125], v[166:169], v[198:201], v[122:125]
	v_mfma_f32_16x16x32_bf16 v[114:117], v[174:177], v[198:201], v[114:117]
	v_mfma_f32_16x16x32_bf16 v[106:109], v[166:169], v[206:209], v[106:109]
	v_mfma_f32_16x16x32_bf16 v[98:101], v[174:177], v[206:209], v[98:101]
	v_mfma_f32_16x16x32_bf16 v[90:93], v[166:169], v[214:217], v[90:93]
	v_mfma_f32_16x16x32_bf16 v[82:85], v[174:177], v[214:217], v[82:85]
	v_mfma_f32_16x16x32_bf16 v[74:77], v[166:169], v[222:225], v[74:77]
	v_mfma_f32_16x16x32_bf16 v[62:65], v[174:177], v[222:225], v[62:65]
	v_mfma_f32_16x16x32_bf16 v[126:129], v[178:181], v[194:197], v[126:129]
	v_mfma_f32_16x16x32_bf16 v[118:121], v[186:189], v[194:197], v[118:121]
	v_mfma_f32_16x16x32_bf16 v[110:113], v[178:181], v[202:205], v[110:113]
	v_mfma_f32_16x16x32_bf16 v[102:105], v[186:189], v[202:205], v[102:105]
	v_mfma_f32_16x16x32_bf16 v[94:97], v[178:181], v[210:213], v[94:97]
	v_mfma_f32_16x16x32_bf16 v[86:89], v[186:189], v[210:213], v[86:89]
	v_mfma_f32_16x16x32_bf16 v[78:81], v[178:181], v[218:221], v[78:81]
	v_mfma_f32_16x16x32_bf16 v[70:73], v[186:189], v[218:221], v[70:73]
	v_mfma_f32_16x16x32_bf16 v[126:129], v[182:185], v[198:201], v[126:129]
	v_mfma_f32_16x16x32_bf16 v[118:121], v[190:193], v[198:201], v[118:121]
	v_mfma_f32_16x16x32_bf16 v[110:113], v[182:185], v[206:209], v[110:113]
	v_mfma_f32_16x16x32_bf16 v[102:105], v[190:193], v[206:209], v[102:105]
	v_mfma_f32_16x16x32_bf16 v[94:97], v[182:185], v[214:217], v[94:97]
	v_mfma_f32_16x16x32_bf16 v[86:89], v[190:193], v[214:217], v[86:89]
	v_mfma_f32_16x16x32_bf16 v[78:81], v[182:185], v[222:225], v[78:81]
	v_mfma_f32_16x16x32_bf16 v[70:73], v[190:193], v[222:225], v[70:73]
	s_setprio 0
	s_barrier
	s_add_i32 s26, s33, s29
	s_add_i32 m0, s26, 0xffffff80
	ds_read_b128 v[194:197], v155 offset:49152
	ds_read_b128 v[198:201], v155 offset:50176
	ds_read_b128 v[202:205], v155 offset:51200
	ds_read_b128 v[206:209], v155 offset:52224
	ds_read_b128 v[210:213], v155 offset:53248
	ds_read_b128 v[214:217], v155 offset:54272
	ds_read_b128 v[218:221], v155 offset:55296
	ds_read_b128 v[222:225], v155 offset:56320
	global_load_lds_dwordx4 v132, s[22:23] offset:128
	s_add_i32 m0, s26, 0x1f80
	s_add_i32 s26, s42, s29
	global_load_lds_dwordx4 v136, s[22:23] offset:128
	s_add_u32 s22, s22, 0x100080
	s_addc_u32 s23, s23, 0
	s_mov_b32 m0, s26
	s_nop 0
	global_load_lds_dwordx4 v132, s[22:23]
	s_add_i32 m0, s26, 0x2000
	s_nop 0
	global_load_lds_dwordx4 v136, s[22:23]
	s_mov_b32 m0, s46
	s_nop 0
	global_load_lds_dwordx4 v130, s[100:101]
	s_mov_b32 m0, s47
	s_nop 0
	global_load_lds_dwordx4 v134, s[100:101]
	s_waitcnt vmcnt(8)
	s_waitcnt lgkmcnt(0)
	s_barrier
	s_setprio 1
	v_mfma_f32_16x16x32_bf16 v[58:61], v[160:163], v[194:197], v[58:61]
	v_mfma_f32_16x16x32_bf16 v[50:53], v[170:173], v[194:197], v[50:53]
	v_mfma_f32_16x16x32_bf16 v[42:45], v[160:163], v[202:205], v[42:45]
	v_mfma_f32_16x16x32_bf16 v[34:37], v[170:173], v[202:205], v[34:37]
	v_mfma_f32_16x16x32_bf16 v[26:29], v[160:163], v[210:213], v[26:29]
	v_mfma_f32_16x16x32_bf16 v[18:21], v[170:173], v[210:213], v[18:21]
	v_mfma_f32_16x16x32_bf16 v[10:13], v[160:163], v[218:221], v[10:13]
	v_mfma_f32_16x16x32_bf16 v[2:5], v[170:173], v[218:221], v[2:5]
	v_mfma_f32_16x16x32_bf16 v[58:61], v[166:169], v[198:201], v[58:61]
	v_mfma_f32_16x16x32_bf16 v[50:53], v[174:177], v[198:201], v[50:53]
	v_mfma_f32_16x16x32_bf16 v[42:45], v[166:169], v[206:209], v[42:45]
	v_mfma_f32_16x16x32_bf16 v[34:37], v[174:177], v[206:209], v[34:37]
	v_mfma_f32_16x16x32_bf16 v[26:29], v[166:169], v[214:217], v[26:29]
	v_mfma_f32_16x16x32_bf16 v[18:21], v[174:177], v[214:217], v[18:21]
	v_mfma_f32_16x16x32_bf16 v[10:13], v[166:169], v[222:225], v[10:13]
	v_mfma_f32_16x16x32_bf16 v[2:5], v[174:177], v[222:225], v[2:5]
	v_mfma_f32_16x16x32_bf16 v[66:69], v[178:181], v[194:197], v[66:69]
	v_mfma_f32_16x16x32_bf16 v[54:57], v[186:189], v[194:197], v[54:57]
	v_mfma_f32_16x16x32_bf16 v[46:49], v[178:181], v[202:205], v[46:49]
	v_mfma_f32_16x16x32_bf16 v[38:41], v[186:189], v[202:205], v[38:41]
	v_mfma_f32_16x16x32_bf16 v[30:33], v[178:181], v[210:213], v[30:33]
	v_mfma_f32_16x16x32_bf16 v[22:25], v[186:189], v[210:213], v[22:25]
	v_mfma_f32_16x16x32_bf16 v[14:17], v[178:181], v[218:221], v[14:17]
	v_mfma_f32_16x16x32_bf16 v[6:9], v[186:189], v[218:221], v[6:9]
	v_mfma_f32_16x16x32_bf16 v[66:69], v[182:185], v[198:201], v[66:69]
	v_mfma_f32_16x16x32_bf16 v[54:57], v[190:193], v[198:201], v[54:57]
	v_mfma_f32_16x16x32_bf16 v[46:49], v[182:185], v[206:209], v[46:49]
	v_mfma_f32_16x16x32_bf16 v[38:41], v[190:193], v[206:209], v[38:41]
	v_mfma_f32_16x16x32_bf16 v[30:33], v[182:185], v[214:217], v[30:33]
	v_mfma_f32_16x16x32_bf16 v[22:25], v[190:193], v[214:217], v[22:25]
	v_mfma_f32_16x16x32_bf16 v[14:17], v[182:185], v[222:225], v[14:17]
	v_mfma_f32_16x16x32_bf16 v[6:9], v[190:193], v[222:225], v[6:9]
	s_setprio 0
	s_barrier
	s_add_i32 s68, s68, 2
	s_add_u32 s24, s24, 0x100
	s_addc_u32 s25, s25, 0
	s_add_u32 s66, s66, 0x100
	s_addc_u32 s67, s67, 0
	s_cmp_gt_u32 s68, 61
	s_cbranch_scc0 .LBB0_1126
	s_and_b64 vcc, exec, s[8:9]
	s_cbranch_vccz .LBB0_1129
	s_barrier

; #define PG8_STAGE(bufoff, gbase, voff) do { _Pragma("unroll") for (int _i = 0; _i < 2; ++_i) \
;         __builtin_amdgcn_global_load_lds((const unsigned*)((const char*)(gbase) + (voff)[_i]), (PG8_LAS unsigned*)(lds + (bufoff) + ldsw + _i * 8192), 16, 0, 0); } while (0)
; #define PG8_LDA(dst, b, h) do { _Pragma("unroll") for (int m = 0; m < 4; ++m) _Pragma("unroll") for (int k = 0; k < 2; ++k) dst[m][k] = *(const PG8_LAS bf16x8*)(lds + PG8_SA(b, h) + aoff + m * 2048 + k * 1024); } while (0)
; #define PG8_LDB(dst, b, h) do { _Pragma("unroll") for (int n = 0; n < 2; ++n) _Pragma("unroll") for (int k = 0; k < 2; ++k) dst[n][k] = *(const PG8_LAS bf16x8*)(lds + PG8_SB(b, h) + boff + n * 2048 + k * 1024); } while (0)
; #define PG8_MMA(ai, bj, At, Bt) do { __builtin_amdgcn_s_setprio(1); _Pragma("unroll") for (int m = 0; m < 4; ++m) _Pragma("unroll") for (int n = 0; n < 2; ++n) _Pragma("unroll") for (int k = 0; k < 2; ++k) \
;         acc[ai][bj][m][n] = __builtin_amdgcn_mfma_f32_16x16x32_bf16(Bt[n][k], At[m][k], acc[ai][bj][m][n], 0, 0, 0); __builtin_amdgcn_s_setprio(0); } while (0)
; #define PG8_WAIT_V(n) asm volatile("s_waitcnt vmcnt(" #n ")" ::: "memory")
; #define PG8_BAR __builtin_amdgcn_s_barrier()
; template <class Epi, class Sched, bool ALIGN_EPI = false, bool SP2 = false>
; __device__ __forceinline__ void gemm_phase(PG8_LAS unsigned char* lds, const Gemm g, const Sched& S, const Epi& E) {
;     ...
;         for (int t = 0; t < nt; t += 2) {
;             const bool last = (t == nt - 2);
;             const char* a1 = cA + (size_t)(t + 1) * kstep;
;             const char* a2 = last ? nA : cA + (size_t)(t + 2) * kstep; const char* b2 = last ? nB : cB + (size_t)(t + 2) * kstep;
;             const char* a3 = a2 + kstep; const char* b3 = b2 + kstep;
;             if (last && has_next) S.a_ready(nxt);
;             if constexpr (SP2) {
;             PG8_LDB(B0, 0, 0); PG8_LDB(B1, 0, 1); PG8_SCHED; PG8_LDA(At, 0, 0); PG8_STAGE(PG8_SA(1, 1), a1 + hstep, voffA);
;             PG8_WAIT_V(8); PG8_WAIT_L(0); PG8_BAR; PG8_MMA(0, 0, At, B0); PG8_MMA(0, 1, At, B1); PG8_BAR; PG8_SCHED;
;             PG8_LDA(At, 0, 1); PG8_STAGE(PG8_SB(0, 0), b2, voffB); PG8_STAGE(PG8_SB(0, 1), b2 + hstep, voffB); PG8_STAGE(PG8_SA(0, 0), a2, voffA);
;             PG8_WAIT_V(8); PG8_WAIT_L(0); PG8_BAR; PG8_MMA(1, 0, At, B0); PG8_MMA(1, 1, At, B1); PG8_BAR; PG8_SCHED;
.LBB0_1245:
	ds_read_b128 v[130:133], v241 offset:0
	ds_read_b128 v[134:137], v241 offset:1024
	ds_read_b128 v[138:141], v241 offset:2048
	ds_read_b128 v[142:145], v241 offset:3072
	ds_read_b128 v[146:149], v241 offset:16384
	ds_read_b128 v[150:153], v241 offset:17408
	ds_read_b128 v[172:175], v241 offset:18432
	ds_read_b128 v[176:179], v241 offset:19456
	s_add_u32 s16, s18, 0xffd50080
	s_addc_u32 s17, s19, -1
	s_cmpk_eq_i32 s64, 0xa8
	s_cselect_b32 s21, s5, s17
	s_cselect_b32 s20, s4, s16
	s_cselect_b32 s17, s15, s63
	s_cselect_b32 s16, s14, s62
	s_add_i32 m0, s25, 0xc000
	ds_read_b128 v[180:183], v185
	ds_read_b128 v[188:191], v185 offset:1024
	ds_read_b128 v[192:195], v185 offset:2048
	ds_read_b128 v[196:199], v185 offset:3072
	ds_read_b128 v[200:203], v185 offset:4096
	ds_read_b128 v[204:207], v185 offset:5120
	ds_read_b128 v[208:211], v185 offset:6144
	ds_read_b128 v[212:215], v185 offset:7168
	global_load_lds_dwordx4 v162, s[18:19]
	s_add_i32 m0, s25, 0xe000
	s_nop 0
	global_load_lds_dwordx4 v166, s[18:19]
	s_waitcnt vmcnt(8)
	s_waitcnt lgkmcnt(0)
	s_barrier
	s_setprio 1
	v_mfma_f32_16x16x32_bf16 v[114:117], v[130:133], v[180:183], v[114:117]
	v_mfma_f32_16x16x32_bf16 v[118:121], v[138:141], v[180:183], v[118:121]
	v_mfma_f32_16x16x32_bf16 v[106:109], v[130:133], v[192:195], v[106:109]
	v_mfma_f32_16x16x32_bf16 v[98:101], v[138:141], v[192:195], v[98:101]
	v_mfma_f32_16x16x32_bf16 v[90:93], v[130:133], v[200:203], v[90:93]
	v_mfma_f32_16x16x32_bf16 v[82:85], v[138:141], v[200:203], v[82:85]
	v_mfma_f32_16x16x32_bf16 v[74:77], v[130:133], v[208:211], v[74:77]
	v_mfma_f32_16x16x32_bf16 v[66:69], v[138:141], v[208:211], v[66:69]
	v_mfma_f32_16x16x32_bf16 v[114:117], v[134:137], v[188:191], v[114:117]
	v_mfma_f32_16x16x32_bf16 v[118:121], v[142:145], v[188:191], v[118:121]
	v_mfma_f32_16x16x32_bf16 v[106:109], v[134:137], v[196:199], v[106:109]
	v_mfma_f32_16x16x32_bf16 v[98:101], v[142:145], v[196:199], v[98:101]
	v_mfma_f32_16x16x32_bf16 v[90:93], v[134:137], v[204:207], v[90:93]
	v_mfma_f32_16x16x32_bf16 v[82:85], v[142:145], v[204:207], v[82:85]
	v_mfma_f32_16x16x32_bf16 v[74:77], v[134:137], v[212:215], v[74:77]
	v_mfma_f32_16x16x32_bf16 v[66:69], v[142:145], v[212:215], v[66:69]
	v_mfma_f32_16x16x32_bf16 v[122:125], v[146:149], v[180:183], v[122:125]
	v_mfma_f32_16x16x32_bf16 v[126:129], v[172:175], v[180:183], v[126:129]
	v_mfma_f32_16x16x32_bf16 v[110:113], v[146:149], v[192:195], v[110:113]
	v_mfma_f32_16x16x32_bf16 v[102:105], v[172:175], v[192:195], v[102:105]
	v_mfma_f32_16x16x32_bf16 v[94:97], v[146:149], v[200:203], v[94:97]
	v_mfma_f32_16x16x32_bf16 v[86:89], v[172:175], v[200:203], v[86:89]
	v_mfma_f32_16x16x32_bf16 v[78:81], v[146:149], v[208:211], v[78:81]
	v_mfma_f32_16x16x32_bf16 v[70:73], v[172:175], v[208:211], v[70:73]
	v_mfma_f32_16x16x32_bf16 v[122:125], v[150:153], v[188:191], v[122:125]
	v_mfma_f32_16x16x32_bf16 v[126:129], v[176:179], v[188:191], v[126:129]
	v_mfma_f32_16x16x32_bf16 v[110:113], v[150:153], v[196:199], v[110:113]
	v_mfma_f32_16x16x32_bf16 v[102:105], v[176:179], v[196:199], v[102:105]
	v_mfma_f32_16x16x32_bf16 v[94:97], v[150:153], v[204:207], v[94:97]
	v_mfma_f32_16x16x32_bf16 v[86:89], v[176:179], v[204:207], v[86:89]
	v_mfma_f32_16x16x32_bf16 v[78:81], v[150:153], v[212:215], v[78:81]
	v_mfma_f32_16x16x32_bf16 v[70:73], v[176:179], v[212:215], v[70:73]
	s_setprio 0
	s_barrier
	s_add_i32 s33, s40, s24
	s_mov_b32 m0, s33
	ds_read_b128 v[180:183], v185 offset:16384
	ds_read_b128 v[188:191], v185 offset:17408
	ds_read_b128 v[192:195], v185 offset:18432
	ds_read_b128 v[196:199], v185 offset:19456
	ds_read_b128 v[200:203], v185 offset:20480
	ds_read_b128 v[204:207], v185 offset:21504
	ds_read_b128 v[208:211], v185 offset:22528
	ds_read_b128 v[212:215], v185 offset:23552
	global_load_lds_dwordx4 v156, s[16:17]
	s_add_i32 m0, s33, 0x2000
	s_add_u32 s66, s16, 0x2b0000
	s_addc_u32 s67, s17, 0
	s_add_i32 s33, s41, s24
	global_load_lds_dwordx4 v160, s[16:17]
	s_mov_b32 m0, s33
	s_add_u32 s100, s20, 0x80
	s_addc_u32 s101, s21, 0
	global_load_lds_dwordx4 v156, s[66:67]
	s_add_i32 m0, s33, 0x2000
	s_nop 0
	global_load_lds_dwordx4 v160, s[66:67]
	s_mov_b32 m0, s25
	s_nop 0
	global_load_lds_dwordx4 v154, s[20:21]
	s_mov_b32 m0, s26
	s_nop 0
	global_load_lds_dwordx4 v158, s[20:21]
	s_waitcnt vmcnt(8)
	s_waitcnt lgkmcnt(0)
	s_barrier
	s_setprio 1
	v_mfma_f32_16x16x32_bf16 v[58:61], v[130:133], v[180:183], v[58:61]
	v_mfma_f32_16x16x32_bf16 v[54:57], v[138:141], v[180:183], v[54:57]
	v_mfma_f32_16x16x32_bf16 v[42:45], v[130:133], v[192:195], v[42:45]
	v_mfma_f32_16x16x32_bf16 v[34:37], v[138:141], v[192:195], v[34:37]
	v_mfma_f32_16x16x32_bf16 v[26:29], v[130:133], v[200:203], v[26:29]
	v_mfma_f32_16x16x32_bf16 v[18:21], v[138:141], v[200:203], v[18:21]
	v_mfma_f32_16x16x32_bf16 v[6:9], v[130:133], v[208:211], v[6:9]
	v_mfma_f32_16x16x32_bf16 v[2:5], v[138:141], v[208:211], v[2:5]
	v_mfma_f32_16x16x32_bf16 v[58:61], v[134:137], v[188:191], v[58:61]
	v_mfma_f32_16x16x32_bf16 v[54:57], v[142:145], v[188:191], v[54:57]
	v_mfma_f32_16x16x32_bf16 v[42:45], v[134:137], v[196:199], v[42:45]
	v_mfma_f32_16x16x32_bf16 v[34:37], v[142:145], v[196:199], v[34:37]
	v_mfma_f32_16x16x32_bf16 v[26:29], v[134:137], v[204:207], v[26:29]
	v_mfma_f32_16x16x32_bf16 v[18:21], v[142:145], v[204:207], v[18:21]
	v_mfma_f32_16x16x32_bf16 v[6:9], v[134:137], v[212:215], v[6:9]
	v_mfma_f32_16x16x32_bf16 v[2:5], v[142:145], v[212:215], v[2:5]
	v_mfma_f32_16x16x32_bf16 v[62:65], v[146:149], v[180:183], v[62:65]
	v_mfma_f32_16x16x32_bf16 v[50:53], v[172:175], v[180:183], v[50:53]
	v_mfma_f32_16x16x32_bf16 v[46:49], v[146:149], v[192:195], v[46:49]
	v_mfma_f32_16x16x32_bf16 v[38:41], v[172:175], v[192:195], v[38:41]
	v_mfma_f32_16x16x32_bf16 v[30:33], v[146:149], v[200:203], v[30:33]
	v_mfma_f32_16x16x32_bf16 v[22:25], v[172:175], v[200:203], v[22:25]
	v_mfma_f32_16x16x32_bf16 v[10:13], v[146:149], v[208:211], v[10:13]
	v_mfma_f32_16x16x32_bf16 v[14:17], v[172:175], v[208:211], v[14:17]
	v_mfma_f32_16x16x32_bf16 v[62:65], v[150:153], v[188:191], v[62:65]
	v_mfma_f32_16x16x32_bf16 v[50:53], v[176:179], v[188:191], v[50:53]
	v_mfma_f32_16x16x32_bf16 v[46:49], v[150:153], v[196:199], v[46:49]
	v_mfma_f32_16x16x32_bf16 v[38:41], v[176:179], v[196:199], v[38:41]
	v_mfma_f32_16x16x32_bf16 v[30:33], v[150:153], v[204:207], v[30:33]
	v_mfma_f32_16x16x32_bf16 v[22:25], v[176:179], v[204:207], v[22:25]
	v_mfma_f32_16x16x32_bf16 v[10:13], v[150:153], v[212:215], v[10:13]
	v_mfma_f32_16x16x32_bf16 v[14:17], v[176:179], v[212:215], v[14:17]
	s_setprio 0
	s_barrier
; #define PG8_STAGE(bufoff, gbase, voff) do { _Pragma("unroll") for (int _i = 0; _i < 2; ++_i) \
;         __builtin_amdgcn_global_load_lds((const unsigned*)((const char*)(gbase) + (voff)[_i]), (PG8_LAS unsigned*)(lds + (bufoff) + ldsw + _i * 8192), 16, 0, 0); } while (0)
; #define PG8_LDA(dst, b, h) do { _Pragma("unroll") for (int m = 0; m < 4; ++m) _Pragma("unroll") for (int k = 0; k < 2; ++k) dst[m][k] = *(const PG8_LAS bf16x8*)(lds + PG8_SA(b, h) + aoff + m * 2048 + k * 1024); } while (0)
; #define PG8_LDB(dst, b, h) do { _Pragma("unroll") for (int n = 0; n < 2; ++n) _Pragma("unroll") for (int k = 0; k < 2; ++k) dst[n][k] = *(const PG8_LAS bf16x8*)(lds + PG8_SB(b, h) + boff + n * 2048 + k * 1024); } while (0)
; #define PG8_MMA(ai, bj, At, Bt) do { __builtin_amdgcn_s_setprio(1); _Pragma("unroll") for (int m = 0; m < 4; ++m) _Pragma("unroll") for (int n = 0; n < 2; ++n) _Pragma("unroll") for (int k = 0; k < 2; ++k) \
;         acc[ai][bj][m][n] = __builtin_amdgcn_mfma_f32_16x16x32_bf16(Bt[n][k], At[m][k], acc[ai][bj][m][n], 0, 0, 0); __builtin_amdgcn_s_setprio(0); } while (0)
; #define PG8_WAIT_V(n) asm volatile("s_waitcnt vmcnt(" #n ")" ::: "memory")
; #define PG8_WAIT_L(n) asm volatile("s_waitcnt lgkmcnt(" #n ")" ::: "memory")
; #define PG8_BAR __builtin_amdgcn_s_barrier()
; #define PG8_SCHED __builtin_amdgcn_sched_barrier(0)
; template <class Epi, class Sched, bool ALIGN_EPI = false, bool SP2 = false>
; __device__ __forceinline__ void gemm_phase(PG8_LAS unsigned char* lds, const Gemm g, const Sched& S, const Epi& E) {
;     ...
;             PG8_LDB(B0, 1, 0); PG8_LDB(B1, 1, 1); PG8_SCHED; PG8_LDA(At, 1, 0); PG8_STAGE(PG8_SA(0, 1), a2 + hstep, voffA);
;             PG8_WAIT_V(8); PG8_WAIT_L(0); PG8_BAR; PG8_MMA(0, 0, At, B0); PG8_MMA(0, 1, At, B1); PG8_BAR; PG8_SCHED;
;             PG8_LDA(At, 1, 1); PG8_STAGE(PG8_SB(1, 0), b3, voffB); PG8_STAGE(PG8_SB(1, 1), b3 + hstep, voffB); PG8_STAGE(PG8_SA(1, 0), a3, voffA);
;             PG8_WAIT_V(8); PG8_WAIT_L(0); PG8_BAR; PG8_MMA(1, 0, At, B0); PG8_MMA(1, 1, At, B1); PG8_BAR; PG8_SCHED;
	s_add_i32 s33, 0, 0x18000
	s_add_i32 s42, 0, 0x1c000
	ds_read_b128 v[130:133], v241 offset:32768
	ds_read_b128 v[134:137], v241 offset:33792
	ds_read_b128 v[138:141], v241 offset:34816
	ds_read_b128 v[142:145], v241 offset:35840
	ds_read_b128 v[146:149], v241 offset:49152
	ds_read_b128 v[150:153], v241 offset:50176
	ds_read_b128 v[172:175], v241 offset:51200
	ds_read_b128 v[176:179], v241 offset:52224
	s_add_u32 s20, s20, 0x2b0000
	s_addc_u32 s21, s21, 0
	s_mov_b32 m0, s27
	ds_read_b128 v[180:183], v185 offset:32768
	ds_read_b128 v[188:191], v185 offset:33792
	ds_read_b128 v[192:195], v185 offset:34816
	ds_read_b128 v[196:199], v185 offset:35840
	ds_read_b128 v[200:203], v185 offset:36864
	ds_read_b128 v[204:207], v185 offset:37888
	ds_read_b128 v[208:211], v185 offset:38912
	ds_read_b128 v[212:215], v185 offset:39936
	global_load_lds_dwordx4 v154, s[20:21]
	s_mov_b32 m0, s28
	s_nop 0
	global_load_lds_dwordx4 v158, s[20:21]
	s_waitcnt vmcnt(8)
	s_waitcnt lgkmcnt(0)
	s_barrier
	s_setprio 1
	v_mfma_f32_16x16x32_bf16 v[114:117], v[130:133], v[180:183], v[114:117]
	v_mfma_f32_16x16x32_bf16 v[118:121], v[138:141], v[180:183], v[118:121]
	v_mfma_f32_16x16x32_bf16 v[106:109], v[130:133], v[192:195], v[106:109]
	v_mfma_f32_16x16x32_bf16 v[98:101], v[138:141], v[192:195], v[98:101]
	v_mfma_f32_16x16x32_bf16 v[90:93], v[130:133], v[200:203], v[90:93]
	v_mfma_f32_16x16x32_bf16 v[82:85], v[138:141], v[200:203], v[82:85]
	v_mfma_f32_16x16x32_bf16 v[74:77], v[130:133], v[208:211], v[74:77]
	v_mfma_f32_16x16x32_bf16 v[66:69], v[138:141], v[208:211], v[66:69]
	v_mfma_f32_16x16x32_bf16 v[114:117], v[134:137], v[188:191], v[114:117]
	v_mfma_f32_16x16x32_bf16 v[118:121], v[142:145], v[188:191], v[118:121]
	v_mfma_f32_16x16x32_bf16 v[106:109], v[134:137], v[196:199], v[106:109]
	v_mfma_f32_16x16x32_bf16 v[98:101], v[142:145], v[196:199], v[98:101]
	v_mfma_f32_16x16x32_bf16 v[90:93], v[134:137], v[204:207], v[90:93]
	v_mfma_f32_16x16x32_bf16 v[82:85], v[142:145], v[204:207], v[82:85]
	v_mfma_f32_16x16x32_bf16 v[74:77], v[134:137], v[212:215], v[74:77]
	v_mfma_f32_16x16x32_bf16 v[66:69], v[142:145], v[212:215], v[66:69]
	v_mfma_f32_16x16x32_bf16 v[122:125], v[146:149], v[180:183], v[122:125]
	v_mfma_f32_16x16x32_bf16 v[126:129], v[172:175], v[180:183], v[126:129]
	v_mfma_f32_16x16x32_bf16 v[110:113], v[146:149], v[192:195], v[110:113]
	v_mfma_f32_16x16x32_bf16 v[102:105], v[172:175], v[192:195], v[102:105]
	v_mfma_f32_16x16x32_bf16 v[94:97], v[146:149], v[200:203], v[94:97]
	v_mfma_f32_16x16x32_bf16 v[86:89], v[172:175], v[200:203], v[86:89]
	v_mfma_f32_16x16x32_bf16 v[78:81], v[146:149], v[208:211], v[78:81]
	v_mfma_f32_16x16x32_bf16 v[70:73], v[172:175], v[208:211], v[70:73]
	v_mfma_f32_16x16x32_bf16 v[122:125], v[150:153], v[188:191], v[122:125]
	v_mfma_f32_16x16x32_bf16 v[126:129], v[176:179], v[188:191], v[126:129]
	v_mfma_f32_16x16x32_bf16 v[110:113], v[150:153], v[196:199], v[110:113]
	v_mfma_f32_16x16x32_bf16 v[102:105], v[176:179], v[196:199], v[102:105]
	v_mfma_f32_16x16x32_bf16 v[94:97], v[150:153], v[204:207], v[94:97]
	v_mfma_f32_16x16x32_bf16 v[86:89], v[176:179], v[204:207], v[86:89]
	v_mfma_f32_16x16x32_bf16 v[78:81], v[150:153], v[212:215], v[78:81]
	v_mfma_f32_16x16x32_bf16 v[70:73], v[176:179], v[212:215], v[70:73]
	s_setprio 0
	s_barrier
	s_add_i32 s20, s33, s24
	s_add_i32 m0, s20, 0xffffff80
	ds_read_b128 v[180:183], v185 offset:49152
	ds_read_b128 v[188:191], v185 offset:50176
	ds_read_b128 v[192:195], v185 offset:51200
	ds_read_b128 v[196:199], v185 offset:52224
	ds_read_b128 v[200:203], v185 offset:53248
	ds_read_b128 v[204:207], v185 offset:54272
	ds_read_b128 v[208:211], v185 offset:55296
	ds_read_b128 v[212:215], v185 offset:56320
	global_load_lds_dwordx4 v156, s[16:17] offset:128
	s_add_i32 m0, s20, 0x1f80
	s_add_i32 s20, s42, s24
	global_load_lds_dwordx4 v160, s[16:17] offset:128
	s_add_u32 s16, s16, 0x2b0080
	s_addc_u32 s17, s17, 0
	s_mov_b32 m0, s20
	s_nop 0
	global_load_lds_dwordx4 v156, s[16:17]
	s_add_i32 m0, s20, 0x2000
	s_nop 0
	global_load_lds_dwordx4 v160, s[16:17]
	s_mov_b32 m0, s34
	s_nop 0
	global_load_lds_dwordx4 v154, s[100:101]
	s_mov_b32 m0, s35
	s_nop 0
	global_load_lds_dwordx4 v158, s[100:101]
	s_waitcnt vmcnt(8)
	s_waitcnt lgkmcnt(0)
	s_barrier
	s_setprio 1
	v_mfma_f32_16x16x32_bf16 v[58:61], v[130:133], v[180:183], v[58:61]
	v_mfma_f32_16x16x32_bf16 v[54:57], v[138:141], v[180:183], v[54:57]
	v_mfma_f32_16x16x32_bf16 v[42:45], v[130:133], v[192:195], v[42:45]
	v_mfma_f32_16x16x32_bf16 v[34:37], v[138:141], v[192:195], v[34:37]
	v_mfma_f32_16x16x32_bf16 v[26:29], v[130:133], v[200:203], v[26:29]
	v_mfma_f32_16x16x32_bf16 v[18:21], v[138:141], v[200:203], v[18:21]
	v_mfma_f32_16x16x32_bf16 v[6:9], v[130:133], v[208:211], v[6:9]
	v_mfma_f32_16x16x32_bf16 v[2:5], v[138:141], v[208:211], v[2:5]
	v_mfma_f32_16x16x32_bf16 v[58:61], v[134:137], v[188:191], v[58:61]
	v_mfma_f32_16x16x32_bf16 v[54:57], v[142:145], v[188:191], v[54:57]
	v_mfma_f32_16x16x32_bf16 v[42:45], v[134:137], v[196:199], v[42:45]
	v_mfma_f32_16x16x32_bf16 v[34:37], v[142:145], v[196:199], v[34:37]
	v_mfma_f32_16x16x32_bf16 v[26:29], v[134:137], v[204:207], v[26:29]
	v_mfma_f32_16x16x32_bf16 v[18:21], v[142:145], v[204:207], v[18:21]
	v_mfma_f32_16x16x32_bf16 v[6:9], v[134:137], v[212:215], v[6:9]
	v_mfma_f32_16x16x32_bf16 v[2:5], v[142:145], v[212:215], v[2:5]
	v_mfma_f32_16x16x32_bf16 v[62:65], v[146:149], v[180:183], v[62:65]
	v_mfma_f32_16x16x32_bf16 v[50:53], v[172:175], v[180:183], v[50:53]
	v_mfma_f32_16x16x32_bf16 v[46:49], v[146:149], v[192:195], v[46:49]
	v_mfma_f32_16x16x32_bf16 v[38:41], v[172:175], v[192:195], v[38:41]
	v_mfma_f32_16x16x32_bf16 v[30:33], v[146:149], v[200:203], v[30:33]
	v_mfma_f32_16x16x32_bf16 v[22:25], v[172:175], v[200:203], v[22:25]
	v_mfma_f32_16x16x32_bf16 v[10:13], v[146:149], v[208:211], v[10:13]
	v_mfma_f32_16x16x32_bf16 v[14:17], v[172:175], v[208:211], v[14:17]
	v_mfma_f32_16x16x32_bf16 v[62:65], v[150:153], v[188:191], v[62:65]
	v_mfma_f32_16x16x32_bf16 v[50:53], v[176:179], v[188:191], v[50:53]
	v_mfma_f32_16x16x32_bf16 v[46:49], v[150:153], v[196:199], v[46:49]
	v_mfma_f32_16x16x32_bf16 v[38:41], v[176:179], v[196:199], v[38:41]
	v_mfma_f32_16x16x32_bf16 v[30:33], v[150:153], v[204:207], v[30:33]
	v_mfma_f32_16x16x32_bf16 v[22:25], v[176:179], v[204:207], v[22:25]
	v_mfma_f32_16x16x32_bf16 v[10:13], v[150:153], v[212:215], v[10:13]
	v_mfma_f32_16x16x32_bf16 v[14:17], v[176:179], v[212:215], v[14:17]
	s_setprio 0
	s_barrier
	s_add_i32 s64, s64, 2
	s_add_u32 s18, s18, 0x100
	s_addc_u32 s19, s19, 0
	s_add_u32 s62, s62, 0x100
	s_addc_u32 s63, s63, 0
	s_cmpk_gt_u32 s64, 0xa9
	s_cbranch_scc0 .LBB0_1245
	s_and_b64 vcc, exec, s[12:13]
	s_cbranch_vccz .LBB0_1248
	s_barrier

; #define PG8_STAGE(bufoff, gbase, voff) do { _Pragma("unroll") for (int _i = 0; _i < 2; ++_i) \
;         __builtin_amdgcn_global_load_lds((const unsigned*)((const char*)(gbase) + (voff)[_i]), (PG8_LAS unsigned*)(lds + (bufoff) + ldsw + _i * 8192), 16, 0, 0); } while (0)
; #define PG8_LDA(dst, b, h) do { _Pragma("unroll") for (int m = 0; m < 4; ++m) _Pragma("unroll") for (int k = 0; k < 2; ++k) dst[m][k] = *(const PG8_LAS bf16x8*)(lds + PG8_SA(b, h) + aoff + m * 2048 + k * 1024); } while (0)
; #define PG8_LDB(dst, b, h) do { _Pragma("unroll") for (int n = 0; n < 2; ++n) _Pragma("unroll") for (int k = 0; k < 2; ++k) dst[n][k] = *(const PG8_LAS bf16x8*)(lds + PG8_SB(b, h) + boff + n * 2048 + k * 1024); } while (0)
; #define PG8_MMA(ai, bj, At, Bt) do { __builtin_amdgcn_s_setprio(1); _Pragma("unroll") for (int m = 0; m < 4; ++m) _Pragma("unroll") for (int n = 0; n < 2; ++n) _Pragma("unroll") for (int k = 0; k < 2; ++k) \
;         acc[ai][bj][m][n] = __builtin_amdgcn_mfma_f32_16x16x32_bf16(Bt[n][k], At[m][k], acc[ai][bj][m][n], 0, 0, 0); __builtin_amdgcn_s_setprio(0); } while (0)
; #define PG8_WAIT_V(n) asm volatile("s_waitcnt vmcnt(" #n ")" ::: "memory")
; #define PG8_BAR __builtin_amdgcn_s_barrier()
; template <class Epi, class Sched, bool ALIGN_EPI = false, bool SP2 = false>
; __device__ __forceinline__ void gemm_phase(PG8_LAS unsigned char* lds, const Gemm g, const Sched& S, const Epi& E) {
;     ...
;         for (int t = 0; t < nt; t += 2) {
;             const bool last = (t == nt - 2);
;             const char* a1 = cA + (size_t)(t + 1) * kstep;
;             const char* a2 = last ? nA : cA + (size_t)(t + 2) * kstep; const char* b2 = last ? nB : cB + (size_t)(t + 2) * kstep;
;             const char* a3 = a2 + kstep; const char* b3 = b2 + kstep;
;             if (last && has_next) S.a_ready(nxt);
;             if constexpr (SP2) {
;             PG8_LDB(B0, 0, 0); PG8_LDB(B1, 0, 1); PG8_SCHED; PG8_LDA(At, 0, 0); PG8_STAGE(PG8_SA(1, 1), a1 + hstep, voffA);
;             PG8_WAIT_V(8); PG8_WAIT_L(0); PG8_BAR; PG8_MMA(0, 0, At, B0); PG8_MMA(0, 1, At, B1); PG8_BAR; PG8_SCHED;
;             PG8_LDA(At, 0, 1); PG8_STAGE(PG8_SB(0, 0), b2, voffB); PG8_STAGE(PG8_SB(0, 1), b2 + hstep, voffB); PG8_STAGE(PG8_SA(0, 0), a2, voffA);
;             PG8_WAIT_V(8); PG8_WAIT_L(0); PG8_BAR; PG8_MMA(1, 0, At, B0); PG8_MMA(1, 1, At, B1); PG8_BAR; PG8_SCHED;
.LBB0_1332:
	ds_read_b128 v[148:151], v241 offset:0
	ds_read_b128 v[156:159], v241 offset:1024
	ds_read_b128 v[166:169], v241 offset:2048
	ds_read_b128 v[170:173], v241 offset:3072
	ds_read_b128 v[174:177], v241 offset:16384
	ds_read_b128 v[178:181], v241 offset:17408
	ds_read_b128 v[182:185], v241 offset:18432
	ds_read_b128 v[186:189], v241 offset:19456
	s_add_u32 s20, s22, 0xfff00080
	s_addc_u32 s21, s23, -1
	s_cmp_eq_u32 s67, 60
	s_cselect_b32 s25, s13, s21
	s_cselect_b32 s24, s63, s20
	s_cselect_b32 s21, s11, s66
	s_cselect_b32 s20, s64, s65
	s_add_i32 m0, s19, 0xc000
	ds_read_b128 v[190:193], v155
	ds_read_b128 v[194:197], v155 offset:1024
	ds_read_b128 v[198:201], v155 offset:2048
	ds_read_b128 v[202:205], v155 offset:3072
	ds_read_b128 v[206:209], v155 offset:4096
	ds_read_b128 v[210:213], v155 offset:5120
	ds_read_b128 v[214:217], v155 offset:6144
	ds_read_b128 v[218:221], v155 offset:7168
	global_load_lds_dwordx4 v138, s[22:23]
	s_add_i32 m0, s19, 0xe000
	s_nop 0
	global_load_lds_dwordx4 v140, s[22:23]
	s_waitcnt vmcnt(8)
	s_waitcnt lgkmcnt(0)
	s_barrier
	s_setprio 1
	v_mfma_f32_16x16x32_bf16 v[118:121], v[148:151], v[190:193], v[118:121]
	v_mfma_f32_16x16x32_bf16 v[114:117], v[166:169], v[190:193], v[114:117]
	v_mfma_f32_16x16x32_bf16 v[102:105], v[148:151], v[198:201], v[102:105]
	v_mfma_f32_16x16x32_bf16 v[98:101], v[166:169], v[198:201], v[98:101]
	v_mfma_f32_16x16x32_bf16 v[86:89], v[148:151], v[206:209], v[86:89]
	v_mfma_f32_16x16x32_bf16 v[82:85], v[166:169], v[206:209], v[82:85]
	v_mfma_f32_16x16x32_bf16 v[70:73], v[148:151], v[214:217], v[70:73]
	v_mfma_f32_16x16x32_bf16 v[66:69], v[166:169], v[214:217], v[66:69]
	v_mfma_f32_16x16x32_bf16 v[118:121], v[156:159], v[194:197], v[118:121]
	v_mfma_f32_16x16x32_bf16 v[114:117], v[170:173], v[194:197], v[114:117]
	v_mfma_f32_16x16x32_bf16 v[102:105], v[156:159], v[202:205], v[102:105]
	v_mfma_f32_16x16x32_bf16 v[98:101], v[170:173], v[202:205], v[98:101]
	v_mfma_f32_16x16x32_bf16 v[86:89], v[156:159], v[210:213], v[86:89]
	v_mfma_f32_16x16x32_bf16 v[82:85], v[170:173], v[210:213], v[82:85]
	v_mfma_f32_16x16x32_bf16 v[70:73], v[156:159], v[218:221], v[70:73]
	v_mfma_f32_16x16x32_bf16 v[66:69], v[170:173], v[218:221], v[66:69]
	v_mfma_f32_16x16x32_bf16 v[126:129], v[174:177], v[190:193], v[126:129]
	v_mfma_f32_16x16x32_bf16 v[122:125], v[182:185], v[190:193], v[122:125]
	v_mfma_f32_16x16x32_bf16 v[110:113], v[174:177], v[198:201], v[110:113]
	v_mfma_f32_16x16x32_bf16 v[106:109], v[182:185], v[198:201], v[106:109]
	v_mfma_f32_16x16x32_bf16 v[94:97], v[174:177], v[206:209], v[94:97]
	v_mfma_f32_16x16x32_bf16 v[90:93], v[182:185], v[206:209], v[90:93]
	v_mfma_f32_16x16x32_bf16 v[78:81], v[174:177], v[214:217], v[78:81]
	v_mfma_f32_16x16x32_bf16 v[74:77], v[182:185], v[214:217], v[74:77]
	v_mfma_f32_16x16x32_bf16 v[126:129], v[178:181], v[194:197], v[126:129]
	v_mfma_f32_16x16x32_bf16 v[122:125], v[186:189], v[194:197], v[122:125]
	v_mfma_f32_16x16x32_bf16 v[110:113], v[178:181], v[202:205], v[110:113]
	v_mfma_f32_16x16x32_bf16 v[106:109], v[186:189], v[202:205], v[106:109]
	v_mfma_f32_16x16x32_bf16 v[94:97], v[178:181], v[210:213], v[94:97]
	v_mfma_f32_16x16x32_bf16 v[90:93], v[186:189], v[210:213], v[90:93]
	v_mfma_f32_16x16x32_bf16 v[78:81], v[178:181], v[218:221], v[78:81]
	v_mfma_f32_16x16x32_bf16 v[74:77], v[186:189], v[218:221], v[74:77]
	s_setprio 0
	s_barrier
	s_add_i32 s33, s47, s28
	s_mov_b32 m0, s33
	ds_read_b128 v[190:193], v155 offset:16384
	ds_read_b128 v[194:197], v155 offset:17408
	ds_read_b128 v[198:201], v155 offset:18432
	ds_read_b128 v[202:205], v155 offset:19456
	ds_read_b128 v[206:209], v155 offset:20480
	ds_read_b128 v[210:213], v155 offset:21504
	ds_read_b128 v[214:217], v155 offset:22528
	ds_read_b128 v[218:221], v155 offset:23552
	global_load_lds_dwordx4 v132, s[20:21]
	s_add_i32 m0, s33, 0x2000
	s_add_u32 s68, s20, 0x100000
	s_addc_u32 s69, s21, 0
	s_add_i32 s33, s52, s28
	global_load_lds_dwordx4 v136, s[20:21]
	s_mov_b32 m0, s33
	s_add_u32 s100, s24, 0x80
	s_addc_u32 s101, s25, 0
	global_load_lds_dwordx4 v132, s[68:69]
	s_add_i32 m0, s33, 0x2000
	s_nop 0
	global_load_lds_dwordx4 v136, s[68:69]
	s_mov_b32 m0, s19
	s_nop 0
	global_load_lds_dwordx4 v130, s[24:25]
	s_mov_b32 m0, s35
	s_nop 0
	global_load_lds_dwordx4 v134, s[24:25]
	s_waitcnt vmcnt(8)
	s_waitcnt lgkmcnt(0)
	s_barrier
	s_setprio 1
	v_mfma_f32_16x16x32_bf16 v[54:57], v[148:151], v[190:193], v[54:57]
	v_mfma_f32_16x16x32_bf16 v[50:53], v[166:169], v[190:193], v[50:53]
	v_mfma_f32_16x16x32_bf16 v[38:41], v[148:151], v[198:201], v[38:41]
	v_mfma_f32_16x16x32_bf16 v[34:37], v[166:169], v[198:201], v[34:37]
	v_mfma_f32_16x16x32_bf16 v[22:25], v[148:151], v[206:209], v[22:25]
	v_mfma_f32_16x16x32_bf16 v[18:21], v[166:169], v[206:209], v[18:21]
	v_mfma_f32_16x16x32_bf16 v[6:9], v[148:151], v[214:217], v[6:9]
	v_mfma_f32_16x16x32_bf16 v[2:5], v[166:169], v[214:217], v[2:5]
	v_mfma_f32_16x16x32_bf16 v[54:57], v[156:159], v[194:197], v[54:57]
	v_mfma_f32_16x16x32_bf16 v[50:53], v[170:173], v[194:197], v[50:53]
	v_mfma_f32_16x16x32_bf16 v[38:41], v[156:159], v[202:205], v[38:41]
	v_mfma_f32_16x16x32_bf16 v[34:37], v[170:173], v[202:205], v[34:37]
	v_mfma_f32_16x16x32_bf16 v[22:25], v[156:159], v[210:213], v[22:25]
	v_mfma_f32_16x16x32_bf16 v[18:21], v[170:173], v[210:213], v[18:21]
	v_mfma_f32_16x16x32_bf16 v[6:9], v[156:159], v[218:221], v[6:9]
	v_mfma_f32_16x16x32_bf16 v[2:5], v[170:173], v[218:221], v[2:5]
	v_mfma_f32_16x16x32_bf16 v[62:65], v[174:177], v[190:193], v[62:65]
	v_mfma_f32_16x16x32_bf16 v[58:61], v[182:185], v[190:193], v[58:61]
	v_mfma_f32_16x16x32_bf16 v[46:49], v[174:177], v[198:201], v[46:49]
	v_mfma_f32_16x16x32_bf16 v[42:45], v[182:185], v[198:201], v[42:45]
	v_mfma_f32_16x16x32_bf16 v[30:33], v[174:177], v[206:209], v[30:33]
	v_mfma_f32_16x16x32_bf16 v[26:29], v[182:185], v[206:209], v[26:29]
	v_mfma_f32_16x16x32_bf16 v[10:13], v[174:177], v[214:217], v[10:13]
	v_mfma_f32_16x16x32_bf16 v[14:17], v[182:185], v[214:217], v[14:17]
	v_mfma_f32_16x16x32_bf16 v[62:65], v[178:181], v[194:197], v[62:65]
	v_mfma_f32_16x16x32_bf16 v[58:61], v[186:189], v[194:197], v[58:61]
	v_mfma_f32_16x16x32_bf16 v[46:49], v[178:181], v[202:205], v[46:49]
	v_mfma_f32_16x16x32_bf16 v[42:45], v[186:189], v[202:205], v[42:45]
	v_mfma_f32_16x16x32_bf16 v[30:33], v[178:181], v[210:213], v[30:33]
	v_mfma_f32_16x16x32_bf16 v[26:29], v[186:189], v[210:213], v[26:29]
	v_mfma_f32_16x16x32_bf16 v[10:13], v[178:181], v[218:221], v[10:13]
	v_mfma_f32_16x16x32_bf16 v[14:17], v[186:189], v[218:221], v[14:17]
	s_setprio 0
	s_barrier
; #define PG8_STAGE(bufoff, gbase, voff) do { _Pragma("unroll") for (int _i = 0; _i < 2; ++_i) \
;         __builtin_amdgcn_global_load_lds((const unsigned*)((const char*)(gbase) + (voff)[_i]), (PG8_LAS unsigned*)(lds + (bufoff) + ldsw + _i * 8192), 16, 0, 0); } while (0)
; #define PG8_LDA(dst, b, h) do { _Pragma("unroll") for (int m = 0; m < 4; ++m) _Pragma("unroll") for (int k = 0; k < 2; ++k) dst[m][k] = *(const PG8_LAS bf16x8*)(lds + PG8_SA(b, h) + aoff + m * 2048 + k * 1024); } while (0)
; #define PG8_LDB(dst, b, h) do { _Pragma("unroll") for (int n = 0; n < 2; ++n) _Pragma("unroll") for (int k = 0; k < 2; ++k) dst[n][k] = *(const PG8_LAS bf16x8*)(lds + PG8_SB(b, h) + boff + n * 2048 + k * 1024); } while (0)
; #define PG8_MMA(ai, bj, At, Bt) do { __builtin_amdgcn_s_setprio(1); _Pragma("unroll") for (int m = 0; m < 4; ++m) _Pragma("unroll") for (int n = 0; n < 2; ++n) _Pragma("unroll") for (int k = 0; k < 2; ++k) \
;         acc[ai][bj][m][n] = __builtin_amdgcn_mfma_f32_16x16x32_bf16(Bt[n][k], At[m][k], acc[ai][bj][m][n], 0, 0, 0); __builtin_amdgcn_s_setprio(0); } while (0)
; #define PG8_WAIT_V(n) asm volatile("s_waitcnt vmcnt(" #n ")" ::: "memory")
; #define PG8_WAIT_L(n) asm volatile("s_waitcnt lgkmcnt(" #n ")" ::: "memory")
; #define PG8_BAR __builtin_amdgcn_s_barrier()
; #define PG8_SCHED __builtin_amdgcn_sched_barrier(0)
; template <class Epi, class Sched, bool ALIGN_EPI = false, bool SP2 = false>
; __device__ __forceinline__ void gemm_phase(PG8_LAS unsigned char* lds, const Gemm g, const Sched& S, const Epi& E) {
;     ...
;             PG8_LDB(B0, 1, 0); PG8_LDB(B1, 1, 1); PG8_SCHED; PG8_LDA(At, 1, 0); PG8_STAGE(PG8_SA(0, 1), a2 + hstep, voffA);
;             PG8_WAIT_V(8); PG8_WAIT_L(0); PG8_BAR; PG8_MMA(0, 0, At, B0); PG8_MMA(0, 1, At, B1); PG8_BAR; PG8_SCHED;
;             PG8_LDA(At, 1, 1); PG8_STAGE(PG8_SB(1, 0), b3, voffB); PG8_STAGE(PG8_SB(1, 1), b3 + hstep, voffB); PG8_STAGE(PG8_SA(1, 0), a3, voffA);
;             PG8_WAIT_V(8); PG8_WAIT_L(0); PG8_BAR; PG8_MMA(1, 0, At, B0); PG8_MMA(1, 1, At, B1); PG8_BAR; PG8_SCHED;
	s_add_i32 s33, 0, 0x18000
	s_add_i32 s42, 0, 0x1c000
	ds_read_b128 v[148:151], v241 offset:32768
	ds_read_b128 v[156:159], v241 offset:33792
	ds_read_b128 v[166:169], v241 offset:34816
	ds_read_b128 v[170:173], v241 offset:35840
	ds_read_b128 v[174:177], v241 offset:49152
	ds_read_b128 v[178:181], v241 offset:50176
	ds_read_b128 v[182:185], v241 offset:51200
	ds_read_b128 v[186:189], v241 offset:52224
	s_add_u32 s24, s24, 0x100000
	s_addc_u32 s25, s25, 0
	s_mov_b32 m0, s36
	ds_read_b128 v[190:193], v155 offset:32768
	ds_read_b128 v[194:197], v155 offset:33792
	ds_read_b128 v[198:201], v155 offset:34816
	ds_read_b128 v[202:205], v155 offset:35840
	ds_read_b128 v[206:209], v155 offset:36864
	ds_read_b128 v[210:213], v155 offset:37888
	ds_read_b128 v[214:217], v155 offset:38912
	ds_read_b128 v[218:221], v155 offset:39936
	global_load_lds_dwordx4 v130, s[24:25]
	s_mov_b32 m0, s37
	s_nop 0
	global_load_lds_dwordx4 v134, s[24:25]
	s_waitcnt vmcnt(8)
	s_waitcnt lgkmcnt(0)
	s_barrier
	s_setprio 1
	v_mfma_f32_16x16x32_bf16 v[118:121], v[148:151], v[190:193], v[118:121]
	v_mfma_f32_16x16x32_bf16 v[114:117], v[166:169], v[190:193], v[114:117]
	v_mfma_f32_16x16x32_bf16 v[102:105], v[148:151], v[198:201], v[102:105]
	v_mfma_f32_16x16x32_bf16 v[98:101], v[166:169], v[198:201], v[98:101]
	v_mfma_f32_16x16x32_bf16 v[86:89], v[148:151], v[206:209], v[86:89]
	v_mfma_f32_16x16x32_bf16 v[82:85], v[166:169], v[206:209], v[82:85]
	v_mfma_f32_16x16x32_bf16 v[70:73], v[148:151], v[214:217], v[70:73]
	v_mfma_f32_16x16x32_bf16 v[66:69], v[166:169], v[214:217], v[66:69]
	v_mfma_f32_16x16x32_bf16 v[118:121], v[156:159], v[194:197], v[118:121]
	v_mfma_f32_16x16x32_bf16 v[114:117], v[170:173], v[194:197], v[114:117]
	v_mfma_f32_16x16x32_bf16 v[102:105], v[156:159], v[202:205], v[102:105]
	v_mfma_f32_16x16x32_bf16 v[98:101], v[170:173], v[202:205], v[98:101]
	v_mfma_f32_16x16x32_bf16 v[86:89], v[156:159], v[210:213], v[86:89]
	v_mfma_f32_16x16x32_bf16 v[82:85], v[170:173], v[210:213], v[82:85]
	v_mfma_f32_16x16x32_bf16 v[70:73], v[156:159], v[218:221], v[70:73]
	v_mfma_f32_16x16x32_bf16 v[66:69], v[170:173], v[218:221], v[66:69]
	v_mfma_f32_16x16x32_bf16 v[126:129], v[174:177], v[190:193], v[126:129]
	v_mfma_f32_16x16x32_bf16 v[122:125], v[182:185], v[190:193], v[122:125]
	v_mfma_f32_16x16x32_bf16 v[110:113], v[174:177], v[198:201], v[110:113]
	v_mfma_f32_16x16x32_bf16 v[106:109], v[182:185], v[198:201], v[106:109]
	v_mfma_f32_16x16x32_bf16 v[94:97], v[174:177], v[206:209], v[94:97]
	v_mfma_f32_16x16x32_bf16 v[90:93], v[182:185], v[206:209], v[90:93]
	v_mfma_f32_16x16x32_bf16 v[78:81], v[174:177], v[214:217], v[78:81]
	v_mfma_f32_16x16x32_bf16 v[74:77], v[182:185], v[214:217], v[74:77]
	v_mfma_f32_16x16x32_bf16 v[126:129], v[178:181], v[194:197], v[126:129]
	v_mfma_f32_16x16x32_bf16 v[122:125], v[186:189], v[194:197], v[122:125]
	v_mfma_f32_16x16x32_bf16 v[110:113], v[178:181], v[202:205], v[110:113]
	v_mfma_f32_16x16x32_bf16 v[106:109], v[186:189], v[202:205], v[106:109]
	v_mfma_f32_16x16x32_bf16 v[94:97], v[178:181], v[210:213], v[94:97]
	v_mfma_f32_16x16x32_bf16 v[90:93], v[186:189], v[210:213], v[90:93]
	v_mfma_f32_16x16x32_bf16 v[78:81], v[178:181], v[218:221], v[78:81]
	v_mfma_f32_16x16x32_bf16 v[74:77], v[186:189], v[218:221], v[74:77]
	s_setprio 0
	s_barrier
	s_add_i32 s24, s33, s28
	s_add_i32 m0, s24, 0xffffff80
	ds_read_b128 v[190:193], v155 offset:49152
	ds_read_b128 v[194:197], v155 offset:50176
	ds_read_b128 v[198:201], v155 offset:51200
	ds_read_b128 v[202:205], v155 offset:52224
	ds_read_b128 v[206:209], v155 offset:53248
	ds_read_b128 v[210:213], v155 offset:54272
	ds_read_b128 v[214:217], v155 offset:55296
	ds_read_b128 v[218:221], v155 offset:56320
	global_load_lds_dwordx4 v132, s[20:21] offset:128
	s_add_i32 m0, s24, 0x1f80
	s_add_i32 s24, s42, s28
	global_load_lds_dwordx4 v136, s[20:21] offset:128
	s_add_u32 s20, s20, 0x100080
	s_addc_u32 s21, s21, 0
	s_mov_b32 m0, s24
	s_nop 0
	global_load_lds_dwordx4 v132, s[20:21]
	s_add_i32 m0, s24, 0x2000
	s_nop 0
	global_load_lds_dwordx4 v136, s[20:21]
	s_mov_b32 m0, s43
	s_nop 0
	global_load_lds_dwordx4 v130, s[100:101]
	s_mov_b32 m0, s46
	s_nop 0
	global_load_lds_dwordx4 v134, s[100:101]
	s_waitcnt vmcnt(8)
	s_waitcnt lgkmcnt(0)
	s_barrier
	s_setprio 1
	v_mfma_f32_16x16x32_bf16 v[54:57], v[148:151], v[190:193], v[54:57]
	v_mfma_f32_16x16x32_bf16 v[50:53], v[166:169], v[190:193], v[50:53]
	v_mfma_f32_16x16x32_bf16 v[38:41], v[148:151], v[198:201], v[38:41]
	v_mfma_f32_16x16x32_bf16 v[34:37], v[166:169], v[198:201], v[34:37]
	v_mfma_f32_16x16x32_bf16 v[22:25], v[148:151], v[206:209], v[22:25]
	v_mfma_f32_16x16x32_bf16 v[18:21], v[166:169], v[206:209], v[18:21]
	v_mfma_f32_16x16x32_bf16 v[6:9], v[148:151], v[214:217], v[6:9]
	v_mfma_f32_16x16x32_bf16 v[2:5], v[166:169], v[214:217], v[2:5]
	v_mfma_f32_16x16x32_bf16 v[54:57], v[156:159], v[194:197], v[54:57]
	v_mfma_f32_16x16x32_bf16 v[50:53], v[170:173], v[194:197], v[50:53]
	v_mfma_f32_16x16x32_bf16 v[38:41], v[156:159], v[202:205], v[38:41]
	v_mfma_f32_16x16x32_bf16 v[34:37], v[170:173], v[202:205], v[34:37]
	v_mfma_f32_16x16x32_bf16 v[22:25], v[156:159], v[210:213], v[22:25]
	v_mfma_f32_16x16x32_bf16 v[18:21], v[170:173], v[210:213], v[18:21]
	v_mfma_f32_16x16x32_bf16 v[6:9], v[156:159], v[218:221], v[6:9]
	v_mfma_f32_16x16x32_bf16 v[2:5], v[170:173], v[218:221], v[2:5]
	v_mfma_f32_16x16x32_bf16 v[62:65], v[174:177], v[190:193], v[62:65]
	v_mfma_f32_16x16x32_bf16 v[58:61], v[182:185], v[190:193], v[58:61]
	v_mfma_f32_16x16x32_bf16 v[46:49], v[174:177], v[198:201], v[46:49]
	v_mfma_f32_16x16x32_bf16 v[42:45], v[182:185], v[198:201], v[42:45]
	v_mfma_f32_16x16x32_bf16 v[30:33], v[174:177], v[206:209], v[30:33]
	v_mfma_f32_16x16x32_bf16 v[26:29], v[182:185], v[206:209], v[26:29]
	v_mfma_f32_16x16x32_bf16 v[10:13], v[174:177], v[214:217], v[10:13]
	v_mfma_f32_16x16x32_bf16 v[14:17], v[182:185], v[214:217], v[14:17]
	v_mfma_f32_16x16x32_bf16 v[62:65], v[178:181], v[194:197], v[62:65]
	v_mfma_f32_16x16x32_bf16 v[58:61], v[186:189], v[194:197], v[58:61]
	v_mfma_f32_16x16x32_bf16 v[46:49], v[178:181], v[202:205], v[46:49]
	v_mfma_f32_16x16x32_bf16 v[42:45], v[186:189], v[202:205], v[42:45]
	v_mfma_f32_16x16x32_bf16 v[30:33], v[178:181], v[210:213], v[30:33]
	v_mfma_f32_16x16x32_bf16 v[26:29], v[186:189], v[210:213], v[26:29]
	v_mfma_f32_16x16x32_bf16 v[10:13], v[178:181], v[218:221], v[10:13]
	v_mfma_f32_16x16x32_bf16 v[14:17], v[186:189], v[218:221], v[14:17]
	s_setprio 0
	s_barrier
	s_add_i32 s67, s67, 2
	s_add_u32 s22, s22, 0x100
	s_addc_u32 s23, s23, 0
	s_add_u32 s65, s65, 0x100
	s_addc_u32 s66, s66, 0
	s_cmp_gt_u32 s67, 61
	s_cbranch_scc0 .LBB0_1332
	s_and_b64 vcc, exec, s[8:9]
	s_cbranch_vccz .LBB0_1335
	s_barrier

; #define PG8_STAGE(bufoff, gbase, voff) do { _Pragma("unroll") for (int _i = 0; _i < 2; ++_i) \
;         __builtin_amdgcn_global_load_lds((const unsigned*)((const char*)(gbase) + (voff)[_i]), (PG8_LAS unsigned*)(lds + (bufoff) + ldsw + _i * 8192), 16, 0, 0); } while (0)
; #define PG8_LDA(dst, b, h) do { _Pragma("unroll") for (int m = 0; m < 4; ++m) _Pragma("unroll") for (int k = 0; k < 2; ++k) dst[m][k] = *(const PG8_LAS bf16x8*)(lds + PG8_SA(b, h) + aoff + m * 2048 + k * 1024); } while (0)
; #define PG8_LDB(dst, b, h) do { _Pragma("unroll") for (int n = 0; n < 2; ++n) _Pragma("unroll") for (int k = 0; k < 2; ++k) dst[n][k] = *(const PG8_LAS bf16x8*)(lds + PG8_SB(b, h) + boff + n * 2048 + k * 1024); } while (0)
; #define PG8_MMA(ai, bj, At, Bt) do { __builtin_amdgcn_s_setprio(1); _Pragma("unroll") for (int m = 0; m < 4; ++m) _Pragma("unroll") for (int n = 0; n < 2; ++n) _Pragma("unroll") for (int k = 0; k < 2; ++k) \
;         acc[ai][bj][m][n] = __builtin_amdgcn_mfma_f32_16x16x32_bf16(Bt[n][k], At[m][k], acc[ai][bj][m][n], 0, 0, 0); __builtin_amdgcn_s_setprio(0); } while (0)
; #define PG8_WAIT_V(n) asm volatile("s_waitcnt vmcnt(" #n ")" ::: "memory")
; #define PG8_BAR __builtin_amdgcn_s_barrier()
; template <class Epi, class Sched, bool ALIGN_EPI = false, bool SP2 = false>
; __device__ __forceinline__ void gemm_phase(PG8_LAS unsigned char* lds, const Gemm g, const Sched& S, const Epi& E) {
;     ...
;         for (int t = 0; t < nt; t += 2) {
;             const bool last = (t == nt - 2);
;             const char* a1 = cA + (size_t)(t + 1) * kstep;
;             const char* a2 = last ? nA : cA + (size_t)(t + 2) * kstep; const char* b2 = last ? nB : cB + (size_t)(t + 2) * kstep;
;             const char* a3 = a2 + kstep; const char* b3 = b2 + kstep;
;             if (last && has_next) S.a_ready(nxt);
;             if constexpr (SP2) {
;             PG8_LDB(B0, 0, 0); PG8_LDB(B1, 0, 1); PG8_SCHED; PG8_LDA(At, 0, 0); PG8_STAGE(PG8_SA(1, 1), a1 + hstep, voffA);
;             PG8_WAIT_V(8); PG8_WAIT_L(0); PG8_BAR; PG8_MMA(0, 0, At, B0); PG8_MMA(0, 1, At, B1); PG8_BAR; PG8_SCHED;
;             PG8_LDA(At, 0, 1); PG8_STAGE(PG8_SB(0, 0), b2, voffB); PG8_STAGE(PG8_SB(0, 1), b2 + hstep, voffB); PG8_STAGE(PG8_SA(0, 0), a2, voffA);
;             PG8_WAIT_V(8); PG8_WAIT_L(0); PG8_BAR; PG8_MMA(1, 0, At, B0); PG8_MMA(1, 1, At, B1); PG8_BAR; PG8_SCHED;
.LBB0_1595:
	ds_read_b128 v[130:133], v241 offset:0
	ds_read_b128 v[134:137], v241 offset:1024
	ds_read_b128 v[138:141], v241 offset:2048
	ds_read_b128 v[142:145], v241 offset:3072
	ds_read_b128 v[146:149], v241 offset:16384
	ds_read_b128 v[150:153], v241 offset:17408
	ds_read_b128 v[172:175], v241 offset:18432
	ds_read_b128 v[176:179], v241 offset:19456
	s_add_u32 s24, s26, 0xfff00080
	s_addc_u32 s25, s27, -1
	s_cmp_eq_u32 s62, 60
	s_cselect_b32 s29, s15, s25
	s_cselect_b32 s28, s21, s24
	s_cselect_b32 s25, s13, s53
	s_cselect_b32 s24, s51, s52
	s_add_i32 m0, s23, 0xc000
	ds_read_b128 v[180:183], v185
	ds_read_b128 v[188:191], v185 offset:1024
	ds_read_b128 v[192:195], v185 offset:2048
	ds_read_b128 v[196:199], v185 offset:3072
	ds_read_b128 v[200:203], v185 offset:4096
	ds_read_b128 v[204:207], v185 offset:5120
	ds_read_b128 v[208:211], v185 offset:6144
	ds_read_b128 v[212:215], v185 offset:7168
	global_load_lds_dwordx4 v162, s[26:27]
	s_add_i32 m0, s23, 0xe000
	s_nop 0
	global_load_lds_dwordx4 v166, s[26:27]
	s_waitcnt vmcnt(8)
	s_waitcnt lgkmcnt(0)
	s_barrier
	s_setprio 1
	v_mfma_f32_16x16x32_bf16 v[114:117], v[130:133], v[180:183], v[114:117]
	v_mfma_f32_16x16x32_bf16 v[118:121], v[138:141], v[180:183], v[118:121]
	v_mfma_f32_16x16x32_bf16 v[106:109], v[130:133], v[192:195], v[106:109]
	v_mfma_f32_16x16x32_bf16 v[98:101], v[138:141], v[192:195], v[98:101]
	v_mfma_f32_16x16x32_bf16 v[90:93], v[130:133], v[200:203], v[90:93]
	v_mfma_f32_16x16x32_bf16 v[82:85], v[138:141], v[200:203], v[82:85]
	v_mfma_f32_16x16x32_bf16 v[74:77], v[130:133], v[208:211], v[74:77]
	v_mfma_f32_16x16x32_bf16 v[66:69], v[138:141], v[208:211], v[66:69]
	v_mfma_f32_16x16x32_bf16 v[114:117], v[134:137], v[188:191], v[114:117]
	v_mfma_f32_16x16x32_bf16 v[118:121], v[142:145], v[188:191], v[118:121]
	v_mfma_f32_16x16x32_bf16 v[106:109], v[134:137], v[196:199], v[106:109]
	v_mfma_f32_16x16x32_bf16 v[98:101], v[142:145], v[196:199], v[98:101]
	v_mfma_f32_16x16x32_bf16 v[90:93], v[134:137], v[204:207], v[90:93]
	v_mfma_f32_16x16x32_bf16 v[82:85], v[142:145], v[204:207], v[82:85]
	v_mfma_f32_16x16x32_bf16 v[74:77], v[134:137], v[212:215], v[74:77]
	v_mfma_f32_16x16x32_bf16 v[66:69], v[142:145], v[212:215], v[66:69]
	v_mfma_f32_16x16x32_bf16 v[122:125], v[146:149], v[180:183], v[122:125]
	v_mfma_f32_16x16x32_bf16 v[126:129], v[172:175], v[180:183], v[126:129]
	v_mfma_f32_16x16x32_bf16 v[110:113], v[146:149], v[192:195], v[110:113]
	v_mfma_f32_16x16x32_bf16 v[102:105], v[172:175], v[192:195], v[102:105]
	v_mfma_f32_16x16x32_bf16 v[94:97], v[146:149], v[200:203], v[94:97]
	v_mfma_f32_16x16x32_bf16 v[86:89], v[172:175], v[200:203], v[86:89]
	v_mfma_f32_16x16x32_bf16 v[78:81], v[146:149], v[208:211], v[78:81]
	v_mfma_f32_16x16x32_bf16 v[70:73], v[172:175], v[208:211], v[70:73]
	v_mfma_f32_16x16x32_bf16 v[122:125], v[150:153], v[188:191], v[122:125]
	v_mfma_f32_16x16x32_bf16 v[126:129], v[176:179], v[188:191], v[126:129]
	v_mfma_f32_16x16x32_bf16 v[110:113], v[150:153], v[196:199], v[110:113]
	v_mfma_f32_16x16x32_bf16 v[102:105], v[176:179], v[196:199], v[102:105]
	v_mfma_f32_16x16x32_bf16 v[94:97], v[150:153], v[204:207], v[94:97]
	v_mfma_f32_16x16x32_bf16 v[86:89], v[176:179], v[204:207], v[86:89]
	v_mfma_f32_16x16x32_bf16 v[78:81], v[150:153], v[212:215], v[78:81]
	v_mfma_f32_16x16x32_bf16 v[70:73], v[176:179], v[212:215], v[70:73]
	s_setprio 0
	s_barrier
	s_add_i32 s33, s48, s36
	s_mov_b32 m0, s33
	ds_read_b128 v[180:183], v185 offset:16384
	ds_read_b128 v[188:191], v185 offset:17408
	ds_read_b128 v[192:195], v185 offset:18432
	ds_read_b128 v[196:199], v185 offset:19456
	ds_read_b128 v[200:203], v185 offset:20480
	ds_read_b128 v[204:207], v185 offset:21504
	ds_read_b128 v[208:211], v185 offset:22528
	ds_read_b128 v[212:215], v185 offset:23552
	global_load_lds_dwordx4 v156, s[24:25]
	s_add_i32 m0, s33, 0x2000
	s_add_u32 s64, s24, 0x100000
	s_addc_u32 s65, s25, 0
	s_add_i32 s33, s49, s36
	global_load_lds_dwordx4 v160, s[24:25]
	s_mov_b32 m0, s33
	s_add_u32 s100, s28, 0x80
	s_addc_u32 s101, s29, 0
	global_load_lds_dwordx4 v156, s[64:65]
	s_add_i32 m0, s33, 0x2000
	s_nop 0
	global_load_lds_dwordx4 v160, s[64:65]
	s_mov_b32 m0, s23
	s_nop 0
	global_load_lds_dwordx4 v154, s[28:29]
	s_mov_b32 m0, s37
	s_nop 0
	global_load_lds_dwordx4 v158, s[28:29]
	s_waitcnt vmcnt(8)
	s_waitcnt lgkmcnt(0)
	s_barrier
	s_setprio 1
	v_mfma_f32_16x16x32_bf16 v[58:61], v[130:133], v[180:183], v[58:61]
	v_mfma_f32_16x16x32_bf16 v[54:57], v[138:141], v[180:183], v[54:57]
	v_mfma_f32_16x16x32_bf16 v[42:45], v[130:133], v[192:195], v[42:45]
	v_mfma_f32_16x16x32_bf16 v[34:37], v[138:141], v[192:195], v[34:37]
	v_mfma_f32_16x16x32_bf16 v[26:29], v[130:133], v[200:203], v[26:29]
	v_mfma_f32_16x16x32_bf16 v[18:21], v[138:141], v[200:203], v[18:21]
	v_mfma_f32_16x16x32_bf16 v[6:9], v[130:133], v[208:211], v[6:9]
	v_mfma_f32_16x16x32_bf16 v[2:5], v[138:141], v[208:211], v[2:5]
	v_mfma_f32_16x16x32_bf16 v[58:61], v[134:137], v[188:191], v[58:61]
	v_mfma_f32_16x16x32_bf16 v[54:57], v[142:145], v[188:191], v[54:57]
	v_mfma_f32_16x16x32_bf16 v[42:45], v[134:137], v[196:199], v[42:45]
	v_mfma_f32_16x16x32_bf16 v[34:37], v[142:145], v[196:199], v[34:37]
	v_mfma_f32_16x16x32_bf16 v[26:29], v[134:137], v[204:207], v[26:29]
	v_mfma_f32_16x16x32_bf16 v[18:21], v[142:145], v[204:207], v[18:21]
	v_mfma_f32_16x16x32_bf16 v[6:9], v[134:137], v[212:215], v[6:9]
	v_mfma_f32_16x16x32_bf16 v[2:5], v[142:145], v[212:215], v[2:5]
	v_mfma_f32_16x16x32_bf16 v[62:65], v[146:149], v[180:183], v[62:65]
	v_mfma_f32_16x16x32_bf16 v[50:53], v[172:175], v[180:183], v[50:53]
	v_mfma_f32_16x16x32_bf16 v[46:49], v[146:149], v[192:195], v[46:49]
	v_mfma_f32_16x16x32_bf16 v[38:41], v[172:175], v[192:195], v[38:41]
	v_mfma_f32_16x16x32_bf16 v[30:33], v[146:149], v[200:203], v[30:33]
	v_mfma_f32_16x16x32_bf16 v[22:25], v[172:175], v[200:203], v[22:25]
	v_mfma_f32_16x16x32_bf16 v[10:13], v[146:149], v[208:211], v[10:13]
	v_mfma_f32_16x16x32_bf16 v[14:17], v[172:175], v[208:211], v[14:17]
	v_mfma_f32_16x16x32_bf16 v[62:65], v[150:153], v[188:191], v[62:65]
	v_mfma_f32_16x16x32_bf16 v[50:53], v[176:179], v[188:191], v[50:53]
	v_mfma_f32_16x16x32_bf16 v[46:49], v[150:153], v[196:199], v[46:49]
	v_mfma_f32_16x16x32_bf16 v[38:41], v[176:179], v[196:199], v[38:41]
	v_mfma_f32_16x16x32_bf16 v[30:33], v[150:153], v[204:207], v[30:33]
	v_mfma_f32_16x16x32_bf16 v[22:25], v[176:179], v[204:207], v[22:25]
	v_mfma_f32_16x16x32_bf16 v[10:13], v[150:153], v[212:215], v[10:13]
	v_mfma_f32_16x16x32_bf16 v[14:17], v[176:179], v[212:215], v[14:17]
	s_setprio 0
	s_barrier
; #define PG8_STAGE(bufoff, gbase, voff) do { _Pragma("unroll") for (int _i = 0; _i < 2; ++_i) \
;         __builtin_amdgcn_global_load_lds((const unsigned*)((const char*)(gbase) + (voff)[_i]), (PG8_LAS unsigned*)(lds + (bufoff) + ldsw + _i * 8192), 16, 0, 0); } while (0)
; #define PG8_LDA(dst, b, h) do { _Pragma("unroll") for (int m = 0; m < 4; ++m) _Pragma("unroll") for (int k = 0; k < 2; ++k) dst[m][k] = *(const PG8_LAS bf16x8*)(lds + PG8_SA(b, h) + aoff + m * 2048 + k * 1024); } while (0)
; #define PG8_LDB(dst, b, h) do { _Pragma("unroll") for (int n = 0; n < 2; ++n) _Pragma("unroll") for (int k = 0; k < 2; ++k) dst[n][k] = *(const PG8_LAS bf16x8*)(lds + PG8_SB(b, h) + boff + n * 2048 + k * 1024); } while (0)
; #define PG8_MMA(ai, bj, At, Bt) do { __builtin_amdgcn_s_setprio(1); _Pragma("unroll") for (int m = 0; m < 4; ++m) _Pragma("unroll") for (int n = 0; n < 2; ++n) _Pragma("unroll") for (int k = 0; k < 2; ++k) \
;         acc[ai][bj][m][n] = __builtin_amdgcn_mfma_f32_16x16x32_bf16(Bt[n][k], At[m][k], acc[ai][bj][m][n], 0, 0, 0); __builtin_amdgcn_s_setprio(0); } while (0)
; #define PG8_WAIT_V(n) asm volatile("s_waitcnt vmcnt(" #n ")" ::: "memory")
; #define PG8_WAIT_L(n) asm volatile("s_waitcnt lgkmcnt(" #n ")" ::: "memory")
; #define PG8_BAR __builtin_amdgcn_s_barrier()
; #define PG8_SCHED __builtin_amdgcn_sched_barrier(0)
; template <class Epi, class Sched, bool ALIGN_EPI = false, bool SP2 = false>
; __device__ __forceinline__ void gemm_phase(PG8_LAS unsigned char* lds, const Gemm g, const Sched& S, const Epi& E) {
;     ...
;             PG8_LDB(B0, 1, 0); PG8_LDB(B1, 1, 1); PG8_SCHED; PG8_LDA(At, 1, 0); PG8_STAGE(PG8_SA(0, 1), a2 + hstep, voffA);
;             PG8_WAIT_V(8); PG8_WAIT_L(0); PG8_BAR; PG8_MMA(0, 0, At, B0); PG8_MMA(0, 1, At, B1); PG8_BAR; PG8_SCHED;
;             PG8_LDA(At, 1, 1); PG8_STAGE(PG8_SB(1, 0), b3, voffB); PG8_STAGE(PG8_SB(1, 1), b3 + hstep, voffB); PG8_STAGE(PG8_SA(1, 0), a3, voffA);
;             PG8_WAIT_V(8); PG8_WAIT_L(0); PG8_BAR; PG8_MMA(1, 0, At, B0); PG8_MMA(1, 1, At, B1); PG8_BAR; PG8_SCHED;
	s_add_i32 s33, 0, 0x18000
	s_add_i32 s42, 0, 0x1c000
	ds_read_b128 v[130:133], v241 offset:32768
	ds_read_b128 v[134:137], v241 offset:33792
	ds_read_b128 v[138:141], v241 offset:34816
	ds_read_b128 v[142:145], v241 offset:35840
	ds_read_b128 v[146:149], v241 offset:49152
	ds_read_b128 v[150:153], v241 offset:50176
	ds_read_b128 v[172:175], v241 offset:51200
	ds_read_b128 v[176:179], v241 offset:52224
	s_add_u32 s28, s28, 0x100000
	s_addc_u32 s29, s29, 0
	s_mov_b32 m0, s40
	ds_read_b128 v[180:183], v185 offset:32768
	ds_read_b128 v[188:191], v185 offset:33792
	ds_read_b128 v[192:195], v185 offset:34816
	ds_read_b128 v[196:199], v185 offset:35840
	ds_read_b128 v[200:203], v185 offset:36864
	ds_read_b128 v[204:207], v185 offset:37888
	ds_read_b128 v[208:211], v185 offset:38912
	ds_read_b128 v[212:215], v185 offset:39936
	global_load_lds_dwordx4 v154, s[28:29]
	s_mov_b32 m0, s41
	s_nop 0
	global_load_lds_dwordx4 v158, s[28:29]
	s_waitcnt vmcnt(8)
	s_waitcnt lgkmcnt(0)
	s_barrier
	s_setprio 1
	v_mfma_f32_16x16x32_bf16 v[114:117], v[130:133], v[180:183], v[114:117]
	v_mfma_f32_16x16x32_bf16 v[118:121], v[138:141], v[180:183], v[118:121]
	v_mfma_f32_16x16x32_bf16 v[106:109], v[130:133], v[192:195], v[106:109]
	v_mfma_f32_16x16x32_bf16 v[98:101], v[138:141], v[192:195], v[98:101]
	v_mfma_f32_16x16x32_bf16 v[90:93], v[130:133], v[200:203], v[90:93]
	v_mfma_f32_16x16x32_bf16 v[82:85], v[138:141], v[200:203], v[82:85]
	v_mfma_f32_16x16x32_bf16 v[74:77], v[130:133], v[208:211], v[74:77]
	v_mfma_f32_16x16x32_bf16 v[66:69], v[138:141], v[208:211], v[66:69]
	v_mfma_f32_16x16x32_bf16 v[114:117], v[134:137], v[188:191], v[114:117]
	v_mfma_f32_16x16x32_bf16 v[118:121], v[142:145], v[188:191], v[118:121]
	v_mfma_f32_16x16x32_bf16 v[106:109], v[134:137], v[196:199], v[106:109]
	v_mfma_f32_16x16x32_bf16 v[98:101], v[142:145], v[196:199], v[98:101]
	v_mfma_f32_16x16x32_bf16 v[90:93], v[134:137], v[204:207], v[90:93]
	v_mfma_f32_16x16x32_bf16 v[82:85], v[142:145], v[204:207], v[82:85]
	v_mfma_f32_16x16x32_bf16 v[74:77], v[134:137], v[212:215], v[74:77]
	v_mfma_f32_16x16x32_bf16 v[66:69], v[142:145], v[212:215], v[66:69]
	v_mfma_f32_16x16x32_bf16 v[122:125], v[146:149], v[180:183], v[122:125]
	v_mfma_f32_16x16x32_bf16 v[126:129], v[172:175], v[180:183], v[126:129]
	v_mfma_f32_16x16x32_bf16 v[110:113], v[146:149], v[192:195], v[110:113]
	v_mfma_f32_16x16x32_bf16 v[102:105], v[172:175], v[192:195], v[102:105]
	v_mfma_f32_16x16x32_bf16 v[94:97], v[146:149], v[200:203], v[94:97]
	v_mfma_f32_16x16x32_bf16 v[86:89], v[172:175], v[200:203], v[86:89]
	v_mfma_f32_16x16x32_bf16 v[78:81], v[146:149], v[208:211], v[78:81]
	v_mfma_f32_16x16x32_bf16 v[70:73], v[172:175], v[208:211], v[70:73]
	v_mfma_f32_16x16x32_bf16 v[122:125], v[150:153], v[188:191], v[122:125]
	v_mfma_f32_16x16x32_bf16 v[126:129], v[176:179], v[188:191], v[126:129]
	v_mfma_f32_16x16x32_bf16 v[110:113], v[150:153], v[196:199], v[110:113]
	v_mfma_f32_16x16x32_bf16 v[102:105], v[176:179], v[196:199], v[102:105]
	v_mfma_f32_16x16x32_bf16 v[94:97], v[150:153], v[204:207], v[94:97]
	v_mfma_f32_16x16x32_bf16 v[86:89], v[176:179], v[204:207], v[86:89]
	v_mfma_f32_16x16x32_bf16 v[78:81], v[150:153], v[212:215], v[78:81]
	v_mfma_f32_16x16x32_bf16 v[70:73], v[176:179], v[212:215], v[70:73]
	s_setprio 0
	s_barrier
	s_add_i32 s28, s33, s36
	s_add_i32 m0, s28, 0xffffff80
	ds_read_b128 v[180:183], v185 offset:49152
	ds_read_b128 v[188:191], v185 offset:50176
	ds_read_b128 v[192:195], v185 offset:51200
	ds_read_b128 v[196:199], v185 offset:52224
	ds_read_b128 v[200:203], v185 offset:53248
	ds_read_b128 v[204:207], v185 offset:54272
	ds_read_b128 v[208:211], v185 offset:55296
	ds_read_b128 v[212:215], v185 offset:56320
	global_load_lds_dwordx4 v156, s[24:25] offset:128
	s_add_i32 m0, s28, 0x1f80
	s_add_i32 s28, s42, s36
	global_load_lds_dwordx4 v160, s[24:25] offset:128
	s_add_u32 s24, s24, 0x100080
	s_addc_u32 s25, s25, 0
	s_mov_b32 m0, s28
	s_nop 0
	global_load_lds_dwordx4 v156, s[24:25]
	s_add_i32 m0, s28, 0x2000
	s_nop 0
	global_load_lds_dwordx4 v160, s[24:25]
	s_mov_b32 m0, s44
	s_nop 0
	global_load_lds_dwordx4 v154, s[100:101]
	s_mov_b32 m0, s45
	s_nop 0
	global_load_lds_dwordx4 v158, s[100:101]
	s_waitcnt vmcnt(8)
	s_waitcnt lgkmcnt(0)
	s_barrier
	s_setprio 1
	v_mfma_f32_16x16x32_bf16 v[58:61], v[130:133], v[180:183], v[58:61]
	v_mfma_f32_16x16x32_bf16 v[54:57], v[138:141], v[180:183], v[54:57]
	v_mfma_f32_16x16x32_bf16 v[42:45], v[130:133], v[192:195], v[42:45]
	v_mfma_f32_16x16x32_bf16 v[34:37], v[138:141], v[192:195], v[34:37]
	v_mfma_f32_16x16x32_bf16 v[26:29], v[130:133], v[200:203], v[26:29]
	v_mfma_f32_16x16x32_bf16 v[18:21], v[138:141], v[200:203], v[18:21]
	v_mfma_f32_16x16x32_bf16 v[6:9], v[130:133], v[208:211], v[6:9]
	v_mfma_f32_16x16x32_bf16 v[2:5], v[138:141], v[208:211], v[2:5]
	v_mfma_f32_16x16x32_bf16 v[58:61], v[134:137], v[188:191], v[58:61]
	v_mfma_f32_16x16x32_bf16 v[54:57], v[142:145], v[188:191], v[54:57]
	v_mfma_f32_16x16x32_bf16 v[42:45], v[134:137], v[196:199], v[42:45]
	v_mfma_f32_16x16x32_bf16 v[34:37], v[142:145], v[196:199], v[34:37]
	v_mfma_f32_16x16x32_bf16 v[26:29], v[134:137], v[204:207], v[26:29]
	v_mfma_f32_16x16x32_bf16 v[18:21], v[142:145], v[204:207], v[18:21]
	v_mfma_f32_16x16x32_bf16 v[6:9], v[134:137], v[212:215], v[6:9]
	v_mfma_f32_16x16x32_bf16 v[2:5], v[142:145], v[212:215], v[2:5]
	v_mfma_f32_16x16x32_bf16 v[62:65], v[146:149], v[180:183], v[62:65]
	v_mfma_f32_16x16x32_bf16 v[50:53], v[172:175], v[180:183], v[50:53]
	v_mfma_f32_16x16x32_bf16 v[46:49], v[146:149], v[192:195], v[46:49]
	v_mfma_f32_16x16x32_bf16 v[38:41], v[172:175], v[192:195], v[38:41]
	v_mfma_f32_16x16x32_bf16 v[30:33], v[146:149], v[200:203], v[30:33]
	v_mfma_f32_16x16x32_bf16 v[22:25], v[172:175], v[200:203], v[22:25]
	v_mfma_f32_16x16x32_bf16 v[10:13], v[146:149], v[208:211], v[10:13]
	v_mfma_f32_16x16x32_bf16 v[14:17], v[172:175], v[208:211], v[14:17]
	v_mfma_f32_16x16x32_bf16 v[62:65], v[150:153], v[188:191], v[62:65]
	v_mfma_f32_16x16x32_bf16 v[50:53], v[176:179], v[188:191], v[50:53]
	v_mfma_f32_16x16x32_bf16 v[46:49], v[150:153], v[196:199], v[46:49]
	v_mfma_f32_16x16x32_bf16 v[38:41], v[176:179], v[196:199], v[38:41]
	v_mfma_f32_16x16x32_bf16 v[30:33], v[150:153], v[204:207], v[30:33]
	v_mfma_f32_16x16x32_bf16 v[22:25], v[176:179], v[204:207], v[22:25]
	v_mfma_f32_16x16x32_bf16 v[10:13], v[150:153], v[212:215], v[10:13]
	v_mfma_f32_16x16x32_bf16 v[14:17], v[176:179], v[212:215], v[14:17]
	s_setprio 0
	s_barrier
	s_add_i32 s62, s62, 2
	s_add_u32 s26, s26, 0x100
	s_addc_u32 s27, s27, 0
	s_add_u32 s52, s52, 0x100
	s_addc_u32 s53, s53, 0
	s_cmp_gt_u32 s62, 61
	s_cbranch_scc0 .LBB0_1595
	s_and_b64 vcc, exec, s[10:11]
	s_cbranch_vccz .LBB0_1598
	s_barrier

; #define PG8_STAGE(bufoff, gbase, voff) do { _Pragma("unroll") for (int _i = 0; _i < 2; ++_i) \
;         __builtin_amdgcn_global_load_lds((const unsigned*)((const char*)(gbase) + (voff)[_i]), (PG8_LAS unsigned*)(lds + (bufoff) + ldsw + _i * 8192), 16, 0, 0); } while (0)
; #define PG8_LDA(dst, b, h) do { _Pragma("unroll") for (int m = 0; m < 4; ++m) _Pragma("unroll") for (int k = 0; k < 2; ++k) dst[m][k] = *(const PG8_LAS bf16x8*)(lds + PG8_SA(b, h) + aoff + m * 2048 + k * 1024); } while (0)
; #define PG8_LDB(dst, b, h) do { _Pragma("unroll") for (int n = 0; n < 2; ++n) _Pragma("unroll") for (int k = 0; k < 2; ++k) dst[n][k] = *(const PG8_LAS bf16x8*)(lds + PG8_SB(b, h) + boff + n * 2048 + k * 1024); } while (0)
; #define PG8_MMA(ai, bj, At, Bt) do { __builtin_amdgcn_s_setprio(1); _Pragma("unroll") for (int m = 0; m < 4; ++m) _Pragma("unroll") for (int n = 0; n < 2; ++n) _Pragma("unroll") for (int k = 0; k < 2; ++k) \
;         acc[ai][bj][m][n] = __builtin_amdgcn_mfma_f32_16x16x32_bf16(Bt[n][k], At[m][k], acc[ai][bj][m][n], 0, 0, 0); __builtin_amdgcn_s_setprio(0); } while (0)
; #define PG8_WAIT_V(n) asm volatile("s_waitcnt vmcnt(" #n ")" ::: "memory")
; #define PG8_BAR __builtin_amdgcn_s_barrier()
; template <class Epi, class Sched, bool ALIGN_EPI = false, bool SP2 = false>
; __device__ __forceinline__ void gemm_phase(PG8_LAS unsigned char* lds, const Gemm g, const Sched& S, const Epi& E) {
;     ...
;         for (int t = 0; t < nt; t += 2) {
;             const bool last = (t == nt - 2);
;             const char* a1 = cA + (size_t)(t + 1) * kstep;
;             const char* a2 = last ? nA : cA + (size_t)(t + 2) * kstep; const char* b2 = last ? nB : cB + (size_t)(t + 2) * kstep;
;             const char* a3 = a2 + kstep; const char* b3 = b2 + kstep;
;             if (last && has_next) S.a_ready(nxt);
;             if constexpr (SP2) {
;             PG8_LDB(B0, 0, 0); PG8_LDB(B1, 0, 1); PG8_SCHED; PG8_LDA(At, 0, 0); PG8_STAGE(PG8_SA(1, 1), a1 + hstep, voffA);
;             PG8_WAIT_V(8); PG8_WAIT_L(0); PG8_BAR; PG8_MMA(0, 0, At, B0); PG8_MMA(0, 1, At, B1); PG8_BAR; PG8_SCHED;
;             PG8_LDA(At, 0, 1); PG8_STAGE(PG8_SB(0, 0), b2, voffB); PG8_STAGE(PG8_SB(0, 1), b2 + hstep, voffB); PG8_STAGE(PG8_SA(0, 0), a2, voffA);
;             PG8_WAIT_V(8); PG8_WAIT_L(0); PG8_BAR; PG8_MMA(1, 0, At, B0); PG8_MMA(1, 1, At, B1); PG8_BAR; PG8_SCHED;
.LBB0_1681:
	ds_read_b128 v[160:163], v241 offset:0
	ds_read_b128 v[166:169], v241 offset:1024
	ds_read_b128 v[170:173], v241 offset:2048
	ds_read_b128 v[174:177], v241 offset:3072
	ds_read_b128 v[178:181], v241 offset:16384
	ds_read_b128 v[182:185], v241 offset:17408
	ds_read_b128 v[186:189], v241 offset:18432
	ds_read_b128 v[190:193], v241 offset:19456
	s_add_u32 s22, s24, 0xfff00080
	s_addc_u32 s23, s25, -1
	s_cmp_eq_u32 s52, 60
	s_cselect_b32 s27, s15, s23
	s_cselect_b32 s26, s48, s22
	s_cselect_b32 s23, s13, s51
	s_cselect_b32 s22, s49, s50
	s_add_i32 m0, s21, 0xc000
	ds_read_b128 v[194:197], v155
	ds_read_b128 v[198:201], v155 offset:1024
	ds_read_b128 v[202:205], v155 offset:2048
	ds_read_b128 v[206:209], v155 offset:3072
	ds_read_b128 v[210:213], v155 offset:4096
	ds_read_b128 v[214:217], v155 offset:5120
	ds_read_b128 v[218:221], v155 offset:6144
	ds_read_b128 v[222:225], v155 offset:7168
	global_load_lds_dwordx4 v138, s[24:25]
	s_add_i32 m0, s21, 0xe000
	s_nop 0
	global_load_lds_dwordx4 v140, s[24:25]
	s_waitcnt vmcnt(8)
	s_waitcnt lgkmcnt(0)
	s_barrier
	s_setprio 1
	v_mfma_f32_16x16x32_bf16 v[122:125], v[160:163], v[194:197], v[122:125]
	v_mfma_f32_16x16x32_bf16 v[114:117], v[170:173], v[194:197], v[114:117]
	v_mfma_f32_16x16x32_bf16 v[106:109], v[160:163], v[202:205], v[106:109]
	v_mfma_f32_16x16x32_bf16 v[98:101], v[170:173], v[202:205], v[98:101]
	v_mfma_f32_16x16x32_bf16 v[90:93], v[160:163], v[210:213], v[90:93]
	v_mfma_f32_16x16x32_bf16 v[82:85], v[170:173], v[210:213], v[82:85]
	v_mfma_f32_16x16x32_bf16 v[74:77], v[160:163], v[218:221], v[74:77]
	v_mfma_f32_16x16x32_bf16 v[62:65], v[170:173], v[218:221], v[62:65]
	v_mfma_f32_16x16x32_bf16 v[122:125], v[166:169], v[198:201], v[122:125]
	v_mfma_f32_16x16x32_bf16 v[114:117], v[174:177], v[198:201], v[114:117]
	v_mfma_f32_16x16x32_bf16 v[106:109], v[166:169], v[206:209], v[106:109]
	v_mfma_f32_16x16x32_bf16 v[98:101], v[174:177], v[206:209], v[98:101]
	v_mfma_f32_16x16x32_bf16 v[90:93], v[166:169], v[214:217], v[90:93]
	v_mfma_f32_16x16x32_bf16 v[82:85], v[174:177], v[214:217], v[82:85]
	v_mfma_f32_16x16x32_bf16 v[74:77], v[166:169], v[222:225], v[74:77]
	v_mfma_f32_16x16x32_bf16 v[62:65], v[174:177], v[222:225], v[62:65]
	v_mfma_f32_16x16x32_bf16 v[126:129], v[178:181], v[194:197], v[126:129]
	v_mfma_f32_16x16x32_bf16 v[118:121], v[186:189], v[194:197], v[118:121]
	v_mfma_f32_16x16x32_bf16 v[110:113], v[178:181], v[202:205], v[110:113]
	v_mfma_f32_16x16x32_bf16 v[102:105], v[186:189], v[202:205], v[102:105]
	v_mfma_f32_16x16x32_bf16 v[94:97], v[178:181], v[210:213], v[94:97]
	v_mfma_f32_16x16x32_bf16 v[86:89], v[186:189], v[210:213], v[86:89]
	v_mfma_f32_16x16x32_bf16 v[78:81], v[178:181], v[218:221], v[78:81]
	v_mfma_f32_16x16x32_bf16 v[70:73], v[186:189], v[218:221], v[70:73]
	v_mfma_f32_16x16x32_bf16 v[126:129], v[182:185], v[198:201], v[126:129]
	v_mfma_f32_16x16x32_bf16 v[118:121], v[190:193], v[198:201], v[118:121]
	v_mfma_f32_16x16x32_bf16 v[110:113], v[182:185], v[206:209], v[110:113]
	v_mfma_f32_16x16x32_bf16 v[102:105], v[190:193], v[206:209], v[102:105]
	v_mfma_f32_16x16x32_bf16 v[94:97], v[182:185], v[214:217], v[94:97]
	v_mfma_f32_16x16x32_bf16 v[86:89], v[190:193], v[214:217], v[86:89]
	v_mfma_f32_16x16x32_bf16 v[78:81], v[182:185], v[222:225], v[78:81]
	v_mfma_f32_16x16x32_bf16 v[70:73], v[190:193], v[222:225], v[70:73]
	s_setprio 0
	s_barrier
	s_add_i32 s33, s44, s29
	s_mov_b32 m0, s33
	ds_read_b128 v[194:197], v155 offset:16384
	ds_read_b128 v[198:201], v155 offset:17408
	ds_read_b128 v[202:205], v155 offset:18432
	ds_read_b128 v[206:209], v155 offset:19456
	ds_read_b128 v[210:213], v155 offset:20480
	ds_read_b128 v[214:217], v155 offset:21504
	ds_read_b128 v[218:221], v155 offset:22528
	ds_read_b128 v[222:225], v155 offset:23552
	global_load_lds_dwordx4 v132, s[22:23]
	s_add_i32 m0, s33, 0x2000
	s_add_u32 s62, s22, 0x100000
	s_addc_u32 s63, s23, 0
	s_add_i32 s33, s45, s29
	global_load_lds_dwordx4 v136, s[22:23]
	s_mov_b32 m0, s33
	s_add_u32 s100, s26, 0x80
	s_addc_u32 s101, s27, 0
	global_load_lds_dwordx4 v132, s[62:63]
	s_add_i32 m0, s33, 0x2000
	s_nop 0
	global_load_lds_dwordx4 v136, s[62:63]
	s_mov_b32 m0, s21
	s_nop 0
	global_load_lds_dwordx4 v130, s[26:27]
	s_mov_b32 m0, s34
	s_nop 0
	global_load_lds_dwordx4 v134, s[26:27]
	s_waitcnt vmcnt(8)
	s_waitcnt lgkmcnt(0)
	s_barrier
	s_setprio 1
	v_mfma_f32_16x16x32_bf16 v[58:61], v[160:163], v[194:197], v[58:61]
	v_mfma_f32_16x16x32_bf16 v[50:53], v[170:173], v[194:197], v[50:53]
	v_mfma_f32_16x16x32_bf16 v[42:45], v[160:163], v[202:205], v[42:45]
	v_mfma_f32_16x16x32_bf16 v[34:37], v[170:173], v[202:205], v[34:37]
	v_mfma_f32_16x16x32_bf16 v[26:29], v[160:163], v[210:213], v[26:29]
	v_mfma_f32_16x16x32_bf16 v[18:21], v[170:173], v[210:213], v[18:21]
	v_mfma_f32_16x16x32_bf16 v[10:13], v[160:163], v[218:221], v[10:13]
	v_mfma_f32_16x16x32_bf16 v[2:5], v[170:173], v[218:221], v[2:5]
	v_mfma_f32_16x16x32_bf16 v[58:61], v[166:169], v[198:201], v[58:61]
	v_mfma_f32_16x16x32_bf16 v[50:53], v[174:177], v[198:201], v[50:53]
	v_mfma_f32_16x16x32_bf16 v[42:45], v[166:169], v[206:209], v[42:45]
	v_mfma_f32_16x16x32_bf16 v[34:37], v[174:177], v[206:209], v[34:37]
	v_mfma_f32_16x16x32_bf16 v[26:29], v[166:169], v[214:217], v[26:29]
	v_mfma_f32_16x16x32_bf16 v[18:21], v[174:177], v[214:217], v[18:21]
	v_mfma_f32_16x16x32_bf16 v[10:13], v[166:169], v[222:225], v[10:13]
	v_mfma_f32_16x16x32_bf16 v[2:5], v[174:177], v[222:225], v[2:5]
	v_mfma_f32_16x16x32_bf16 v[66:69], v[178:181], v[194:197], v[66:69]
	v_mfma_f32_16x16x32_bf16 v[54:57], v[186:189], v[194:197], v[54:57]
	v_mfma_f32_16x16x32_bf16 v[46:49], v[178:181], v[202:205], v[46:49]
	v_mfma_f32_16x16x32_bf16 v[38:41], v[186:189], v[202:205], v[38:41]
	v_mfma_f32_16x16x32_bf16 v[30:33], v[178:181], v[210:213], v[30:33]
	v_mfma_f32_16x16x32_bf16 v[22:25], v[186:189], v[210:213], v[22:25]
	v_mfma_f32_16x16x32_bf16 v[14:17], v[178:181], v[218:221], v[14:17]
	v_mfma_f32_16x16x32_bf16 v[6:9], v[186:189], v[218:221], v[6:9]
	v_mfma_f32_16x16x32_bf16 v[66:69], v[182:185], v[198:201], v[66:69]
	v_mfma_f32_16x16x32_bf16 v[54:57], v[190:193], v[198:201], v[54:57]
	v_mfma_f32_16x16x32_bf16 v[46:49], v[182:185], v[206:209], v[46:49]
	v_mfma_f32_16x16x32_bf16 v[38:41], v[190:193], v[206:209], v[38:41]
	v_mfma_f32_16x16x32_bf16 v[30:33], v[182:185], v[214:217], v[30:33]
	v_mfma_f32_16x16x32_bf16 v[22:25], v[190:193], v[214:217], v[22:25]
	v_mfma_f32_16x16x32_bf16 v[14:17], v[182:185], v[222:225], v[14:17]
	v_mfma_f32_16x16x32_bf16 v[6:9], v[190:193], v[222:225], v[6:9]
	s_setprio 0
	s_barrier
; #define PG8_STAGE(bufoff, gbase, voff) do { _Pragma("unroll") for (int _i = 0; _i < 2; ++_i) \
;         __builtin_amdgcn_global_load_lds((const unsigned*)((const char*)(gbase) + (voff)[_i]), (PG8_LAS unsigned*)(lds + (bufoff) + ldsw + _i * 8192), 16, 0, 0); } while (0)
; #define PG8_LDA(dst, b, h) do { _Pragma("unroll") for (int m = 0; m < 4; ++m) _Pragma("unroll") for (int k = 0; k < 2; ++k) dst[m][k] = *(const PG8_LAS bf16x8*)(lds + PG8_SA(b, h) + aoff + m * 2048 + k * 1024); } while (0)
; #define PG8_LDB(dst, b, h) do { _Pragma("unroll") for (int n = 0; n < 2; ++n) _Pragma("unroll") for (int k = 0; k < 2; ++k) dst[n][k] = *(const PG8_LAS bf16x8*)(lds + PG8_SB(b, h) + boff + n * 2048 + k * 1024); } while (0)
; #define PG8_MMA(ai, bj, At, Bt) do { __builtin_amdgcn_s_setprio(1); _Pragma("unroll") for (int m = 0; m < 4; ++m) _Pragma("unroll") for (int n = 0; n < 2; ++n) _Pragma("unroll") for (int k = 0; k < 2; ++k) \
;         acc[ai][bj][m][n] = __builtin_amdgcn_mfma_f32_16x16x32_bf16(Bt[n][k], At[m][k], acc[ai][bj][m][n], 0, 0, 0); __builtin_amdgcn_s_setprio(0); } while (0)
; #define PG8_WAIT_V(n) asm volatile("s_waitcnt vmcnt(" #n ")" ::: "memory")
; #define PG8_WAIT_L(n) asm volatile("s_waitcnt lgkmcnt(" #n ")" ::: "memory")
; #define PG8_BAR __builtin_amdgcn_s_barrier()
; #define PG8_SCHED __builtin_amdgcn_sched_barrier(0)
; template <class Epi, class Sched, bool ALIGN_EPI = false, bool SP2 = false>
; __device__ __forceinline__ void gemm_phase(PG8_LAS unsigned char* lds, const Gemm g, const Sched& S, const Epi& E) {
;     ...
;             PG8_LDB(B0, 1, 0); PG8_LDB(B1, 1, 1); PG8_SCHED; PG8_LDA(At, 1, 0); PG8_STAGE(PG8_SA(0, 1), a2 + hstep, voffA);
;             PG8_WAIT_V(8); PG8_WAIT_L(0); PG8_BAR; PG8_MMA(0, 0, At, B0); PG8_MMA(0, 1, At, B1); PG8_BAR; PG8_SCHED;
;             PG8_LDA(At, 1, 1); PG8_STAGE(PG8_SB(1, 0), b3, voffB); PG8_STAGE(PG8_SB(1, 1), b3 + hstep, voffB); PG8_STAGE(PG8_SA(1, 0), a3, voffA);
;             PG8_WAIT_V(8); PG8_WAIT_L(0); PG8_BAR; PG8_MMA(1, 0, At, B0); PG8_MMA(1, 1, At, B1); PG8_BAR; PG8_SCHED;
	s_add_i32 s33, 0, 0x18000
	s_add_i32 s42, 0, 0x1c000
	ds_read_b128 v[160:163], v241 offset:32768
	ds_read_b128 v[166:169], v241 offset:33792
	ds_read_b128 v[170:173], v241 offset:34816
	ds_read_b128 v[174:177], v241 offset:35840
	ds_read_b128 v[178:181], v241 offset:49152
	ds_read_b128 v[182:185], v241 offset:50176
	ds_read_b128 v[186:189], v241 offset:51200
	ds_read_b128 v[190:193], v241 offset:52224
	s_add_u32 s26, s26, 0x100000
	s_addc_u32 s27, s27, 0
	s_mov_b32 m0, s35
	ds_read_b128 v[194:197], v155 offset:32768
	ds_read_b128 v[198:201], v155 offset:33792
	ds_read_b128 v[202:205], v155 offset:34816
	ds_read_b128 v[206:209], v155 offset:35840
	ds_read_b128 v[210:213], v155 offset:36864
	ds_read_b128 v[214:217], v155 offset:37888
	ds_read_b128 v[218:221], v155 offset:38912
	ds_read_b128 v[222:225], v155 offset:39936
	global_load_lds_dwordx4 v130, s[26:27]
	s_mov_b32 m0, s36
	s_nop 0
	global_load_lds_dwordx4 v134, s[26:27]
	s_waitcnt vmcnt(8)
	s_waitcnt lgkmcnt(0)
	s_barrier
	s_setprio 1
	v_mfma_f32_16x16x32_bf16 v[122:125], v[160:163], v[194:197], v[122:125]
	v_mfma_f32_16x16x32_bf16 v[114:117], v[170:173], v[194:197], v[114:117]
	v_mfma_f32_16x16x32_bf16 v[106:109], v[160:163], v[202:205], v[106:109]
	v_mfma_f32_16x16x32_bf16 v[98:101], v[170:173], v[202:205], v[98:101]
	v_mfma_f32_16x16x32_bf16 v[90:93], v[160:163], v[210:213], v[90:93]
	v_mfma_f32_16x16x32_bf16 v[82:85], v[170:173], v[210:213], v[82:85]
	v_mfma_f32_16x16x32_bf16 v[74:77], v[160:163], v[218:221], v[74:77]
	v_mfma_f32_16x16x32_bf16 v[62:65], v[170:173], v[218:221], v[62:65]
	v_mfma_f32_16x16x32_bf16 v[122:125], v[166:169], v[198:201], v[122:125]
	v_mfma_f32_16x16x32_bf16 v[114:117], v[174:177], v[198:201], v[114:117]
	v_mfma_f32_16x16x32_bf16 v[106:109], v[166:169], v[206:209], v[106:109]
	v_mfma_f32_16x16x32_bf16 v[98:101], v[174:177], v[206:209], v[98:101]
	v_mfma_f32_16x16x32_bf16 v[90:93], v[166:169], v[214:217], v[90:93]
	v_mfma_f32_16x16x32_bf16 v[82:85], v[174:177], v[214:217], v[82:85]
	v_mfma_f32_16x16x32_bf16 v[74:77], v[166:169], v[222:225], v[74:77]
	v_mfma_f32_16x16x32_bf16 v[62:65], v[174:177], v[222:225], v[62:65]
	v_mfma_f32_16x16x32_bf16 v[126:129], v[178:181], v[194:197], v[126:129]
	v_mfma_f32_16x16x32_bf16 v[118:121], v[186:189], v[194:197], v[118:121]
	v_mfma_f32_16x16x32_bf16 v[110:113], v[178:181], v[202:205], v[110:113]
	v_mfma_f32_16x16x32_bf16 v[102:105], v[186:189], v[202:205], v[102:105]
	v_mfma_f32_16x16x32_bf16 v[94:97], v[178:181], v[210:213], v[94:97]
	v_mfma_f32_16x16x32_bf16 v[86:89], v[186:189], v[210:213], v[86:89]
	v_mfma_f32_16x16x32_bf16 v[78:81], v[178:181], v[218:221], v[78:81]
	v_mfma_f32_16x16x32_bf16 v[70:73], v[186:189], v[218:221], v[70:73]
	v_mfma_f32_16x16x32_bf16 v[126:129], v[182:185], v[198:201], v[126:129]
	v_mfma_f32_16x16x32_bf16 v[118:121], v[190:193], v[198:201], v[118:121]
	v_mfma_f32_16x16x32_bf16 v[110:113], v[182:185], v[206:209], v[110:113]
	v_mfma_f32_16x16x32_bf16 v[102:105], v[190:193], v[206:209], v[102:105]
	v_mfma_f32_16x16x32_bf16 v[94:97], v[182:185], v[214:217], v[94:97]
	v_mfma_f32_16x16x32_bf16 v[86:89], v[190:193], v[214:217], v[86:89]
	v_mfma_f32_16x16x32_bf16 v[78:81], v[182:185], v[222:225], v[78:81]
	v_mfma_f32_16x16x32_bf16 v[70:73], v[190:193], v[222:225], v[70:73]
	s_setprio 0
	s_barrier
	s_add_i32 s26, s33, s29
	s_add_i32 m0, s26, 0xffffff80
	ds_read_b128 v[194:197], v155 offset:49152
	ds_read_b128 v[198:201], v155 offset:50176
	ds_read_b128 v[202:205], v155 offset:51200
	ds_read_b128 v[206:209], v155 offset:52224
	ds_read_b128 v[210:213], v155 offset:53248
	ds_read_b128 v[214:217], v155 offset:54272
	ds_read_b128 v[218:221], v155 offset:55296
	ds_read_b128 v[222:225], v155 offset:56320
	global_load_lds_dwordx4 v132, s[22:23] offset:128
	s_add_i32 m0, s26, 0x1f80
	s_add_i32 s26, s42, s29
	global_load_lds_dwordx4 v136, s[22:23] offset:128
	s_add_u32 s22, s22, 0x100080
	s_addc_u32 s23, s23, 0
	s_mov_b32 m0, s26
	s_nop 0
	global_load_lds_dwordx4 v132, s[22:23]
	s_add_i32 m0, s26, 0x2000
	s_nop 0
	global_load_lds_dwordx4 v136, s[22:23]
	s_mov_b32 m0, s41
	s_nop 0
	global_load_lds_dwordx4 v130, s[100:101]
	s_mov_b32 m0, s43
	s_nop 0
	global_load_lds_dwordx4 v134, s[100:101]
	s_waitcnt vmcnt(8)
	s_waitcnt lgkmcnt(0)
	s_barrier
	s_setprio 1
	v_mfma_f32_16x16x32_bf16 v[58:61], v[160:163], v[194:197], v[58:61]
	v_mfma_f32_16x16x32_bf16 v[50:53], v[170:173], v[194:197], v[50:53]
	v_mfma_f32_16x16x32_bf16 v[42:45], v[160:163], v[202:205], v[42:45]
	v_mfma_f32_16x16x32_bf16 v[34:37], v[170:173], v[202:205], v[34:37]
	v_mfma_f32_16x16x32_bf16 v[26:29], v[160:163], v[210:213], v[26:29]
	v_mfma_f32_16x16x32_bf16 v[18:21], v[170:173], v[210:213], v[18:21]
	v_mfma_f32_16x16x32_bf16 v[10:13], v[160:163], v[218:221], v[10:13]
	v_mfma_f32_16x16x32_bf16 v[2:5], v[170:173], v[218:221], v[2:5]
	v_mfma_f32_16x16x32_bf16 v[58:61], v[166:169], v[198:201], v[58:61]
	v_mfma_f32_16x16x32_bf16 v[50:53], v[174:177], v[198:201], v[50:53]
	v_mfma_f32_16x16x32_bf16 v[42:45], v[166:169], v[206:209], v[42:45]
	v_mfma_f32_16x16x32_bf16 v[34:37], v[174:177], v[206:209], v[34:37]
	v_mfma_f32_16x16x32_bf16 v[26:29], v[166:169], v[214:217], v[26:29]
	v_mfma_f32_16x16x32_bf16 v[18:21], v[174:177], v[214:217], v[18:21]
	v_mfma_f32_16x16x32_bf16 v[10:13], v[166:169], v[222:225], v[10:13]
	v_mfma_f32_16x16x32_bf16 v[2:5], v[174:177], v[222:225], v[2:5]
	v_mfma_f32_16x16x32_bf16 v[66:69], v[178:181], v[194:197], v[66:69]
	v_mfma_f32_16x16x32_bf16 v[54:57], v[186:189], v[194:197], v[54:57]
	v_mfma_f32_16x16x32_bf16 v[46:49], v[178:181], v[202:205], v[46:49]
	v_mfma_f32_16x16x32_bf16 v[38:41], v[186:189], v[202:205], v[38:41]
	v_mfma_f32_16x16x32_bf16 v[30:33], v[178:181], v[210:213], v[30:33]
	v_mfma_f32_16x16x32_bf16 v[22:25], v[186:189], v[210:213], v[22:25]
	v_mfma_f32_16x16x32_bf16 v[14:17], v[178:181], v[218:221], v[14:17]
	v_mfma_f32_16x16x32_bf16 v[6:9], v[186:189], v[218:221], v[6:9]
	v_mfma_f32_16x16x32_bf16 v[66:69], v[182:185], v[198:201], v[66:69]
	v_mfma_f32_16x16x32_bf16 v[54:57], v[190:193], v[198:201], v[54:57]
	v_mfma_f32_16x16x32_bf16 v[46:49], v[182:185], v[206:209], v[46:49]
	v_mfma_f32_16x16x32_bf16 v[38:41], v[190:193], v[206:209], v[38:41]
	v_mfma_f32_16x16x32_bf16 v[30:33], v[182:185], v[214:217], v[30:33]
	v_mfma_f32_16x16x32_bf16 v[22:25], v[190:193], v[214:217], v[22:25]
	v_mfma_f32_16x16x32_bf16 v[14:17], v[182:185], v[222:225], v[14:17]
	v_mfma_f32_16x16x32_bf16 v[6:9], v[190:193], v[222:225], v[6:9]
	s_setprio 0
	s_barrier
	s_add_i32 s52, s52, 2
	s_add_u32 s24, s24, 0x100
	s_addc_u32 s25, s25, 0
	s_add_u32 s50, s50, 0x100
	s_addc_u32 s51, s51, 0
	s_cmp_gt_u32 s52, 61
	s_cbranch_scc0 .LBB0_1681
	s_and_b64 vcc, exec, s[8:9]
	s_cbranch_vccz .LBB0_1684
	s_barrier

; #define PG8_STAGE(bufoff, gbase, voff) do { _Pragma("unroll") for (int _i = 0; _i < 2; ++_i) \
;         __builtin_amdgcn_global_load_lds((const unsigned*)((const char*)(gbase) + (voff)[_i]), (PG8_LAS unsigned*)(lds + (bufoff) + ldsw + _i * 8192), 16, 0, 0); } while (0)
; #define PG8_LDA(dst, b, h) do { _Pragma("unroll") for (int m = 0; m < 4; ++m) _Pragma("unroll") for (int k = 0; k < 2; ++k) dst[m][k] = *(const PG8_LAS bf16x8*)(lds + PG8_SA(b, h) + aoff + m * 2048 + k * 1024); } while (0)
; #define PG8_LDB(dst, b, h) do { _Pragma("unroll") for (int n = 0; n < 2; ++n) _Pragma("unroll") for (int k = 0; k < 2; ++k) dst[n][k] = *(const PG8_LAS bf16x8*)(lds + PG8_SB(b, h) + boff + n * 2048 + k * 1024); } while (0)
; #define PG8_MMA(ai, bj, At, Bt) do { __builtin_amdgcn_s_setprio(1); _Pragma("unroll") for (int m = 0; m < 4; ++m) _Pragma("unroll") for (int n = 0; n < 2; ++n) _Pragma("unroll") for (int k = 0; k < 2; ++k) \
;         acc[ai][bj][m][n] = __builtin_amdgcn_mfma_f32_16x16x32_bf16(Bt[n][k], At[m][k], acc[ai][bj][m][n], 0, 0, 0); __builtin_amdgcn_s_setprio(0); } while (0)
; #define PG8_WAIT_V(n) asm volatile("s_waitcnt vmcnt(" #n ")" ::: "memory")
; #define PG8_BAR __builtin_amdgcn_s_barrier()
; template <class Epi, class Sched, bool ALIGN_EPI = false, bool SP2 = false>
; __device__ __forceinline__ void gemm_phase(PG8_LAS unsigned char* lds, const Gemm g, const Sched& S, const Epi& E) {
;     ...
;         for (int t = 0; t < nt; t += 2) {
;             const bool last = (t == nt - 2);
;             const char* a1 = cA + (size_t)(t + 1) * kstep;
;             const char* a2 = last ? nA : cA + (size_t)(t + 2) * kstep; const char* b2 = last ? nB : cB + (size_t)(t + 2) * kstep;
;             const char* a3 = a2 + kstep; const char* b3 = b2 + kstep;
;             if (last && has_next) S.a_ready(nxt);
;             if constexpr (SP2) {
;             PG8_LDB(B0, 0, 0); PG8_LDB(B1, 0, 1); PG8_SCHED; PG8_LDA(At, 0, 0); PG8_STAGE(PG8_SA(1, 1), a1 + hstep, voffA);
;             PG8_WAIT_V(8); PG8_WAIT_L(0); PG8_BAR; PG8_MMA(0, 0, At, B0); PG8_MMA(0, 1, At, B1); PG8_BAR; PG8_SCHED;
;             PG8_LDA(At, 0, 1); PG8_STAGE(PG8_SB(0, 0), b2, voffB); PG8_STAGE(PG8_SB(0, 1), b2 + hstep, voffB); PG8_STAGE(PG8_SA(0, 0), a2, voffA);
;             PG8_WAIT_V(8); PG8_WAIT_L(0); PG8_BAR; PG8_MMA(1, 0, At, B0); PG8_MMA(1, 1, At, B1); PG8_BAR; PG8_SCHED;
.LBB0_1801:
	ds_read_b128 v[130:133], v241 offset:0
	ds_read_b128 v[134:137], v241 offset:1024
	ds_read_b128 v[138:141], v241 offset:2048
	ds_read_b128 v[142:145], v241 offset:3072
	ds_read_b128 v[146:149], v241 offset:16384
	ds_read_b128 v[150:153], v241 offset:17408
	ds_read_b128 v[170:173], v241 offset:18432
	ds_read_b128 v[174:177], v241 offset:19456
	s_add_u32 s16, s18, 0xffd50080
	s_addc_u32 s17, s19, -1
	s_cmpk_eq_i32 s48, 0xa8
	s_cselect_b32 s21, s5, s17
	s_cselect_b32 s20, s4, s16
	s_cselect_b32 s17, s15, s47
	s_cselect_b32 s16, s14, s46
	s_add_i32 m0, s25, 0xc000
	ds_read_b128 v[178:181], v184
	ds_read_b128 v[186:189], v184 offset:1024
	ds_read_b128 v[190:193], v184 offset:2048
	ds_read_b128 v[194:197], v184 offset:3072
	ds_read_b128 v[198:201], v184 offset:4096
	ds_read_b128 v[202:205], v184 offset:5120
	ds_read_b128 v[206:209], v184 offset:6144
	ds_read_b128 v[210:213], v184 offset:7168
	global_load_lds_dwordx4 v0, s[18:19]
	s_add_i32 m0, s25, 0xe000
	s_nop 0
	global_load_lds_dwordx4 v162, s[18:19]
	s_waitcnt vmcnt(8)
	s_waitcnt lgkmcnt(0)
	s_barrier
	s_setprio 1
	v_mfma_f32_16x16x32_bf16 v[114:117], v[130:133], v[178:181], v[114:117]
	v_mfma_f32_16x16x32_bf16 v[118:121], v[138:141], v[178:181], v[118:121]
	v_mfma_f32_16x16x32_bf16 v[106:109], v[130:133], v[190:193], v[106:109]
	v_mfma_f32_16x16x32_bf16 v[98:101], v[138:141], v[190:193], v[98:101]
	v_mfma_f32_16x16x32_bf16 v[90:93], v[130:133], v[198:201], v[90:93]
	v_mfma_f32_16x16x32_bf16 v[82:85], v[138:141], v[198:201], v[82:85]
	v_mfma_f32_16x16x32_bf16 v[74:77], v[130:133], v[206:209], v[74:77]
	v_mfma_f32_16x16x32_bf16 v[66:69], v[138:141], v[206:209], v[66:69]
	v_mfma_f32_16x16x32_bf16 v[114:117], v[134:137], v[186:189], v[114:117]
	v_mfma_f32_16x16x32_bf16 v[118:121], v[142:145], v[186:189], v[118:121]
	v_mfma_f32_16x16x32_bf16 v[106:109], v[134:137], v[194:197], v[106:109]
	v_mfma_f32_16x16x32_bf16 v[98:101], v[142:145], v[194:197], v[98:101]
	v_mfma_f32_16x16x32_bf16 v[90:93], v[134:137], v[202:205], v[90:93]
	v_mfma_f32_16x16x32_bf16 v[82:85], v[142:145], v[202:205], v[82:85]
	v_mfma_f32_16x16x32_bf16 v[74:77], v[134:137], v[210:213], v[74:77]
	v_mfma_f32_16x16x32_bf16 v[66:69], v[142:145], v[210:213], v[66:69]
	v_mfma_f32_16x16x32_bf16 v[122:125], v[146:149], v[178:181], v[122:125]
	v_mfma_f32_16x16x32_bf16 v[126:129], v[170:173], v[178:181], v[126:129]
	v_mfma_f32_16x16x32_bf16 v[110:113], v[146:149], v[190:193], v[110:113]
	v_mfma_f32_16x16x32_bf16 v[102:105], v[170:173], v[190:193], v[102:105]
	v_mfma_f32_16x16x32_bf16 v[94:97], v[146:149], v[198:201], v[94:97]
	v_mfma_f32_16x16x32_bf16 v[86:89], v[170:173], v[198:201], v[86:89]
	v_mfma_f32_16x16x32_bf16 v[78:81], v[146:149], v[206:209], v[78:81]
	v_mfma_f32_16x16x32_bf16 v[70:73], v[170:173], v[206:209], v[70:73]
	v_mfma_f32_16x16x32_bf16 v[122:125], v[150:153], v[186:189], v[122:125]
	v_mfma_f32_16x16x32_bf16 v[126:129], v[174:177], v[186:189], v[126:129]
	v_mfma_f32_16x16x32_bf16 v[110:113], v[150:153], v[194:197], v[110:113]
	v_mfma_f32_16x16x32_bf16 v[102:105], v[174:177], v[194:197], v[102:105]
	v_mfma_f32_16x16x32_bf16 v[94:97], v[150:153], v[202:205], v[94:97]
	v_mfma_f32_16x16x32_bf16 v[86:89], v[174:177], v[202:205], v[86:89]
	v_mfma_f32_16x16x32_bf16 v[78:81], v[150:153], v[210:213], v[78:81]
	v_mfma_f32_16x16x32_bf16 v[70:73], v[174:177], v[210:213], v[70:73]
	s_setprio 0
	s_barrier
	s_add_i32 s33, s36, s24
	s_mov_b32 m0, s33
	ds_read_b128 v[178:181], v184 offset:16384
	ds_read_b128 v[186:189], v184 offset:17408
	ds_read_b128 v[190:193], v184 offset:18432
	ds_read_b128 v[194:197], v184 offset:19456
	ds_read_b128 v[198:201], v184 offset:20480
	ds_read_b128 v[202:205], v184 offset:21504
	ds_read_b128 v[206:209], v184 offset:22528
	ds_read_b128 v[210:213], v184 offset:23552
	global_load_lds_dwordx4 v156, s[16:17]
	s_add_i32 m0, s33, 0x2000
	s_add_u32 s50, s16, 0x2b0000
	s_addc_u32 s51, s17, 0
	s_add_i32 s33, s37, s24
	global_load_lds_dwordx4 v160, s[16:17]
	s_mov_b32 m0, s33
	s_add_u32 s100, s20, 0x80
	s_addc_u32 s101, s21, 0
	global_load_lds_dwordx4 v156, s[50:51]
	s_add_i32 m0, s33, 0x2000
	s_nop 0
	global_load_lds_dwordx4 v160, s[50:51]
	s_mov_b32 m0, s25
	s_nop 0
	global_load_lds_dwordx4 v154, s[20:21]
	s_mov_b32 m0, s26
	s_nop 0
	global_load_lds_dwordx4 v158, s[20:21]
	s_waitcnt vmcnt(8)
	s_waitcnt lgkmcnt(0)
	s_barrier
	s_setprio 1
	v_mfma_f32_16x16x32_bf16 v[58:61], v[130:133], v[178:181], v[58:61]
	v_mfma_f32_16x16x32_bf16 v[54:57], v[138:141], v[178:181], v[54:57]
	v_mfma_f32_16x16x32_bf16 v[42:45], v[130:133], v[190:193], v[42:45]
	v_mfma_f32_16x16x32_bf16 v[34:37], v[138:141], v[190:193], v[34:37]
	v_mfma_f32_16x16x32_bf16 v[26:29], v[130:133], v[198:201], v[26:29]
	v_mfma_f32_16x16x32_bf16 v[18:21], v[138:141], v[198:201], v[18:21]
	v_mfma_f32_16x16x32_bf16 v[6:9], v[130:133], v[206:209], v[6:9]
	v_mfma_f32_16x16x32_bf16 v[2:5], v[138:141], v[206:209], v[2:5]
	v_mfma_f32_16x16x32_bf16 v[58:61], v[134:137], v[186:189], v[58:61]
	v_mfma_f32_16x16x32_bf16 v[54:57], v[142:145], v[186:189], v[54:57]
	v_mfma_f32_16x16x32_bf16 v[42:45], v[134:137], v[194:197], v[42:45]
	v_mfma_f32_16x16x32_bf16 v[34:37], v[142:145], v[194:197], v[34:37]
	v_mfma_f32_16x16x32_bf16 v[26:29], v[134:137], v[202:205], v[26:29]
	v_mfma_f32_16x16x32_bf16 v[18:21], v[142:145], v[202:205], v[18:21]
	v_mfma_f32_16x16x32_bf16 v[6:9], v[134:137], v[210:213], v[6:9]
	v_mfma_f32_16x16x32_bf16 v[2:5], v[142:145], v[210:213], v[2:5]
	v_mfma_f32_16x16x32_bf16 v[62:65], v[146:149], v[178:181], v[62:65]
	v_mfma_f32_16x16x32_bf16 v[50:53], v[170:173], v[178:181], v[50:53]
	v_mfma_f32_16x16x32_bf16 v[46:49], v[146:149], v[190:193], v[46:49]
	v_mfma_f32_16x16x32_bf16 v[38:41], v[170:173], v[190:193], v[38:41]
	v_mfma_f32_16x16x32_bf16 v[30:33], v[146:149], v[198:201], v[30:33]
	v_mfma_f32_16x16x32_bf16 v[22:25], v[170:173], v[198:201], v[22:25]
	v_mfma_f32_16x16x32_bf16 v[10:13], v[146:149], v[206:209], v[10:13]
	v_mfma_f32_16x16x32_bf16 v[14:17], v[170:173], v[206:209], v[14:17]
	v_mfma_f32_16x16x32_bf16 v[62:65], v[150:153], v[186:189], v[62:65]
	v_mfma_f32_16x16x32_bf16 v[50:53], v[174:177], v[186:189], v[50:53]
	v_mfma_f32_16x16x32_bf16 v[46:49], v[150:153], v[194:197], v[46:49]
	v_mfma_f32_16x16x32_bf16 v[38:41], v[174:177], v[194:197], v[38:41]
	v_mfma_f32_16x16x32_bf16 v[30:33], v[150:153], v[202:205], v[30:33]
	v_mfma_f32_16x16x32_bf16 v[22:25], v[174:177], v[202:205], v[22:25]
	v_mfma_f32_16x16x32_bf16 v[10:13], v[150:153], v[210:213], v[10:13]
	v_mfma_f32_16x16x32_bf16 v[14:17], v[174:177], v[210:213], v[14:17]
	s_setprio 0
	s_barrier
; #define PG8_STAGE(bufoff, gbase, voff) do { _Pragma("unroll") for (int _i = 0; _i < 2; ++_i) \
;         __builtin_amdgcn_global_load_lds((const unsigned*)((const char*)(gbase) + (voff)[_i]), (PG8_LAS unsigned*)(lds + (bufoff) + ldsw + _i * 8192), 16, 0, 0); } while (0)
; #define PG8_LDA(dst, b, h) do { _Pragma("unroll") for (int m = 0; m < 4; ++m) _Pragma("unroll") for (int k = 0; k < 2; ++k) dst[m][k] = *(const PG8_LAS bf16x8*)(lds + PG8_SA(b, h) + aoff + m * 2048 + k * 1024); } while (0)
; #define PG8_LDB(dst, b, h) do { _Pragma("unroll") for (int n = 0; n < 2; ++n) _Pragma("unroll") for (int k = 0; k < 2; ++k) dst[n][k] = *(const PG8_LAS bf16x8*)(lds + PG8_SB(b, h) + boff + n * 2048 + k * 1024); } while (0)
; #define PG8_MMA(ai, bj, At, Bt) do { __builtin_amdgcn_s_setprio(1); _Pragma("unroll") for (int m = 0; m < 4; ++m) _Pragma("unroll") for (int n = 0; n < 2; ++n) _Pragma("unroll") for (int k = 0; k < 2; ++k) \
;         acc[ai][bj][m][n] = __builtin_amdgcn_mfma_f32_16x16x32_bf16(Bt[n][k], At[m][k], acc[ai][bj][m][n], 0, 0, 0); __builtin_amdgcn_s_setprio(0); } while (0)
; #define PG8_WAIT_V(n) asm volatile("s_waitcnt vmcnt(" #n ")" ::: "memory")
; #define PG8_WAIT_L(n) asm volatile("s_waitcnt lgkmcnt(" #n ")" ::: "memory")
; #define PG8_BAR __builtin_amdgcn_s_barrier()
; #define PG8_SCHED __builtin_amdgcn_sched_barrier(0)
; template <class Epi, class Sched, bool ALIGN_EPI = false, bool SP2 = false>
; __device__ __forceinline__ void gemm_phase(PG8_LAS unsigned char* lds, const Gemm g, const Sched& S, const Epi& E) {
;     ...
;             PG8_LDB(B0, 1, 0); PG8_LDB(B1, 1, 1); PG8_SCHED; PG8_LDA(At, 1, 0); PG8_STAGE(PG8_SA(0, 1), a2 + hstep, voffA);
;             PG8_WAIT_V(8); PG8_WAIT_L(0); PG8_BAR; PG8_MMA(0, 0, At, B0); PG8_MMA(0, 1, At, B1); PG8_BAR; PG8_SCHED;
;             PG8_LDA(At, 1, 1); PG8_STAGE(PG8_SB(1, 0), b3, voffB); PG8_STAGE(PG8_SB(1, 1), b3 + hstep, voffB); PG8_STAGE(PG8_SA(1, 0), a3, voffA);
;             PG8_WAIT_V(8); PG8_WAIT_L(0); PG8_BAR; PG8_MMA(1, 0, At, B0); PG8_MMA(1, 1, At, B1); PG8_BAR; PG8_SCHED;
	s_add_i32 s33, 0, 0x18000
	s_add_i32 s42, 0, 0x1c000
	ds_read_b128 v[130:133], v241 offset:32768
	ds_read_b128 v[134:137], v241 offset:33792
	ds_read_b128 v[138:141], v241 offset:34816
	ds_read_b128 v[142:145], v241 offset:35840
	ds_read_b128 v[146:149], v241 offset:49152
	ds_read_b128 v[150:153], v241 offset:50176
	ds_read_b128 v[170:173], v241 offset:51200
	ds_read_b128 v[174:177], v241 offset:52224
	s_add_u32 s20, s20, 0x2b0000
	s_addc_u32 s21, s21, 0
	s_mov_b32 m0, s27
	ds_read_b128 v[178:181], v184 offset:32768
	ds_read_b128 v[186:189], v184 offset:33792
	ds_read_b128 v[190:193], v184 offset:34816
	ds_read_b128 v[194:197], v184 offset:35840
	ds_read_b128 v[198:201], v184 offset:36864
	ds_read_b128 v[202:205], v184 offset:37888
	ds_read_b128 v[206:209], v184 offset:38912
	ds_read_b128 v[210:213], v184 offset:39936
	global_load_lds_dwordx4 v154, s[20:21]
	s_mov_b32 m0, s28
	s_nop 0
	global_load_lds_dwordx4 v158, s[20:21]
	s_waitcnt vmcnt(8)
	s_waitcnt lgkmcnt(0)
	s_barrier
	s_setprio 1
	v_mfma_f32_16x16x32_bf16 v[114:117], v[130:133], v[178:181], v[114:117]
	v_mfma_f32_16x16x32_bf16 v[118:121], v[138:141], v[178:181], v[118:121]
	v_mfma_f32_16x16x32_bf16 v[106:109], v[130:133], v[190:193], v[106:109]
	v_mfma_f32_16x16x32_bf16 v[98:101], v[138:141], v[190:193], v[98:101]
	v_mfma_f32_16x16x32_bf16 v[90:93], v[130:133], v[198:201], v[90:93]
	v_mfma_f32_16x16x32_bf16 v[82:85], v[138:141], v[198:201], v[82:85]
	v_mfma_f32_16x16x32_bf16 v[74:77], v[130:133], v[206:209], v[74:77]
	v_mfma_f32_16x16x32_bf16 v[66:69], v[138:141], v[206:209], v[66:69]
	v_mfma_f32_16x16x32_bf16 v[114:117], v[134:137], v[186:189], v[114:117]
	v_mfma_f32_16x16x32_bf16 v[118:121], v[142:145], v[186:189], v[118:121]
	v_mfma_f32_16x16x32_bf16 v[106:109], v[134:137], v[194:197], v[106:109]
	v_mfma_f32_16x16x32_bf16 v[98:101], v[142:145], v[194:197], v[98:101]
	v_mfma_f32_16x16x32_bf16 v[90:93], v[134:137], v[202:205], v[90:93]
	v_mfma_f32_16x16x32_bf16 v[82:85], v[142:145], v[202:205], v[82:85]
	v_mfma_f32_16x16x32_bf16 v[74:77], v[134:137], v[210:213], v[74:77]
	v_mfma_f32_16x16x32_bf16 v[66:69], v[142:145], v[210:213], v[66:69]
	v_mfma_f32_16x16x32_bf16 v[122:125], v[146:149], v[178:181], v[122:125]
	v_mfma_f32_16x16x32_bf16 v[126:129], v[170:173], v[178:181], v[126:129]
	v_mfma_f32_16x16x32_bf16 v[110:113], v[146:149], v[190:193], v[110:113]
	v_mfma_f32_16x16x32_bf16 v[102:105], v[170:173], v[190:193], v[102:105]
	v_mfma_f32_16x16x32_bf16 v[94:97], v[146:149], v[198:201], v[94:97]
	v_mfma_f32_16x16x32_bf16 v[86:89], v[170:173], v[198:201], v[86:89]
	v_mfma_f32_16x16x32_bf16 v[78:81], v[146:149], v[206:209], v[78:81]
	v_mfma_f32_16x16x32_bf16 v[70:73], v[170:173], v[206:209], v[70:73]
	v_mfma_f32_16x16x32_bf16 v[122:125], v[150:153], v[186:189], v[122:125]
	v_mfma_f32_16x16x32_bf16 v[126:129], v[174:177], v[186:189], v[126:129]
	v_mfma_f32_16x16x32_bf16 v[110:113], v[150:153], v[194:197], v[110:113]
	v_mfma_f32_16x16x32_bf16 v[102:105], v[174:177], v[194:197], v[102:105]
	v_mfma_f32_16x16x32_bf16 v[94:97], v[150:153], v[202:205], v[94:97]
	v_mfma_f32_16x16x32_bf16 v[86:89], v[174:177], v[202:205], v[86:89]
	v_mfma_f32_16x16x32_bf16 v[78:81], v[150:153], v[210:213], v[78:81]
	v_mfma_f32_16x16x32_bf16 v[70:73], v[174:177], v[210:213], v[70:73]
	s_setprio 0
	s_barrier
	s_add_i32 s20, s33, s24
	s_add_i32 m0, s20, 0xffffff80
	ds_read_b128 v[178:181], v184 offset:49152
	ds_read_b128 v[186:189], v184 offset:50176
	ds_read_b128 v[190:193], v184 offset:51200
	ds_read_b128 v[194:197], v184 offset:52224
	ds_read_b128 v[198:201], v184 offset:53248
	ds_read_b128 v[202:205], v184 offset:54272
	ds_read_b128 v[206:209], v184 offset:55296
	ds_read_b128 v[210:213], v184 offset:56320
	global_load_lds_dwordx4 v156, s[16:17] offset:128
	s_add_i32 m0, s20, 0x1f80
	s_add_i32 s20, s42, s24
	global_load_lds_dwordx4 v160, s[16:17] offset:128
	s_add_u32 s16, s16, 0x2b0080
	s_addc_u32 s17, s17, 0
	s_mov_b32 m0, s20
	s_nop 0
	global_load_lds_dwordx4 v156, s[16:17]
	s_add_i32 m0, s20, 0x2000
	s_nop 0
	global_load_lds_dwordx4 v160, s[16:17]
	s_mov_b32 m0, s30
	s_nop 0
	global_load_lds_dwordx4 v154, s[100:101]
	s_mov_b32 m0, s31
	s_nop 0
	global_load_lds_dwordx4 v158, s[100:101]
	s_waitcnt vmcnt(8)
	s_waitcnt lgkmcnt(0)
	s_barrier
	s_setprio 1
	v_mfma_f32_16x16x32_bf16 v[58:61], v[130:133], v[178:181], v[58:61]
	v_mfma_f32_16x16x32_bf16 v[54:57], v[138:141], v[178:181], v[54:57]
	v_mfma_f32_16x16x32_bf16 v[42:45], v[130:133], v[190:193], v[42:45]
	v_mfma_f32_16x16x32_bf16 v[34:37], v[138:141], v[190:193], v[34:37]
	v_mfma_f32_16x16x32_bf16 v[26:29], v[130:133], v[198:201], v[26:29]
	v_mfma_f32_16x16x32_bf16 v[18:21], v[138:141], v[198:201], v[18:21]
	v_mfma_f32_16x16x32_bf16 v[6:9], v[130:133], v[206:209], v[6:9]
	v_mfma_f32_16x16x32_bf16 v[2:5], v[138:141], v[206:209], v[2:5]
	v_mfma_f32_16x16x32_bf16 v[58:61], v[134:137], v[186:189], v[58:61]
	v_mfma_f32_16x16x32_bf16 v[54:57], v[142:145], v[186:189], v[54:57]
	v_mfma_f32_16x16x32_bf16 v[42:45], v[134:137], v[194:197], v[42:45]
	v_mfma_f32_16x16x32_bf16 v[34:37], v[142:145], v[194:197], v[34:37]
	v_mfma_f32_16x16x32_bf16 v[26:29], v[134:137], v[202:205], v[26:29]
	v_mfma_f32_16x16x32_bf16 v[18:21], v[142:145], v[202:205], v[18:21]
	v_mfma_f32_16x16x32_bf16 v[6:9], v[134:137], v[210:213], v[6:9]
	v_mfma_f32_16x16x32_bf16 v[2:5], v[142:145], v[210:213], v[2:5]
	v_mfma_f32_16x16x32_bf16 v[62:65], v[146:149], v[178:181], v[62:65]
	v_mfma_f32_16x16x32_bf16 v[50:53], v[170:173], v[178:181], v[50:53]
	v_mfma_f32_16x16x32_bf16 v[46:49], v[146:149], v[190:193], v[46:49]
	v_mfma_f32_16x16x32_bf16 v[38:41], v[170:173], v[190:193], v[38:41]
	v_mfma_f32_16x16x32_bf16 v[30:33], v[146:149], v[198:201], v[30:33]
	v_mfma_f32_16x16x32_bf16 v[22:25], v[170:173], v[198:201], v[22:25]
	v_mfma_f32_16x16x32_bf16 v[10:13], v[146:149], v[206:209], v[10:13]
	v_mfma_f32_16x16x32_bf16 v[14:17], v[170:173], v[206:209], v[14:17]
	v_mfma_f32_16x16x32_bf16 v[62:65], v[150:153], v[186:189], v[62:65]
	v_mfma_f32_16x16x32_bf16 v[50:53], v[174:177], v[186:189], v[50:53]
	v_mfma_f32_16x16x32_bf16 v[46:49], v[150:153], v[194:197], v[46:49]
	v_mfma_f32_16x16x32_bf16 v[38:41], v[174:177], v[194:197], v[38:41]
	v_mfma_f32_16x16x32_bf16 v[30:33], v[150:153], v[202:205], v[30:33]
	v_mfma_f32_16x16x32_bf16 v[22:25], v[174:177], v[202:205], v[22:25]
	v_mfma_f32_16x16x32_bf16 v[10:13], v[150:153], v[210:213], v[10:13]
	v_mfma_f32_16x16x32_bf16 v[14:17], v[174:177], v[210:213], v[14:17]
	s_setprio 0
	s_barrier
	s_add_i32 s48, s48, 2
	s_add_u32 s18, s18, 0x100
	s_addc_u32 s19, s19, 0
	s_add_u32 s46, s46, 0x100
	s_addc_u32 s47, s47, 0
	s_cmpk_gt_u32 s48, 0xa9
	s_cbranch_scc0 .LBB0_1801
	s_and_b64 vcc, exec, s[12:13]
	s_cbranch_vccz .LBB0_1804
	s_barrier
